# hoisted residual loads in P3,P5,P10,P12 epilogues + sc1 16B epilogue stores
# baseline (speedup 1.0000x reference)
; __device__ __forceinline__ unsigned pkh(float lo, float hi) { f32x2 v = {lo, hi}; h16x2 h = __builtin_convertvector(v, h16x2); return __builtin_bit_cast(unsigned, h); }
; __device__ __forceinline__ unsigned pk8(float a, float b, float c, float d) { int w = __builtin_amdgcn_cvt_pk_fp8_f32(a, b, 0, false); w = __builtin_amdgcn_cvt_pk_fp8_f32(c, d, w, true); return (unsigned)w; }
;     __device__ __forceinline__ void operator()(f32x4 (&acc)[2][2][4][2], const Unit& u, const Order& S, int wr, int wc, int fr_, int fq_, LAS unsigned char*, int) const {
;     ...
;         for (int ai = 0; ai < 2; ++ai)
; #pragma unroll
;             for (int m = 0; m < 4; ++m) {
;                 const int row = row0 + ai * HALF + m * 16; const size_t off = (size_t)row * DM + col0;
;                 float sq = 0.f;
; #pragma unroll
;                 for (int bj = 0; bj < 2; ++bj) {
;                     const h16x8 bs = *(const h16x8*)(h16 + off + bj * HALF);
;                     f32x4 o0 = acc[ai][bj][m][0] * pre, o1 = acc[ai][bj][m][1] * pre;
; #pragma unroll
;                     for (int e = 0; e < 4; ++e) { o0[e] += (float)bs[e]; o1[e] += (float)bs[4 + e]; }
;                     if (out32) { if (!dry) { __builtin_nontemporal_store(o0, (f32x4*)(out32 + off + bj * HALF)); __builtin_nontemporal_store(o1, (f32x4*)(out32 + off + bj * HALF + 4)); } }
;                     else if (!dry) {
;                         sq += (o0[0] * o0[0] + o0[1] * o0[1]) + (o0[2] * o0[2] + o0[3] * o0[3]) + (o1[0] * o1[0] + o1[1] * o1[1]) + (o1[2] * o1[2] + o1[3] * o1[3]);
;                         u32x4 w; w.x = pkh(o0[0], o0[1]); w.y = pkh(o0[2], o0[3]); w.z = pkh(o1[0], o1[1]); w.w = pkh(o1[2], o1[3]);
;                         *(u32x4*)(h16 + off + bj * HALF) = w;
;                         if (h8) { u32x2 q; q.x = pk8(o0[0] * F8_SA, o0[1] * F8_SA, o0[2] * F8_SA, o0[3] * F8_SA); q.y = pk8(o1[0] * F8_SA, o1[1] * F8_SA, o1[2] * F8_SA, o1[3] * F8_SA); *(u32x2*)(h8 + off + bj * HALF) = q; } }
;                 }
;                 if (!out32 && !dry) { sq += __shfl_xor(sq, 16); sq += __shfl_xor(sq, 32); if (fq == 0) atomicAdd(ss_out + row, sq); }
.LBB0_403:
	s_lshl_b32 s3, s45, 8
	v_mov_b32_e32 v146, v150
	v_mov_b32_e32 v168, v1
	s_add_i32 s3, s3, s38
	s_lshl_b32 s2, s2, 8
	v_add_u32_e32 v148, s3, v146
	s_or_b32 s2, s2, s39
	v_ashrrev_i32_e32 v149, 31, v148
	v_lshl_add_u32 v146, v168, 3, s2
	v_lshlrev_b64 v[156:157], 11, v[148:149]
	v_ashrrev_i32_e32 v147, 31, v146
	v_lshl_add_u64 v[156:157], s[90:91], 0, v[156:157]
	v_lshl_add_u64 v[166:167], v[146:147], 1, v[156:157]
	global_load_dwordx4 v[158:161], v[166:167], off
	global_load_dwordx4 v[162:165], v[166:167], off offset:256
	s_mov_b32 s99, 0
	s_mov_b32 s98, 0x8000
	v_lshl_add_u64 v[170:171], s[98:99], 0, v[166:167]
	global_load_dwordx4 v[176:179], v[170:171], off
	global_load_dwordx4 v[180:183], v[170:171], off offset:256
	s_mov_b32 s98, 0x10000
	v_lshl_add_u64 v[170:171], s[98:99], 0, v[166:167]
	global_load_dwordx4 v[184:187], v[170:171], off
	global_load_dwordx4 v[188:191], v[170:171], off offset:256
	s_mov_b32 s98, 0x18000
	v_lshl_add_u64 v[170:171], s[98:99], 0, v[166:167]
	global_load_dwordx4 v[192:195], v[170:171], off
	global_load_dwordx4 v[196:199], v[170:171], off offset:256
	s_mov_b32 s98, 0x40000
	v_lshl_add_u64 v[170:171], s[98:99], 0, v[166:167]
	global_load_dwordx4 v[200:203], v[170:171], off
	global_load_dwordx4 v[208:211], v[170:171], off offset:256
	s_mov_b32 s98, 0x48000
	v_lshl_add_u64 v[170:171], s[98:99], 0, v[166:167]
	global_load_dwordx4 v[212:215], v[170:171], off
	global_load_dwordx4 v[216:219], v[170:171], off offset:256
	s_mov_b32 s98, 0x50000
	v_lshl_add_u64 v[170:171], s[98:99], 0, v[166:167]
	global_load_dwordx4 v[240:243], v[170:171], off
	global_load_dwordx4 v[244:247], v[170:171], off offset:256
	s_mov_b32 s98, 0x58000
	v_lshl_add_u64 v[170:171], s[98:99], 0, v[166:167]
	global_load_dwordx4 v[248:251], v[170:171], off
	global_load_dwordx4 v[252:255], v[170:171], off offset:256
	v_and_b32_e32 v157, 64, v155
	v_xor_b32_e32 v156, 16, v155
	v_add_u32_e32 v157, 64, v157
	v_xor_b32_e32 v169, 32, v155
	v_cmp_lt_i32_e64 s[2:3], v156, v157
	v_cmp_eq_u32_e32 vcc, 0, v168
	s_waitcnt vmcnt(14)
	v_cvt_f32_f16_e32 v168, v158
	v_cndmask_b32_e64 v156, v155, v156, s[2:3]
	v_cmp_lt_i32_e64 s[2:3], v169, v157
	v_cvt_f32_f16_e32 v172, v162
	v_cvt_f32_f16_sdwa v173, v162 dst_sel:DWORD dst_unused:UNUSED_PAD src0_sel:WORD_1
	v_cndmask_b32_e64 v157, v155, v169, s[2:3]
	v_cvt_f32_f16_sdwa v169, v158 dst_sel:DWORD dst_unused:UNUSED_PAD src0_sel:WORD_1
	v_cvt_f32_f16_e32 v158, v159
	v_cvt_f32_f16_sdwa v159, v159 dst_sel:DWORD dst_unused:UNUSED_PAD src0_sel:WORD_1
	v_cvt_f32_f16_e32 v162, v163
	v_cvt_f32_f16_sdwa v163, v163 dst_sel:DWORD dst_unused:UNUSED_PAD src0_sel:WORD_1
	v_cvt_f32_f16_e32 v170, v160
	v_cvt_f32_f16_sdwa v171, v160 dst_sel:DWORD dst_unused:UNUSED_PAD src0_sel:WORD_1
	v_cvt_f32_f16_e32 v160, v161
	v_cvt_f32_f16_sdwa v161, v161 dst_sel:DWORD dst_unused:UNUSED_PAD src0_sel:WORD_1
	v_cvt_f32_f16_e32 v174, v164
	v_cvt_f32_f16_sdwa v175, v164 dst_sel:DWORD dst_unused:UNUSED_PAD src0_sel:WORD_1
	v_cvt_f32_f16_e32 v164, v165
	v_cvt_f32_f16_sdwa v165, v165 dst_sel:DWORD dst_unused:UNUSED_PAD src0_sel:WORD_1
	v_pk_add_f32 v[126:127], v[126:127], v[168:169]
	v_pk_add_f32 v[128:129], v[128:129], v[158:159]
	v_pk_add_f32 v[118:119], v[118:119], v[172:173]
	v_pk_add_f32 v[120:121], v[120:121], v[162:163]
	v_pk_add_f32 v[122:123], v[122:123], v[170:171]
	v_pk_add_f32 v[124:125], v[124:125], v[160:161]
	v_pk_add_f32 v[158:159], v[114:115], v[174:175]
	v_pk_add_f32 v[160:161], v[116:117], v[164:165]
	v_pk_mul_f32 v[116:117], v[126:127], v[126:127]
	v_pk_mul_f32 v[162:163], v[128:129], v[128:129]
	v_cvt_pk_f16_f32 v114, v126, v127
	v_cvt_pk_f16_f32 v115, v128, v129
	v_pk_mul_f32 v[126:127], v[118:119], v[118:119]
	v_pk_mul_f32 v[128:129], v[120:121], v[120:121]
	v_pk_mul_f32 v[164:165], v[122:123], v[122:123]
	v_pk_mul_f32 v[170:171], v[158:159], v[158:159]
	v_add_f32_e32 v128, v128, v129
	v_add_f32_e32 v126, v126, v127
	v_add_f32_e32 v162, v162, v163
	v_add_f32_e32 v116, v116, v117
	v_pk_mul_f32 v[168:169], v[124:125], v[124:125]
	v_pk_mul_f32 v[172:173], v[160:161], v[160:161]
	v_add_f32_e32 v127, v170, v171
	v_add_f32_e32 v117, v164, v165
	v_add_f32_e32 v126, v126, v128
	v_add_f32_e32 v116, v116, v162
	v_add_f32_e32 v129, v172, v173
	v_add_f32_e32 v163, v168, v169
	v_add_f32_e32 v126, v127, v126
	v_add_f32_e32 v116, v117, v116
	v_add_f32_e32 v117, v129, v126
	v_add_f32_e32 v116, v163, v116
	v_lshlrev_b32_e32 v156, 2, v156
	v_add_f32_e32 v126, v116, v117
	ds_bpermute_b32 v127, v156, v126
	v_cvt_pk_f16_f32 v116, v122, v123
	v_cvt_pk_f16_f32 v117, v124, v125
	global_store_dwordx4 v[166:167], v[114:117], off sc1
	v_cvt_pk_f16_f32 v118, v118, v119
	v_cvt_pk_f16_f32 v119, v120, v121
	s_waitcnt lgkmcnt(0)
	v_add_f32_e32 v114, v126, v127
	v_lshlrev_b32_e32 v116, 2, v157
	ds_bpermute_b32 v115, v116, v114
	v_cvt_pk_f16_f32 v120, v158, v159
	v_cvt_pk_f16_f32 v121, v160, v161
	global_store_dwordx4 v[166:167], v[118:121], off offset:256 sc1
	s_and_saveexec_b64 s[2:3], vcc
	s_cbranch_execz .LBB0_405
	v_lshl_add_u64 v[118:119], v[148:149], 2, s[18:19]
	s_waitcnt lgkmcnt(0)
	v_add_f32_e32 v114, v114, v115
	global_atomic_add_f32 v[118:119], v114, off
; __device__ __forceinline__ unsigned pkh(float lo, float hi) { f32x2 v = {lo, hi}; h16x2 h = __builtin_convertvector(v, h16x2); return __builtin_bit_cast(unsigned, h); }
; __device__ __forceinline__ unsigned pk8(float a, float b, float c, float d) { int w = __builtin_amdgcn_cvt_pk_fp8_f32(a, b, 0, false); w = __builtin_amdgcn_cvt_pk_fp8_f32(c, d, w, true); return (unsigned)w; }
;     __device__ __forceinline__ void operator()(f32x4 (&acc)[2][2][4][2], const Unit& u, const Order& S, int wr, int wc, int fr_, int fq_, LAS unsigned char*, int) const {
;     ...
;         for (int ai = 0; ai < 2; ++ai)
; #pragma unroll
;             for (int m = 0; m < 4; ++m) {
;                 const int row = row0 + ai * HALF + m * 16; const size_t off = (size_t)row * DM + col0;
;                 float sq = 0.f;
; #pragma unroll
;                 for (int bj = 0; bj < 2; ++bj) {
;                     const h16x8 bs = *(const h16x8*)(h16 + off + bj * HALF);
;                     f32x4 o0 = acc[ai][bj][m][0] * pre, o1 = acc[ai][bj][m][1] * pre;
; #pragma unroll
;                     for (int e = 0; e < 4; ++e) { o0[e] += (float)bs[e]; o1[e] += (float)bs[4 + e]; }
;                     if (out32) { if (!dry) { __builtin_nontemporal_store(o0, (f32x4*)(out32 + off + bj * HALF)); __builtin_nontemporal_store(o1, (f32x4*)(out32 + off + bj * HALF + 4)); } }
;                     else if (!dry) {
;                         sq += (o0[0] * o0[0] + o0[1] * o0[1]) + (o0[2] * o0[2] + o0[3] * o0[3]) + (o1[0] * o1[0] + o1[1] * o1[1]) + (o1[2] * o1[2] + o1[3] * o1[3]);
;                         u32x4 w; w.x = pkh(o0[0], o0[1]); w.y = pkh(o0[2], o0[3]); w.z = pkh(o1[0], o1[1]); w.w = pkh(o1[2], o1[3]);
;                         *(u32x4*)(h16 + off + bj * HALF) = w;
;                         if (h8) { u32x2 q; q.x = pk8(o0[0] * F8_SA, o0[1] * F8_SA, o0[2] * F8_SA, o0[3] * F8_SA); q.y = pk8(o1[0] * F8_SA, o1[1] * F8_SA, o1[2] * F8_SA, o1[3] * F8_SA); *(u32x2*)(h8 + off + bj * HALF) = q; } }
;                 }
;                 if (!out32 && !dry) { sq += __shfl_xor(sq, 16); sq += __shfl_xor(sq, 32); if (fq == 0) atomicAdd(ss_out + row, sq); }
.LBB0_405:
	s_or_b64 exec, exec, s[2:3]
	v_add_u32_e32 v114, 16, v148
	s_waitcnt lgkmcnt(0)
	v_ashrrev_i32_e32 v115, 31, v114
	v_lshlrev_b64 v[118:119], 11, v[114:115]
	v_lshl_add_u64 v[118:119], s[90:91], 0, v[118:119]
	v_lshl_add_u64 v[126:127], v[146:147], 1, v[118:119]
	s_waitcnt vmcnt(15)
	v_cvt_f32_f16_e32 v128, v176
	v_cvt_f32_f16_sdwa v129, v176 dst_sel:DWORD dst_unused:UNUSED_PAD src0_sel:WORD_1
	v_cvt_f32_f16_e32 v118, v177
	v_cvt_f32_f16_sdwa v119, v177 dst_sel:DWORD dst_unused:UNUSED_PAD src0_sel:WORD_1
	s_waitcnt vmcnt(14)
	v_cvt_f32_f16_e32 v160, v180
	v_cvt_f32_f16_sdwa v161, v180 dst_sel:DWORD dst_unused:UNUSED_PAD src0_sel:WORD_1
	v_cvt_f32_f16_e32 v122, v181
	v_cvt_f32_f16_sdwa v123, v181 dst_sel:DWORD dst_unused:UNUSED_PAD src0_sel:WORD_1
	v_cvt_f32_f16_e32 v158, v178
	v_cvt_f32_f16_sdwa v159, v178 dst_sel:DWORD dst_unused:UNUSED_PAD src0_sel:WORD_1
	v_cvt_f32_f16_e32 v120, v179
	v_cvt_f32_f16_sdwa v121, v179 dst_sel:DWORD dst_unused:UNUSED_PAD src0_sel:WORD_1
	v_cvt_f32_f16_e32 v162, v182
	v_cvt_f32_f16_sdwa v163, v182 dst_sel:DWORD dst_unused:UNUSED_PAD src0_sel:WORD_1
	v_cvt_f32_f16_e32 v124, v183
	v_cvt_f32_f16_sdwa v125, v183 dst_sel:DWORD dst_unused:UNUSED_PAD src0_sel:WORD_1
	v_pk_add_f32 v[110:111], v[110:111], v[128:129]
	v_pk_add_f32 v[112:113], v[112:113], v[118:119]
	v_pk_add_f32 v[102:103], v[102:103], v[160:161]
	v_pk_add_f32 v[104:105], v[104:105], v[122:123]
	v_pk_add_f32 v[106:107], v[106:107], v[158:159]
	v_pk_add_f32 v[108:109], v[108:109], v[120:121]
	v_pk_add_f32 v[118:119], v[98:99], v[162:163]
	v_pk_add_f32 v[120:121], v[100:101], v[124:125]
	v_pk_mul_f32 v[100:101], v[110:111], v[110:111]
	v_pk_mul_f32 v[122:123], v[112:113], v[112:113]
	v_cvt_pk_f16_f32 v98, v110, v111
	v_cvt_pk_f16_f32 v99, v112, v113
	v_pk_mul_f32 v[110:111], v[102:103], v[102:103]
	v_pk_mul_f32 v[112:113], v[104:105], v[104:105]
	v_pk_mul_f32 v[124:125], v[106:107], v[106:107]
	v_pk_mul_f32 v[158:159], v[118:119], v[118:119]
	v_add_f32_e32 v112, v112, v113
	v_add_f32_e32 v110, v110, v111
	v_add_f32_e32 v117, v122, v123
	v_add_f32_e32 v100, v100, v101
	v_pk_mul_f32 v[128:129], v[108:109], v[108:109]
	v_pk_mul_f32 v[160:161], v[120:121], v[120:121]
	v_add_f32_e32 v111, v158, v159
	v_add_f32_e32 v101, v124, v125
	v_add_f32_e32 v110, v110, v112
	v_add_f32_e32 v100, v100, v117
	v_add_f32_e32 v113, v160, v161
	v_add_f32_e32 v122, v128, v129
	v_add_f32_e32 v110, v111, v110
	v_add_f32_e32 v100, v101, v100
	v_add_f32_e32 v101, v113, v110
	v_add_f32_e32 v100, v122, v100
	v_add_f32_e32 v110, v100, v101
	ds_bpermute_b32 v111, v156, v110
	v_cvt_pk_f16_f32 v100, v106, v107
	v_cvt_pk_f16_f32 v101, v108, v109
	global_store_dwordx4 v[126:127], v[98:101], off sc1
	s_waitcnt lgkmcnt(0)
	s_nop 0
	v_add_f32_e32 v98, v110, v111
	ds_bpermute_b32 v99, v116, v98
	v_cvt_pk_f16_f32 v100, v102, v103
	v_cvt_pk_f16_f32 v101, v104, v105
	v_cvt_pk_f16_f32 v102, v118, v119
	v_cvt_pk_f16_f32 v103, v120, v121
	global_store_dwordx4 v[126:127], v[100:103], off offset:256 sc1
	s_and_saveexec_b64 s[2:3], vcc
	s_cbranch_execz .LBB0_407
	v_lshl_add_u64 v[100:101], v[114:115], 2, s[18:19]
	s_waitcnt lgkmcnt(0)
	v_add_f32_e32 v98, v98, v99
	global_atomic_add_f32 v[100:101], v98, off
.LBB0_407:
	s_or_b64 exec, exec, s[2:3]
	v_add_u32_e32 v98, 32, v148
	s_waitcnt lgkmcnt(0)
	v_ashrrev_i32_e32 v99, 31, v98
	v_lshlrev_b64 v[100:101], 11, v[98:99]
	v_lshl_add_u64 v[100:101], s[90:91], 0, v[100:101]
	v_lshl_add_u64 v[108:109], v[146:147], 1, v[100:101]
	s_waitcnt vmcnt(15)
	v_cvt_f32_f16_e32 v110, v184
	v_cvt_f32_f16_sdwa v111, v184 dst_sel:DWORD dst_unused:UNUSED_PAD src0_sel:WORD_1
	v_cvt_f32_f16_e32 v100, v185
	v_cvt_f32_f16_sdwa v101, v185 dst_sel:DWORD dst_unused:UNUSED_PAD src0_sel:WORD_1
	s_waitcnt vmcnt(14)
	v_cvt_f32_f16_e32 v114, v188
	v_cvt_f32_f16_sdwa v115, v188 dst_sel:DWORD dst_unused:UNUSED_PAD src0_sel:WORD_1
	v_cvt_f32_f16_e32 v104, v189
	v_cvt_f32_f16_sdwa v105, v189 dst_sel:DWORD dst_unused:UNUSED_PAD src0_sel:WORD_1
	v_cvt_f32_f16_e32 v112, v186
	v_cvt_f32_f16_sdwa v113, v186 dst_sel:DWORD dst_unused:UNUSED_PAD src0_sel:WORD_1
	v_cvt_f32_f16_e32 v102, v187
	v_cvt_f32_f16_sdwa v103, v187 dst_sel:DWORD dst_unused:UNUSED_PAD src0_sel:WORD_1
	v_cvt_f32_f16_e32 v118, v190
	v_cvt_f32_f16_sdwa v119, v190 dst_sel:DWORD dst_unused:UNUSED_PAD src0_sel:WORD_1
	v_cvt_f32_f16_e32 v106, v191
	v_cvt_f32_f16_sdwa v107, v191 dst_sel:DWORD dst_unused:UNUSED_PAD src0_sel:WORD_1
	v_pk_add_f32 v[94:95], v[94:95], v[110:111]
	v_pk_add_f32 v[96:97], v[96:97], v[100:101]
	v_pk_add_f32 v[86:87], v[86:87], v[114:115]
	v_pk_add_f32 v[88:89], v[88:89], v[104:105]
	v_pk_add_f32 v[90:91], v[90:91], v[112:113]
	v_pk_add_f32 v[92:93], v[92:93], v[102:103]
	v_pk_add_f32 v[100:101], v[82:83], v[118:119]
	v_pk_add_f32 v[102:103], v[84:85], v[106:107]
	v_pk_mul_f32 v[84:85], v[94:95], v[94:95]
	v_pk_mul_f32 v[104:105], v[96:97], v[96:97]
	v_cvt_pk_f16_f32 v82, v94, v95
	v_cvt_pk_f16_f32 v83, v96, v97
	v_pk_mul_f32 v[94:95], v[86:87], v[86:87]
	v_pk_mul_f32 v[96:97], v[88:89], v[88:89]
	v_pk_mul_f32 v[106:107], v[90:91], v[90:91]
	v_pk_mul_f32 v[112:113], v[100:101], v[100:101]
	v_add_f32_e32 v96, v96, v97
	v_add_f32_e32 v94, v94, v95
	v_add_f32_e32 v104, v104, v105
	v_add_f32_e32 v84, v84, v85
	v_pk_mul_f32 v[110:111], v[92:93], v[92:93]
	v_pk_mul_f32 v[114:115], v[102:103], v[102:103]
	v_add_f32_e32 v95, v112, v113
	v_add_f32_e32 v85, v106, v107
	v_add_f32_e32 v94, v94, v96
	v_add_f32_e32 v84, v84, v104
	v_add_f32_e32 v97, v114, v115
	v_add_f32_e32 v105, v110, v111
	v_add_f32_e32 v94, v95, v94
	v_add_f32_e32 v84, v85, v84
	v_add_f32_e32 v85, v97, v94
	v_add_f32_e32 v84, v105, v84
	v_add_f32_e32 v94, v84, v85
	ds_bpermute_b32 v95, v156, v94
	v_cvt_pk_f16_f32 v84, v90, v91
	v_cvt_pk_f16_f32 v85, v92, v93
	global_store_dwordx4 v[108:109], v[82:85], off sc1
	s_waitcnt lgkmcnt(0)
	s_nop 0
	v_add_f32_e32 v82, v94, v95
	ds_bpermute_b32 v83, v116, v82
	v_cvt_pk_f16_f32 v84, v86, v87
	v_cvt_pk_f16_f32 v85, v88, v89
	v_cvt_pk_f16_f32 v86, v100, v101
	v_cvt_pk_f16_f32 v87, v102, v103
	global_store_dwordx4 v[108:109], v[84:87], off offset:256 sc1
	s_and_saveexec_b64 s[2:3], vcc
	s_cbranch_execz .LBB0_409
	v_lshl_add_u64 v[84:85], v[98:99], 2, s[18:19]
	s_waitcnt lgkmcnt(0)
	v_add_f32_e32 v82, v82, v83
	global_atomic_add_f32 v[84:85], v82, off
; __device__ __forceinline__ unsigned pkh(float lo, float hi) { f32x2 v = {lo, hi}; h16x2 h = __builtin_convertvector(v, h16x2); return __builtin_bit_cast(unsigned, h); }
; __device__ __forceinline__ unsigned pk8(float a, float b, float c, float d) { int w = __builtin_amdgcn_cvt_pk_fp8_f32(a, b, 0, false); w = __builtin_amdgcn_cvt_pk_fp8_f32(c, d, w, true); return (unsigned)w; }
;     __device__ __forceinline__ void operator()(f32x4 (&acc)[2][2][4][2], const Unit& u, const Order& S, int wr, int wc, int fr_, int fq_, LAS unsigned char*, int) const {
;     ...
;         for (int ai = 0; ai < 2; ++ai)
; #pragma unroll
;             for (int m = 0; m < 4; ++m) {
;                 const int row = row0 + ai * HALF + m * 16; const size_t off = (size_t)row * DM + col0;
;                 float sq = 0.f;
; #pragma unroll
;                 for (int bj = 0; bj < 2; ++bj) {
;                     const h16x8 bs = *(const h16x8*)(h16 + off + bj * HALF);
;                     f32x4 o0 = acc[ai][bj][m][0] * pre, o1 = acc[ai][bj][m][1] * pre;
; #pragma unroll
;                     for (int e = 0; e < 4; ++e) { o0[e] += (float)bs[e]; o1[e] += (float)bs[4 + e]; }
;                     if (out32) { if (!dry) { __builtin_nontemporal_store(o0, (f32x4*)(out32 + off + bj * HALF)); __builtin_nontemporal_store(o1, (f32x4*)(out32 + off + bj * HALF + 4)); } }
;                     else if (!dry) {
;                         sq += (o0[0] * o0[0] + o0[1] * o0[1]) + (o0[2] * o0[2] + o0[3] * o0[3]) + (o1[0] * o1[0] + o1[1] * o1[1]) + (o1[2] * o1[2] + o1[3] * o1[3]);
;                         u32x4 w; w.x = pkh(o0[0], o0[1]); w.y = pkh(o0[2], o0[3]); w.z = pkh(o1[0], o1[1]); w.w = pkh(o1[2], o1[3]);
;                         *(u32x4*)(h16 + off + bj * HALF) = w;
;                         if (h8) { u32x2 q; q.x = pk8(o0[0] * F8_SA, o0[1] * F8_SA, o0[2] * F8_SA, o0[3] * F8_SA); q.y = pk8(o1[0] * F8_SA, o1[1] * F8_SA, o1[2] * F8_SA, o1[3] * F8_SA); *(u32x2*)(h8 + off + bj * HALF) = q; } }
;                 }
;                 if (!out32 && !dry) { sq += __shfl_xor(sq, 16); sq += __shfl_xor(sq, 32); if (fq == 0) atomicAdd(ss_out + row, sq); }
.LBB0_409:
	s_or_b64 exec, exec, s[2:3]
	v_add_u32_e32 v82, 48, v148
	s_waitcnt lgkmcnt(0)
	v_ashrrev_i32_e32 v83, 31, v82
	v_lshlrev_b64 v[84:85], 11, v[82:83]
	v_lshl_add_u64 v[84:85], s[90:91], 0, v[84:85]
	v_lshl_add_u64 v[92:93], v[146:147], 1, v[84:85]
	s_waitcnt vmcnt(15)
	v_cvt_f32_f16_e32 v94, v192
	v_cvt_f32_f16_sdwa v95, v192 dst_sel:DWORD dst_unused:UNUSED_PAD src0_sel:WORD_1
	v_cvt_f32_f16_e32 v84, v193
	v_cvt_f32_f16_sdwa v85, v193 dst_sel:DWORD dst_unused:UNUSED_PAD src0_sel:WORD_1
	s_waitcnt vmcnt(14)
	v_cvt_f32_f16_e32 v98, v196
	v_cvt_f32_f16_sdwa v99, v196 dst_sel:DWORD dst_unused:UNUSED_PAD src0_sel:WORD_1
	v_cvt_f32_f16_e32 v88, v197
	v_cvt_f32_f16_sdwa v89, v197 dst_sel:DWORD dst_unused:UNUSED_PAD src0_sel:WORD_1
	v_cvt_f32_f16_e32 v96, v194
	v_cvt_f32_f16_sdwa v97, v194 dst_sel:DWORD dst_unused:UNUSED_PAD src0_sel:WORD_1
	v_cvt_f32_f16_e32 v86, v195
	v_cvt_f32_f16_sdwa v87, v195 dst_sel:DWORD dst_unused:UNUSED_PAD src0_sel:WORD_1
	v_cvt_f32_f16_e32 v100, v198
	v_cvt_f32_f16_sdwa v101, v198 dst_sel:DWORD dst_unused:UNUSED_PAD src0_sel:WORD_1
	v_cvt_f32_f16_e32 v90, v199
	v_cvt_f32_f16_sdwa v91, v199 dst_sel:DWORD dst_unused:UNUSED_PAD src0_sel:WORD_1
	v_pk_add_f32 v[78:79], v[78:79], v[94:95]
	v_pk_add_f32 v[80:81], v[80:81], v[84:85]
	v_pk_add_f32 v[70:71], v[70:71], v[98:99]
	v_pk_add_f32 v[72:73], v[72:73], v[88:89]
	v_pk_add_f32 v[74:75], v[74:75], v[96:97]
	v_pk_add_f32 v[76:77], v[76:77], v[86:87]
	v_pk_add_f32 v[84:85], v[66:67], v[100:101]
	v_pk_add_f32 v[86:87], v[68:69], v[90:91]
	v_pk_mul_f32 v[68:69], v[78:79], v[78:79]
	v_pk_mul_f32 v[88:89], v[80:81], v[80:81]
	v_cvt_pk_f16_f32 v66, v78, v79
	v_cvt_pk_f16_f32 v67, v80, v81
	v_pk_mul_f32 v[78:79], v[70:71], v[70:71]
	v_pk_mul_f32 v[80:81], v[72:73], v[72:73]
	v_pk_mul_f32 v[90:91], v[74:75], v[74:75]
	v_pk_mul_f32 v[96:97], v[84:85], v[84:85]
	v_add_f32_e32 v80, v80, v81
	v_add_f32_e32 v78, v78, v79
	v_add_f32_e32 v88, v88, v89
	v_add_f32_e32 v68, v68, v69
	v_pk_mul_f32 v[94:95], v[76:77], v[76:77]
	v_pk_mul_f32 v[98:99], v[86:87], v[86:87]
	v_add_f32_e32 v79, v96, v97
	v_add_f32_e32 v69, v90, v91
	v_add_f32_e32 v78, v78, v80
	v_add_f32_e32 v68, v68, v88
	v_add_f32_e32 v81, v98, v99
	v_add_f32_e32 v89, v94, v95
	v_add_f32_e32 v78, v79, v78
	v_add_f32_e32 v68, v69, v68
	v_add_f32_e32 v69, v81, v78
	v_add_f32_e32 v68, v89, v68
	v_add_f32_e32 v78, v68, v69
	ds_bpermute_b32 v79, v156, v78
	v_cvt_pk_f16_f32 v68, v74, v75
	v_cvt_pk_f16_f32 v69, v76, v77
	global_store_dwordx4 v[92:93], v[66:69], off sc1
	s_waitcnt lgkmcnt(0)
	s_nop 0
	v_add_f32_e32 v66, v78, v79
	ds_bpermute_b32 v67, v116, v66
	v_cvt_pk_f16_f32 v68, v70, v71
	v_cvt_pk_f16_f32 v69, v72, v73
	v_cvt_pk_f16_f32 v70, v84, v85
	v_cvt_pk_f16_f32 v71, v86, v87
	global_store_dwordx4 v[92:93], v[68:71], off offset:256 sc1
	s_and_saveexec_b64 s[2:3], vcc
	s_cbranch_execz .LBB0_411
	v_lshl_add_u64 v[68:69], v[82:83], 2, s[18:19]
	s_waitcnt lgkmcnt(0)
	v_add_f32_e32 v66, v66, v67
	global_atomic_add_f32 v[68:69], v66, off
.LBB0_411:
	s_or_b64 exec, exec, s[2:3]
	v_add_u32_e32 v66, 0x80, v148
	s_waitcnt lgkmcnt(0)
	v_ashrrev_i32_e32 v67, 31, v66
	v_lshlrev_b64 v[68:69], 11, v[66:67]
	v_lshl_add_u64 v[68:69], s[90:91], 0, v[68:69]
	v_lshl_add_u64 v[76:77], v[146:147], 1, v[68:69]
	s_waitcnt vmcnt(15)
	v_cvt_f32_f16_e32 v78, v200
	v_cvt_f32_f16_sdwa v79, v200 dst_sel:DWORD dst_unused:UNUSED_PAD src0_sel:WORD_1
	v_cvt_f32_f16_e32 v68, v201
	v_cvt_f32_f16_sdwa v69, v201 dst_sel:DWORD dst_unused:UNUSED_PAD src0_sel:WORD_1
	s_waitcnt vmcnt(14)
	v_cvt_f32_f16_e32 v82, v208
	v_cvt_f32_f16_sdwa v83, v208 dst_sel:DWORD dst_unused:UNUSED_PAD src0_sel:WORD_1
	v_cvt_f32_f16_e32 v72, v209
	v_cvt_f32_f16_sdwa v73, v209 dst_sel:DWORD dst_unused:UNUSED_PAD src0_sel:WORD_1
	v_cvt_f32_f16_e32 v80, v202
	v_cvt_f32_f16_sdwa v81, v202 dst_sel:DWORD dst_unused:UNUSED_PAD src0_sel:WORD_1
	v_cvt_f32_f16_e32 v70, v203
	v_cvt_f32_f16_sdwa v71, v203 dst_sel:DWORD dst_unused:UNUSED_PAD src0_sel:WORD_1
	v_cvt_f32_f16_e32 v84, v210
	v_cvt_f32_f16_sdwa v85, v210 dst_sel:DWORD dst_unused:UNUSED_PAD src0_sel:WORD_1
	v_cvt_f32_f16_e32 v74, v211
	v_cvt_f32_f16_sdwa v75, v211 dst_sel:DWORD dst_unused:UNUSED_PAD src0_sel:WORD_1
	v_pk_add_f32 v[62:63], v[62:63], v[78:79]
	v_pk_add_f32 v[64:65], v[64:65], v[68:69]
	v_pk_add_f32 v[54:55], v[54:55], v[82:83]
	v_pk_add_f32 v[56:57], v[56:57], v[72:73]
	v_pk_add_f32 v[58:59], v[58:59], v[80:81]
	v_pk_add_f32 v[60:61], v[60:61], v[70:71]
	v_pk_add_f32 v[68:69], v[50:51], v[84:85]
	v_pk_add_f32 v[70:71], v[52:53], v[74:75]
	v_pk_mul_f32 v[52:53], v[62:63], v[62:63]
	v_pk_mul_f32 v[72:73], v[64:65], v[64:65]
	v_cvt_pk_f16_f32 v50, v62, v63
	v_cvt_pk_f16_f32 v51, v64, v65
	v_pk_mul_f32 v[62:63], v[54:55], v[54:55]
	v_pk_mul_f32 v[64:65], v[56:57], v[56:57]
	v_pk_mul_f32 v[74:75], v[58:59], v[58:59]
	v_pk_mul_f32 v[80:81], v[68:69], v[68:69]
	v_add_f32_e32 v64, v64, v65
	v_add_f32_e32 v62, v62, v63
	v_add_f32_e32 v72, v72, v73
	v_add_f32_e32 v52, v52, v53
	v_pk_mul_f32 v[78:79], v[60:61], v[60:61]
	v_pk_mul_f32 v[82:83], v[70:71], v[70:71]
	v_add_f32_e32 v63, v80, v81
	v_add_f32_e32 v53, v74, v75
	v_add_f32_e32 v62, v62, v64
	v_add_f32_e32 v52, v52, v72
	v_add_f32_e32 v65, v82, v83
	v_add_f32_e32 v73, v78, v79
	v_add_f32_e32 v62, v63, v62
	v_add_f32_e32 v52, v53, v52
	v_add_f32_e32 v53, v65, v62
	v_add_f32_e32 v52, v73, v52
	v_add_f32_e32 v62, v52, v53
	ds_bpermute_b32 v63, v156, v62
	v_cvt_pk_f16_f32 v52, v58, v59
	v_cvt_pk_f16_f32 v53, v60, v61
	global_store_dwordx4 v[76:77], v[50:53], off sc1
	s_waitcnt lgkmcnt(0)
	s_nop 0
	v_add_f32_e32 v50, v62, v63
	ds_bpermute_b32 v51, v116, v50
	v_cvt_pk_f16_f32 v52, v54, v55
	v_cvt_pk_f16_f32 v53, v56, v57
	v_cvt_pk_f16_f32 v54, v68, v69
	v_cvt_pk_f16_f32 v55, v70, v71
	global_store_dwordx4 v[76:77], v[52:55], off offset:256 sc1
	s_and_saveexec_b64 s[2:3], vcc
	s_cbranch_execz .LBB0_413
	v_lshl_add_u64 v[52:53], v[66:67], 2, s[18:19]
	s_waitcnt lgkmcnt(0)
	v_add_f32_e32 v50, v50, v51
	global_atomic_add_f32 v[52:53], v50, off
; __device__ __forceinline__ unsigned pkh(float lo, float hi) { f32x2 v = {lo, hi}; h16x2 h = __builtin_convertvector(v, h16x2); return __builtin_bit_cast(unsigned, h); }
; __device__ __forceinline__ unsigned pk8(float a, float b, float c, float d) { int w = __builtin_amdgcn_cvt_pk_fp8_f32(a, b, 0, false); w = __builtin_amdgcn_cvt_pk_fp8_f32(c, d, w, true); return (unsigned)w; }
;     __device__ __forceinline__ void operator()(f32x4 (&acc)[2][2][4][2], const Unit& u, const Order& S, int wr, int wc, int fr_, int fq_, LAS unsigned char*, int) const {
;     ...
;         for (int ai = 0; ai < 2; ++ai)
; #pragma unroll
;             for (int m = 0; m < 4; ++m) {
;                 const int row = row0 + ai * HALF + m * 16; const size_t off = (size_t)row * DM + col0;
;                 float sq = 0.f;
; #pragma unroll
;                 for (int bj = 0; bj < 2; ++bj) {
;                     const h16x8 bs = *(const h16x8*)(h16 + off + bj * HALF);
;                     f32x4 o0 = acc[ai][bj][m][0] * pre, o1 = acc[ai][bj][m][1] * pre;
; #pragma unroll
;                     for (int e = 0; e < 4; ++e) { o0[e] += (float)bs[e]; o1[e] += (float)bs[4 + e]; }
;                     if (out32) { if (!dry) { __builtin_nontemporal_store(o0, (f32x4*)(out32 + off + bj * HALF)); __builtin_nontemporal_store(o1, (f32x4*)(out32 + off + bj * HALF + 4)); } }
;                     else if (!dry) {
;                         sq += (o0[0] * o0[0] + o0[1] * o0[1]) + (o0[2] * o0[2] + o0[3] * o0[3]) + (o1[0] * o1[0] + o1[1] * o1[1]) + (o1[2] * o1[2] + o1[3] * o1[3]);
;                         u32x4 w; w.x = pkh(o0[0], o0[1]); w.y = pkh(o0[2], o0[3]); w.z = pkh(o1[0], o1[1]); w.w = pkh(o1[2], o1[3]);
;                         *(u32x4*)(h16 + off + bj * HALF) = w;
;                         if (h8) { u32x2 q; q.x = pk8(o0[0] * F8_SA, o0[1] * F8_SA, o0[2] * F8_SA, o0[3] * F8_SA); q.y = pk8(o1[0] * F8_SA, o1[1] * F8_SA, o1[2] * F8_SA, o1[3] * F8_SA); *(u32x2*)(h8 + off + bj * HALF) = q; } }
;                 }
;                 if (!out32 && !dry) { sq += __shfl_xor(sq, 16); sq += __shfl_xor(sq, 32); if (fq == 0) atomicAdd(ss_out + row, sq); }
.LBB0_413:
	s_or_b64 exec, exec, s[2:3]
	v_add_u32_e32 v50, 0x90, v148
	s_waitcnt lgkmcnt(0)
	v_ashrrev_i32_e32 v51, 31, v50
	v_lshlrev_b64 v[52:53], 11, v[50:51]
	v_lshl_add_u64 v[52:53], s[90:91], 0, v[52:53]
	v_lshl_add_u64 v[60:61], v[146:147], 1, v[52:53]
	s_waitcnt vmcnt(15)
	v_cvt_f32_f16_e32 v62, v212
	v_cvt_f32_f16_sdwa v63, v212 dst_sel:DWORD dst_unused:UNUSED_PAD src0_sel:WORD_1
	v_cvt_f32_f16_e32 v52, v213
	v_cvt_f32_f16_sdwa v53, v213 dst_sel:DWORD dst_unused:UNUSED_PAD src0_sel:WORD_1
	s_waitcnt vmcnt(14)
	v_cvt_f32_f16_e32 v66, v216
	v_cvt_f32_f16_sdwa v67, v216 dst_sel:DWORD dst_unused:UNUSED_PAD src0_sel:WORD_1
	v_cvt_f32_f16_e32 v56, v217
	v_cvt_f32_f16_sdwa v57, v217 dst_sel:DWORD dst_unused:UNUSED_PAD src0_sel:WORD_1
	v_cvt_f32_f16_e32 v64, v214
	v_cvt_f32_f16_sdwa v65, v214 dst_sel:DWORD dst_unused:UNUSED_PAD src0_sel:WORD_1
	v_cvt_f32_f16_e32 v54, v215
	v_cvt_f32_f16_sdwa v55, v215 dst_sel:DWORD dst_unused:UNUSED_PAD src0_sel:WORD_1
	v_cvt_f32_f16_e32 v68, v218
	v_cvt_f32_f16_sdwa v69, v218 dst_sel:DWORD dst_unused:UNUSED_PAD src0_sel:WORD_1
	v_cvt_f32_f16_e32 v58, v219
	v_cvt_f32_f16_sdwa v59, v219 dst_sel:DWORD dst_unused:UNUSED_PAD src0_sel:WORD_1
	v_pk_add_f32 v[46:47], v[46:47], v[62:63]
	v_pk_add_f32 v[48:49], v[48:49], v[52:53]
	v_pk_add_f32 v[38:39], v[38:39], v[66:67]
	v_pk_add_f32 v[40:41], v[40:41], v[56:57]
	v_pk_add_f32 v[42:43], v[42:43], v[64:65]
	v_pk_add_f32 v[44:45], v[44:45], v[54:55]
	v_pk_add_f32 v[52:53], v[34:35], v[68:69]
	v_pk_add_f32 v[54:55], v[36:37], v[58:59]
	v_pk_mul_f32 v[36:37], v[46:47], v[46:47]
	v_pk_mul_f32 v[56:57], v[48:49], v[48:49]
	v_cvt_pk_f16_f32 v34, v46, v47
	v_cvt_pk_f16_f32 v35, v48, v49
	v_pk_mul_f32 v[46:47], v[38:39], v[38:39]
	v_pk_mul_f32 v[48:49], v[40:41], v[40:41]
	v_pk_mul_f32 v[58:59], v[42:43], v[42:43]
	v_pk_mul_f32 v[64:65], v[52:53], v[52:53]
	v_add_f32_e32 v48, v48, v49
	v_add_f32_e32 v46, v46, v47
	v_add_f32_e32 v56, v56, v57
	v_add_f32_e32 v36, v36, v37
	v_pk_mul_f32 v[62:63], v[44:45], v[44:45]
	v_pk_mul_f32 v[66:67], v[54:55], v[54:55]
	v_add_f32_e32 v47, v64, v65
	v_add_f32_e32 v37, v58, v59
	v_add_f32_e32 v46, v46, v48
	v_add_f32_e32 v36, v36, v56
	v_add_f32_e32 v49, v66, v67
	v_add_f32_e32 v57, v62, v63
	v_add_f32_e32 v46, v47, v46
	v_add_f32_e32 v36, v37, v36
	v_add_f32_e32 v37, v49, v46
	v_add_f32_e32 v36, v57, v36
	v_add_f32_e32 v46, v36, v37
	ds_bpermute_b32 v47, v156, v46
	v_cvt_pk_f16_f32 v36, v42, v43
	v_cvt_pk_f16_f32 v37, v44, v45
	global_store_dwordx4 v[60:61], v[34:37], off sc1
	s_waitcnt lgkmcnt(0)
	s_nop 0
	v_add_f32_e32 v34, v46, v47
	ds_bpermute_b32 v35, v116, v34
	v_cvt_pk_f16_f32 v36, v38, v39
	v_cvt_pk_f16_f32 v37, v40, v41
	v_cvt_pk_f16_f32 v38, v52, v53
	v_cvt_pk_f16_f32 v39, v54, v55
	global_store_dwordx4 v[60:61], v[36:39], off offset:256 sc1
	s_and_saveexec_b64 s[2:3], vcc
	s_cbranch_execz .LBB0_415
	v_lshl_add_u64 v[36:37], v[50:51], 2, s[18:19]
	s_waitcnt lgkmcnt(0)
	v_add_f32_e32 v34, v34, v35
	global_atomic_add_f32 v[36:37], v34, off
; __device__ __forceinline__ unsigned pkh(float lo, float hi) { f32x2 v = {lo, hi}; h16x2 h = __builtin_convertvector(v, h16x2); return __builtin_bit_cast(unsigned, h); }
; __device__ __forceinline__ unsigned pk8(float a, float b, float c, float d) { int w = __builtin_amdgcn_cvt_pk_fp8_f32(a, b, 0, false); w = __builtin_amdgcn_cvt_pk_fp8_f32(c, d, w, true); return (unsigned)w; }
;     __device__ __forceinline__ void operator()(f32x4 (&acc)[2][2][4][2], const Unit& u, const Order& S, int wr, int wc, int fr_, int fq_, LAS unsigned char*, int) const {
;     ...
;         for (int ai = 0; ai < 2; ++ai)
; #pragma unroll
;             for (int m = 0; m < 4; ++m) {
;                 const int row = row0 + ai * HALF + m * 16; const size_t off = (size_t)row * DM + col0;
;                 float sq = 0.f;
; #pragma unroll
;                 for (int bj = 0; bj < 2; ++bj) {
;                     const h16x8 bs = *(const h16x8*)(h16 + off + bj * HALF);
;                     f32x4 o0 = acc[ai][bj][m][0] * pre, o1 = acc[ai][bj][m][1] * pre;
; #pragma unroll
;                     for (int e = 0; e < 4; ++e) { o0[e] += (float)bs[e]; o1[e] += (float)bs[4 + e]; }
;                     if (out32) { if (!dry) { __builtin_nontemporal_store(o0, (f32x4*)(out32 + off + bj * HALF)); __builtin_nontemporal_store(o1, (f32x4*)(out32 + off + bj * HALF + 4)); } }
;                     else if (!dry) {
;                         sq += (o0[0] * o0[0] + o0[1] * o0[1]) + (o0[2] * o0[2] + o0[3] * o0[3]) + (o1[0] * o1[0] + o1[1] * o1[1]) + (o1[2] * o1[2] + o1[3] * o1[3]);
;                         u32x4 w; w.x = pkh(o0[0], o0[1]); w.y = pkh(o0[2], o0[3]); w.z = pkh(o1[0], o1[1]); w.w = pkh(o1[2], o1[3]);
;                         *(u32x4*)(h16 + off + bj * HALF) = w;
;                         if (h8) { u32x2 q; q.x = pk8(o0[0] * F8_SA, o0[1] * F8_SA, o0[2] * F8_SA, o0[3] * F8_SA); q.y = pk8(o1[0] * F8_SA, o1[1] * F8_SA, o1[2] * F8_SA, o1[3] * F8_SA); *(u32x2*)(h8 + off + bj * HALF) = q; } }
;                 }
;                 if (!out32 && !dry) { sq += __shfl_xor(sq, 16); sq += __shfl_xor(sq, 32); if (fq == 0) atomicAdd(ss_out + row, sq); }
.LBB0_415:
	s_or_b64 exec, exec, s[2:3]
	v_add_u32_e32 v34, 0xa0, v148
	s_waitcnt lgkmcnt(0)
	v_ashrrev_i32_e32 v35, 31, v34
	v_lshlrev_b64 v[36:37], 11, v[34:35]
	v_lshl_add_u64 v[36:37], s[90:91], 0, v[36:37]
	v_lshl_add_u64 v[44:45], v[146:147], 1, v[36:37]
	s_waitcnt vmcnt(15)
	v_cvt_f32_f16_e32 v46, v240
	v_cvt_f32_f16_sdwa v47, v240 dst_sel:DWORD dst_unused:UNUSED_PAD src0_sel:WORD_1
	v_cvt_f32_f16_e32 v36, v241
	v_cvt_f32_f16_sdwa v37, v241 dst_sel:DWORD dst_unused:UNUSED_PAD src0_sel:WORD_1
	s_waitcnt vmcnt(14)
	v_cvt_f32_f16_e32 v50, v244
	v_cvt_f32_f16_sdwa v51, v244 dst_sel:DWORD dst_unused:UNUSED_PAD src0_sel:WORD_1
	v_cvt_f32_f16_e32 v40, v245
	v_cvt_f32_f16_sdwa v41, v245 dst_sel:DWORD dst_unused:UNUSED_PAD src0_sel:WORD_1
	v_cvt_f32_f16_e32 v48, v242
	v_cvt_f32_f16_sdwa v49, v242 dst_sel:DWORD dst_unused:UNUSED_PAD src0_sel:WORD_1
	v_cvt_f32_f16_e32 v38, v243
	v_cvt_f32_f16_sdwa v39, v243 dst_sel:DWORD dst_unused:UNUSED_PAD src0_sel:WORD_1
	v_cvt_f32_f16_e32 v52, v246
	v_cvt_f32_f16_sdwa v53, v246 dst_sel:DWORD dst_unused:UNUSED_PAD src0_sel:WORD_1
	v_cvt_f32_f16_e32 v42, v247
	v_cvt_f32_f16_sdwa v43, v247 dst_sel:DWORD dst_unused:UNUSED_PAD src0_sel:WORD_1
	v_pk_add_f32 v[30:31], v[30:31], v[46:47]
	v_pk_add_f32 v[32:33], v[32:33], v[36:37]
	v_pk_add_f32 v[22:23], v[22:23], v[50:51]
	v_pk_add_f32 v[24:25], v[24:25], v[40:41]
	v_pk_add_f32 v[26:27], v[26:27], v[48:49]
	v_pk_add_f32 v[28:29], v[28:29], v[38:39]
	v_pk_add_f32 v[36:37], v[18:19], v[52:53]
	v_pk_add_f32 v[38:39], v[20:21], v[42:43]
	v_pk_mul_f32 v[20:21], v[30:31], v[30:31]
	v_pk_mul_f32 v[40:41], v[32:33], v[32:33]
	v_cvt_pk_f16_f32 v18, v30, v31
	v_cvt_pk_f16_f32 v19, v32, v33
	v_pk_mul_f32 v[30:31], v[22:23], v[22:23]
	v_pk_mul_f32 v[32:33], v[24:25], v[24:25]
	v_pk_mul_f32 v[42:43], v[26:27], v[26:27]
	v_pk_mul_f32 v[48:49], v[36:37], v[36:37]
	v_add_f32_e32 v32, v32, v33
	v_add_f32_e32 v30, v30, v31
	v_add_f32_e32 v40, v40, v41
	v_add_f32_e32 v20, v20, v21
	v_pk_mul_f32 v[46:47], v[28:29], v[28:29]
	v_pk_mul_f32 v[50:51], v[38:39], v[38:39]
	v_add_f32_e32 v31, v48, v49
	v_add_f32_e32 v21, v42, v43
	v_add_f32_e32 v30, v30, v32
	v_add_f32_e32 v20, v20, v40
	v_add_f32_e32 v33, v50, v51
	v_add_f32_e32 v41, v46, v47
	v_add_f32_e32 v30, v31, v30
	v_add_f32_e32 v20, v21, v20
	v_add_f32_e32 v21, v33, v30
	v_add_f32_e32 v20, v41, v20
	v_add_f32_e32 v30, v20, v21
	ds_bpermute_b32 v31, v156, v30
	v_cvt_pk_f16_f32 v20, v26, v27
	v_cvt_pk_f16_f32 v21, v28, v29
	global_store_dwordx4 v[44:45], v[18:21], off sc1
	s_waitcnt lgkmcnt(0)
	s_nop 0
	v_add_f32_e32 v18, v30, v31
	ds_bpermute_b32 v19, v116, v18
	v_cvt_pk_f16_f32 v20, v22, v23
	v_cvt_pk_f16_f32 v21, v24, v25
	v_cvt_pk_f16_f32 v22, v36, v37
	v_cvt_pk_f16_f32 v23, v38, v39
	global_store_dwordx4 v[44:45], v[20:23], off offset:256 sc1
	s_and_saveexec_b64 s[2:3], vcc
	s_cbranch_execz .LBB0_417
	v_lshl_add_u64 v[20:21], v[34:35], 2, s[18:19]
	s_waitcnt lgkmcnt(0)
	v_add_f32_e32 v18, v18, v19
	global_atomic_add_f32 v[20:21], v18, off
.LBB0_417:
	s_or_b64 exec, exec, s[2:3]
	v_add_u32_e32 v18, 0xb0, v148
	s_waitcnt lgkmcnt(0)
	v_ashrrev_i32_e32 v19, 31, v18
	v_lshlrev_b64 v[20:21], 11, v[18:19]
	v_lshl_add_u64 v[20:21], s[90:91], 0, v[20:21]
	v_lshl_add_u64 v[28:29], v[146:147], 1, v[20:21]
	s_waitcnt vmcnt(15)
	v_cvt_f32_f16_e32 v30, v248
	v_cvt_f32_f16_sdwa v31, v248 dst_sel:DWORD dst_unused:UNUSED_PAD src0_sel:WORD_1
	v_cvt_f32_f16_e32 v20, v249
	v_cvt_f32_f16_sdwa v21, v249 dst_sel:DWORD dst_unused:UNUSED_PAD src0_sel:WORD_1
	s_waitcnt vmcnt(14)
	v_cvt_f32_f16_e32 v34, v252
	v_cvt_f32_f16_sdwa v35, v252 dst_sel:DWORD dst_unused:UNUSED_PAD src0_sel:WORD_1
	v_cvt_f32_f16_e32 v24, v253
	v_cvt_f32_f16_sdwa v25, v253 dst_sel:DWORD dst_unused:UNUSED_PAD src0_sel:WORD_1
	v_cvt_f32_f16_e32 v32, v250
	v_cvt_f32_f16_sdwa v33, v250 dst_sel:DWORD dst_unused:UNUSED_PAD src0_sel:WORD_1
	v_cvt_f32_f16_e32 v22, v251
	v_cvt_f32_f16_sdwa v23, v251 dst_sel:DWORD dst_unused:UNUSED_PAD src0_sel:WORD_1
	v_cvt_f32_f16_e32 v36, v254
	v_cvt_f32_f16_sdwa v37, v254 dst_sel:DWORD dst_unused:UNUSED_PAD src0_sel:WORD_1
	v_cvt_f32_f16_e32 v26, v255
	v_cvt_f32_f16_sdwa v27, v255 dst_sel:DWORD dst_unused:UNUSED_PAD src0_sel:WORD_1
	v_pk_add_f32 v[14:15], v[14:15], v[30:31]
	v_pk_add_f32 v[16:17], v[16:17], v[20:21]
	v_pk_add_f32 v[6:7], v[6:7], v[34:35]
	v_pk_add_f32 v[8:9], v[8:9], v[24:25]
	v_pk_add_f32 v[10:11], v[10:11], v[32:33]
	v_pk_add_f32 v[12:13], v[12:13], v[22:23]
	v_pk_add_f32 v[20:21], v[2:3], v[36:37]
	v_pk_add_f32 v[22:23], v[4:5], v[26:27]
	v_pk_mul_f32 v[4:5], v[14:15], v[14:15]
	v_pk_mul_f32 v[24:25], v[16:17], v[16:17]
	v_cvt_pk_f16_f32 v2, v14, v15
	v_cvt_pk_f16_f32 v3, v16, v17
	v_pk_mul_f32 v[14:15], v[6:7], v[6:7]
	v_pk_mul_f32 v[16:17], v[8:9], v[8:9]
	v_pk_mul_f32 v[26:27], v[10:11], v[10:11]
	v_pk_mul_f32 v[32:33], v[20:21], v[20:21]
	v_add_f32_e32 v16, v16, v17
	v_add_f32_e32 v14, v14, v15
	v_add_f32_e32 v24, v24, v25
	v_add_f32_e32 v4, v4, v5
	v_pk_mul_f32 v[30:31], v[12:13], v[12:13]
	v_pk_mul_f32 v[34:35], v[22:23], v[22:23]
	v_add_f32_e32 v15, v32, v33
	v_add_f32_e32 v5, v26, v27
	v_add_f32_e32 v14, v14, v16
	v_add_f32_e32 v4, v4, v24
	v_add_f32_e32 v17, v34, v35
	v_add_f32_e32 v25, v30, v31
	v_add_f32_e32 v14, v15, v14
	v_add_f32_e32 v4, v5, v4
	v_add_f32_e32 v5, v17, v14
	v_add_f32_e32 v4, v25, v4
	v_add_f32_e32 v14, v4, v5
	ds_bpermute_b32 v15, v156, v14
	v_cvt_pk_f16_f32 v4, v10, v11
	v_cvt_pk_f16_f32 v5, v12, v13
	global_store_dwordx4 v[28:29], v[2:5], off sc1
	s_waitcnt lgkmcnt(0)
	s_nop 0
	v_add_f32_e32 v2, v14, v15
	ds_bpermute_b32 v3, v116, v2
	v_cvt_pk_f16_f32 v4, v6, v7
	v_cvt_pk_f16_f32 v5, v8, v9
	v_cvt_pk_f16_f32 v6, v20, v21
	v_cvt_pk_f16_f32 v7, v22, v23
	global_store_dwordx4 v[28:29], v[4:7], off offset:256 sc1
	s_and_saveexec_b64 s[2:3], vcc
	s_cbranch_execz .LBB0_419
	v_lshl_add_u64 v[4:5], v[18:19], 2, s[18:19]
	s_waitcnt lgkmcnt(0)
	v_add_f32_e32 v2, v2, v3
	global_atomic_add_f32 v[4:5], v2, off

; __device__ __forceinline__ unsigned pkh(float lo, float hi) { f32x2 v = {lo, hi}; h16x2 h = __builtin_convertvector(v, h16x2); return __builtin_bit_cast(unsigned, h); }
; __device__ __forceinline__ unsigned pk8(float a, float b, float c, float d) { int w = __builtin_amdgcn_cvt_pk_fp8_f32(a, b, 0, false); w = __builtin_amdgcn_cvt_pk_fp8_f32(c, d, w, true); return (unsigned)w; }
;     __device__ __forceinline__ void operator()(f32x4 (&acc)[2][2][4][2], const Unit& u, const Order& S, int wr, int wc, int fr_, int fq_, LAS unsigned char*, int) const {
;     ...
;         for (int ai = 0; ai < 2; ++ai)
; #pragma unroll
;             for (int m = 0; m < 4; ++m) {
;                 const int row = row0 + ai * HALF + m * 16; const size_t off = (size_t)row * DM + col0;
;                 float sq = 0.f;
; #pragma unroll
;                 for (int bj = 0; bj < 2; ++bj) {
;                     const h16x8 bs = *(const h16x8*)(h16 + off + bj * HALF);
;                     f32x4 o0 = acc[ai][bj][m][0] * pre, o1 = acc[ai][bj][m][1] * pre;
; #pragma unroll
;                     for (int e = 0; e < 4; ++e) { o0[e] += (float)bs[e]; o1[e] += (float)bs[4 + e]; }
;                     if (out32) { if (!dry) { __builtin_nontemporal_store(o0, (f32x4*)(out32 + off + bj * HALF)); __builtin_nontemporal_store(o1, (f32x4*)(out32 + off + bj * HALF + 4)); } }
;                     else if (!dry) {
;                         sq += (o0[0] * o0[0] + o0[1] * o0[1]) + (o0[2] * o0[2] + o0[3] * o0[3]) + (o1[0] * o1[0] + o1[1] * o1[1]) + (o1[2] * o1[2] + o1[3] * o1[3]);
;                         u32x4 w; w.x = pkh(o0[0], o0[1]); w.y = pkh(o0[2], o0[3]); w.z = pkh(o1[0], o1[1]); w.w = pkh(o1[2], o1[3]);
;                         *(u32x4*)(h16 + off + bj * HALF) = w;
;                         if (h8) { u32x2 q; q.x = pk8(o0[0] * F8_SA, o0[1] * F8_SA, o0[2] * F8_SA, o0[3] * F8_SA); q.y = pk8(o1[0] * F8_SA, o1[1] * F8_SA, o1[2] * F8_SA, o1[3] * F8_SA); *(u32x2*)(h8 + off + bj * HALF) = q; } }
;                 }
;                 if (!out32 && !dry) { sq += __shfl_xor(sq, 16); sq += __shfl_xor(sq, 32); if (fq == 0) atomicAdd(ss_out + row, sq); }
.LBB0_670:
	s_lshl_b32 s2, s45, 8
	v_mov_b32_e32 v146, v150
	v_mov_b32_e32 v170, v1
	s_add_i32 s2, s2, s36
	v_mov_b32_e32 v164, 0
	v_add_u32_e32 v148, s2, v146
	s_lshl_b32 s2, s44, 8
	s_or_b32 s2, s2, s37
	v_lshl_add_u32 v146, v170, 3, s2
	v_ashrrev_i32_e32 v149, 31, v148
	v_ashrrev_i32_e32 v147, 31, v146
	v_lshlrev_b64 v[156:157], 10, v[148:149]
	v_lshl_add_u64 v[160:161], v[156:157], 0, v[146:147]
	v_lshl_add_u64 v[162:163], v[160:161], 1, s[90:91]
	global_load_dwordx4 v[156:159], v[162:163], off
	s_mov_b32 s99, 0
	global_load_dwordx4 v[172:175], v[162:163], off offset:256
	s_mov_b32 s98, 0x8000
	v_lshl_add_u64 v[252:253], s[98:99], 0, v[162:163]
	global_load_dwordx4 v[176:179], v[252:253], off
	global_load_dwordx4 v[180:183], v[252:253], off offset:256
	s_mov_b32 s98, 0x10000
	v_lshl_add_u64 v[252:253], s[98:99], 0, v[162:163]
	global_load_dwordx4 v[184:187], v[252:253], off
	global_load_dwordx4 v[188:191], v[252:253], off offset:256
	s_mov_b32 s98, 0x18000
	v_lshl_add_u64 v[252:253], s[98:99], 0, v[162:163]
	global_load_dwordx4 v[192:195], v[252:253], off
	global_load_dwordx4 v[196:199], v[252:253], off offset:256
	s_mov_b32 s98, 0x40000
	v_lshl_add_u64 v[252:253], s[98:99], 0, v[162:163]
	global_load_dwordx4 v[200:203], v[252:253], off
	global_load_dwordx4 v[208:211], v[252:253], off offset:256
	s_mov_b32 s98, 0x48000
	v_lshl_add_u64 v[252:253], s[98:99], 0, v[162:163]
	global_load_dwordx4 v[212:215], v[252:253], off
	global_load_dwordx4 v[216:219], v[252:253], off offset:256
	s_mov_b32 s98, 0x50000
	v_lshl_add_u64 v[252:253], s[98:99], 0, v[162:163]
	global_load_dwordx4 v[240:243], v[252:253], off
	global_load_dwordx4 v[244:247], v[252:253], off offset:256
	s_mov_b32 s98, 0x58000
	v_lshl_add_u64 v[252:253], s[98:99], 0, v[162:163]
	global_load_dwordx4 v[248:251], v[252:253], off
	global_load_dwordx4 v[252:255], v[252:253], off offset:256
	v_mov_b32_e32 v165, 0
	v_lshl_add_u64 v[160:161], s[10:11], 0, v[160:161]
	v_cmp_eq_u32_e32 vcc, 0, v170
	s_waitcnt vmcnt(15)
	v_cvt_f32_f16_e32 v166, v156
	v_cvt_f32_f16_sdwa v167, v156 dst_sel:DWORD dst_unused:UNUSED_PAD src0_sel:WORD_1
	v_cvt_f32_f16_e32 v168, v158
	v_cvt_f32_f16_sdwa v169, v158 dst_sel:DWORD dst_unused:UNUSED_PAD src0_sel:WORD_1
	v_cvt_f32_f16_e32 v156, v157
	v_cvt_f32_f16_sdwa v157, v157 dst_sel:DWORD dst_unused:UNUSED_PAD src0_sel:WORD_1
	v_cvt_f32_f16_e32 v158, v159
	v_cvt_f32_f16_sdwa v159, v159 dst_sel:DWORD dst_unused:UNUSED_PAD src0_sel:WORD_1
	v_pk_add_f32 v[166:167], v[126:127], v[166:167]
	v_pk_add_f32 v[168:169], v[122:123], v[168:169]
	v_pk_add_f32 v[128:129], v[128:129], v[156:157]
	v_pk_add_f32 v[156:157], v[124:125], v[158:159]
	v_mul_f32_e32 v124, 0x41000000, v166
	v_mul_f32_e32 v125, 0x41000000, v167
	v_mul_f32_e32 v158, 0x41000000, v168
	v_mul_f32_e32 v159, 0x41000000, v169
	v_cvt_pk_fp8_f32 v164, v124, v125
	v_cvt_pk_fp8_f32 v165, v158, v159
	v_mul_f32_e32 v126, 0x41000000, v128
	v_mul_f32_e32 v127, 0x41000000, v129
	v_mul_f32_e32 v124, 0x41000000, v156
	v_mul_f32_e32 v125, 0x41000000, v157
	v_cvt_pk_fp8_f32 v164, v126, v127 op_sel:[0,0,1]
	v_cvt_pk_fp8_f32 v165, v124, v125 op_sel:[0,0,1]
	v_cvt_pk_f16_f32 v122, v166, v167
	v_cvt_pk_f16_f32 v123, v128, v129
	v_cvt_pk_f16_f32 v124, v168, v169
	v_cvt_pk_f16_f32 v125, v156, v157
	global_store_dwordx4 v[162:163], v[122:125], off sc1
	global_store_dwordx2 v[160:161], v[164:165], off
	s_nop 0
	v_and_b32_e32 v123, 64, v155
	v_xor_b32_e32 v122, 16, v155
	v_add_u32_e32 v123, 64, v123
	v_xor_b32_e32 v164, 32, v155
	v_cmp_lt_i32_e64 s[2:3], v122, v123
	v_pk_mul_f32 v[128:129], v[128:129], v[128:129]
	v_pk_mul_f32 v[156:157], v[156:157], v[156:157]
	v_cndmask_b32_e64 v122, v155, v122, s[2:3]
	v_cmp_lt_i32_e64 s[2:3], v164, v123
	v_add_f32_e32 v128, v128, v129
	v_add_f32_e32 v156, v156, v157
	v_cndmask_b32_e64 v123, v155, v164, s[2:3]
	v_pk_mul_f32 v[164:165], v[166:167], v[166:167]
	v_pk_mul_f32 v[166:167], v[168:169], v[168:169]
	v_add_f32_e32 v129, v164, v165
	v_add_f32_e32 v164, v166, v167
	v_add_f32_e32 v128, v129, v128
	v_add_f32_e32 v128, v164, v128
	v_add_f32_e32 v166, v156, v128
	v_lshlrev_b32_e32 v122, 2, v122
	v_mov_b32_e32 v158, 0
	v_mov_b32_e32 v159, 0
	s_waitcnt vmcnt(16)
	v_cvt_f32_f16_e32 v128, v172
	v_cvt_f32_f16_sdwa v129, v172 dst_sel:DWORD dst_unused:UNUSED_PAD src0_sel:WORD_1
	v_cvt_f32_f16_e32 v156, v174
	v_cvt_f32_f16_sdwa v157, v174 dst_sel:DWORD dst_unused:UNUSED_PAD src0_sel:WORD_1
	v_cvt_f32_f16_e32 v124, v173
	v_cvt_f32_f16_sdwa v125, v173 dst_sel:DWORD dst_unused:UNUSED_PAD src0_sel:WORD_1
	v_cvt_f32_f16_e32 v126, v175
	v_cvt_f32_f16_sdwa v127, v175 dst_sel:DWORD dst_unused:UNUSED_PAD src0_sel:WORD_1
	v_pk_add_f32 v[128:129], v[118:119], v[128:129]
	v_pk_add_f32 v[156:157], v[114:115], v[156:157]
	v_pk_add_f32 v[114:115], v[120:121], v[124:125]
	v_pk_add_f32 v[124:125], v[116:117], v[126:127]
	v_pk_mul_f32 v[116:117], v[128:129], v[128:129]
	v_pk_mul_f32 v[120:121], v[114:115], v[114:115]
	v_pk_mul_f32 v[126:127], v[156:157], v[156:157]
	v_add_f32_e32 v120, v120, v121
	v_add_f32_e32 v116, v116, v117
	v_pk_mul_f32 v[164:165], v[124:125], v[124:125]
	v_add_f32_e32 v117, v126, v127
	v_add_f32_e32 v116, v116, v120
	v_add_f32_e32 v121, v164, v165
	v_add_f32_e32 v116, v117, v116
	v_add_f32_e32 v116, v121, v116
	v_add_f32_e32 v116, v166, v116
	v_cvt_pk_f16_f32 v118, v128, v129
	v_mul_f32_e32 v128, 0x41000000, v128
	v_mul_f32_e32 v129, 0x41000000, v129
	ds_bpermute_b32 v117, v122, v116
	v_cvt_pk_fp8_f32 v158, v128, v129
	v_mul_f32_e32 v167, 0x41000000, v156
	v_mul_f32_e32 v168, 0x41000000, v157
	v_cvt_pk_f16_f32 v119, v114, v115
	v_mul_f32_e32 v114, 0x41000000, v114
	v_mul_f32_e32 v115, 0x41000000, v115
	v_cvt_pk_fp8_f32 v159, v167, v168
	v_cvt_pk_fp8_f32 v158, v114, v115 op_sel:[0,0,1]
	s_waitcnt lgkmcnt(0)
	v_add_f32_e32 v114, v116, v117
	v_lshlrev_b32_e32 v116, 2, v123
	ds_bpermute_b32 v115, v116, v114
	v_mul_f32_e32 v120, 0x41000000, v124
	v_mul_f32_e32 v121, 0x41000000, v125
	v_cvt_pk_fp8_f32 v159, v120, v121 op_sel:[0,0,1]
	v_cvt_pk_f16_f32 v120, v156, v157
	v_cvt_pk_f16_f32 v121, v124, v125
	global_store_dwordx4 v[162:163], v[118:121], off offset:256 sc1
	global_store_dwordx2 v[160:161], v[158:159], off offset:128
	s_and_saveexec_b64 s[2:3], vcc
	s_cbranch_execz .LBB0_672
	v_lshl_add_u64 v[118:119], v[148:149], 2, s[4:5]
	s_waitcnt lgkmcnt(0)
	v_add_f32_e32 v114, v114, v115
	global_atomic_add_f32 v[118:119], v114, off
; __device__ __forceinline__ unsigned pkh(float lo, float hi) { f32x2 v = {lo, hi}; h16x2 h = __builtin_convertvector(v, h16x2); return __builtin_bit_cast(unsigned, h); }
; __device__ __forceinline__ unsigned pk8(float a, float b, float c, float d) { int w = __builtin_amdgcn_cvt_pk_fp8_f32(a, b, 0, false); w = __builtin_amdgcn_cvt_pk_fp8_f32(c, d, w, true); return (unsigned)w; }
;     __device__ __forceinline__ void operator()(f32x4 (&acc)[2][2][4][2], const Unit& u, const Order& S, int wr, int wc, int fr_, int fq_, LAS unsigned char*, int) const {
;     ...
;             for (int m = 0; m < 4; ++m) {
;                 const int row = row0 + ai * HALF + m * 16; const size_t off = (size_t)row * DM + col0;
;                 float sq = 0.f;
; #pragma unroll
;                 for (int bj = 0; bj < 2; ++bj) {
;                     const h16x8 bs = *(const h16x8*)(h16 + off + bj * HALF);
;                     f32x4 o0 = acc[ai][bj][m][0] * pre, o1 = acc[ai][bj][m][1] * pre;
; #pragma unroll
;                     for (int e = 0; e < 4; ++e) { o0[e] += (float)bs[e]; o1[e] += (float)bs[4 + e]; }
;                     if (out32) { if (!dry) { __builtin_nontemporal_store(o0, (f32x4*)(out32 + off + bj * HALF)); __builtin_nontemporal_store(o1, (f32x4*)(out32 + off + bj * HALF + 4)); } }
;                     else if (!dry) {
;                         sq += (o0[0] * o0[0] + o0[1] * o0[1]) + (o0[2] * o0[2] + o0[3] * o0[3]) + (o1[0] * o1[0] + o1[1] * o1[1]) + (o1[2] * o1[2] + o1[3] * o1[3]);
;                         u32x4 w; w.x = pkh(o0[0], o0[1]); w.y = pkh(o0[2], o0[3]); w.z = pkh(o1[0], o1[1]); w.w = pkh(o1[2], o1[3]);
;                         *(u32x4*)(h16 + off + bj * HALF) = w;
;                         if (h8) { u32x2 q; q.x = pk8(o0[0] * F8_SA, o0[1] * F8_SA, o0[2] * F8_SA, o0[3] * F8_SA); q.y = pk8(o1[0] * F8_SA, o1[1] * F8_SA, o1[2] * F8_SA, o1[3] * F8_SA); *(u32x2*)(h8 + off + bj * HALF) = q; } }
;                 }
;                 if (!out32 && !dry) { sq += __shfl_xor(sq, 16); sq += __shfl_xor(sq, 32); if (fq == 0) atomicAdd(ss_out + row, sq); }
.LBB0_672:
	s_or_b64 exec, exec, s[2:3]
	v_add_u32_e32 v114, 16, v148
	s_waitcnt lgkmcnt(0)
	v_ashrrev_i32_e32 v115, 31, v114
	v_lshlrev_b64 v[118:119], 10, v[114:115]
	v_lshl_add_u64 v[124:125], v[118:119], 0, v[146:147]
	v_lshl_add_u64 v[126:127], v[124:125], 1, s[90:91]
	v_mov_b32_e32 v128, 0
	v_mov_b32_e32 v129, 0
	v_lshl_add_u64 v[124:125], s[10:11], 0, v[124:125]
	s_waitcnt vmcnt(17)
	v_cvt_f32_f16_e32 v156, v176
	v_cvt_f32_f16_sdwa v157, v176 dst_sel:DWORD dst_unused:UNUSED_PAD src0_sel:WORD_1
	v_cvt_f32_f16_e32 v158, v178
	v_cvt_f32_f16_sdwa v159, v178 dst_sel:DWORD dst_unused:UNUSED_PAD src0_sel:WORD_1
	v_cvt_f32_f16_e32 v118, v177
	v_cvt_f32_f16_sdwa v119, v177 dst_sel:DWORD dst_unused:UNUSED_PAD src0_sel:WORD_1
	v_cvt_f32_f16_e32 v120, v179
	v_cvt_f32_f16_sdwa v121, v179 dst_sel:DWORD dst_unused:UNUSED_PAD src0_sel:WORD_1
	v_pk_add_f32 v[110:111], v[110:111], v[156:157]
	v_pk_add_f32 v[156:157], v[106:107], v[158:159]
	v_pk_add_f32 v[112:113], v[112:113], v[118:119]
	v_pk_add_f32 v[118:119], v[108:109], v[120:121]
	v_mul_f32_e32 v108, 0x41000000, v110
	v_mul_f32_e32 v109, 0x41000000, v111
	v_mul_f32_e32 v121, 0x41000000, v156
	v_mul_f32_e32 v123, 0x41000000, v157
	v_cvt_pk_fp8_f32 v128, v108, v109
	v_cvt_pk_fp8_f32 v129, v121, v123
	v_mul_f32_e32 v117, 0x41000000, v112
	v_mul_f32_e32 v120, 0x41000000, v113
	v_mul_f32_e32 v108, 0x41000000, v118
	v_mul_f32_e32 v109, 0x41000000, v119
	v_cvt_pk_fp8_f32 v128, v117, v120 op_sel:[0,0,1]
	v_cvt_pk_fp8_f32 v129, v108, v109 op_sel:[0,0,1]
	v_cvt_pk_f16_f32 v106, v110, v111
	v_cvt_pk_f16_f32 v107, v112, v113
	v_cvt_pk_f16_f32 v108, v156, v157
	v_cvt_pk_f16_f32 v109, v118, v119
	global_store_dwordx4 v[126:127], v[106:109], off sc1
	global_store_dwordx2 v[124:125], v[128:129], off
	v_pk_mul_f32 v[110:111], v[110:111], v[110:111]
	v_pk_mul_f32 v[112:113], v[112:113], v[112:113]
	v_pk_mul_f32 v[128:129], v[156:157], v[156:157]
	v_add_f32_e32 v112, v112, v113
	v_add_f32_e32 v110, v110, v111
	v_pk_mul_f32 v[118:119], v[118:119], v[118:119]
	v_add_f32_e32 v111, v128, v129
	v_add_f32_e32 v110, v110, v112
	v_add_f32_e32 v113, v118, v119
	v_add_f32_e32 v110, v111, v110
	v_add_f32_e32 v117, v113, v110
	v_mov_b32_e32 v120, 0
	v_mov_b32_e32 v121, 0
	s_waitcnt vmcnt(18)
	v_cvt_f32_f16_e32 v110, v180
	v_cvt_f32_f16_sdwa v111, v180 dst_sel:DWORD dst_unused:UNUSED_PAD src0_sel:WORD_1
	v_cvt_f32_f16_e32 v112, v182
	v_cvt_f32_f16_sdwa v113, v182 dst_sel:DWORD dst_unused:UNUSED_PAD src0_sel:WORD_1
	v_cvt_f32_f16_e32 v106, v181
	v_cvt_f32_f16_sdwa v107, v181 dst_sel:DWORD dst_unused:UNUSED_PAD src0_sel:WORD_1
	v_cvt_f32_f16_e32 v108, v183
	v_cvt_f32_f16_sdwa v109, v183 dst_sel:DWORD dst_unused:UNUSED_PAD src0_sel:WORD_1
	v_pk_add_f32 v[102:103], v[102:103], v[110:111]
	v_pk_add_f32 v[110:111], v[98:99], v[112:113]
	v_pk_add_f32 v[98:99], v[104:105], v[106:107]
	v_pk_add_f32 v[104:105], v[100:101], v[108:109]
	v_pk_mul_f32 v[106:107], v[102:103], v[102:103]
	v_pk_mul_f32 v[108:109], v[98:99], v[98:99]
	v_pk_mul_f32 v[112:113], v[110:111], v[110:111]
	v_cvt_pk_f16_f32 v100, v102, v103
	v_mul_f32_e32 v102, 0x41000000, v102
	v_mul_f32_e32 v103, 0x41000000, v103
	v_add_f32_e32 v108, v108, v109
	v_add_f32_e32 v106, v106, v107
	v_pk_mul_f32 v[118:119], v[104:105], v[104:105]
	v_add_f32_e32 v107, v112, v113
	v_cvt_pk_fp8_f32 v120, v102, v103
	v_add_f32_e32 v102, v106, v108
	v_add_f32_e32 v109, v118, v119
	v_add_f32_e32 v102, v107, v102
	v_add_f32_e32 v102, v109, v102
	v_add_f32_e32 v102, v117, v102
	v_mul_f32_e32 v123, 0x41000000, v110
	v_mul_f32_e32 v128, 0x41000000, v111
	ds_bpermute_b32 v103, v122, v102
	v_cvt_pk_fp8_f32 v121, v123, v128
	v_cvt_pk_f16_f32 v101, v98, v99
	v_mul_f32_e32 v98, 0x41000000, v98
	v_mul_f32_e32 v99, 0x41000000, v99
	v_cvt_pk_fp8_f32 v120, v98, v99 op_sel:[0,0,1]
	v_mul_f32_e32 v98, 0x41000000, v104
	v_mul_f32_e32 v99, 0x41000000, v105
	v_cvt_pk_fp8_f32 v121, v98, v99 op_sel:[0,0,1]
	s_waitcnt lgkmcnt(0)
	v_add_f32_e32 v98, v102, v103
	ds_bpermute_b32 v99, v116, v98
	v_cvt_pk_f16_f32 v102, v110, v111
	v_cvt_pk_f16_f32 v103, v104, v105
	global_store_dwordx4 v[126:127], v[100:103], off offset:256 sc1
	global_store_dwordx2 v[124:125], v[120:121], off offset:128
	s_and_saveexec_b64 s[2:3], vcc
	s_cbranch_execz .LBB0_674
	v_lshl_add_u64 v[100:101], v[114:115], 2, s[4:5]
	s_waitcnt lgkmcnt(0)
	v_add_f32_e32 v98, v98, v99
	global_atomic_add_f32 v[100:101], v98, off
; __device__ __forceinline__ unsigned pkh(float lo, float hi) { f32x2 v = {lo, hi}; h16x2 h = __builtin_convertvector(v, h16x2); return __builtin_bit_cast(unsigned, h); }
; __device__ __forceinline__ unsigned pk8(float a, float b, float c, float d) { int w = __builtin_amdgcn_cvt_pk_fp8_f32(a, b, 0, false); w = __builtin_amdgcn_cvt_pk_fp8_f32(c, d, w, true); return (unsigned)w; }
;     __device__ __forceinline__ void operator()(f32x4 (&acc)[2][2][4][2], const Unit& u, const Order& S, int wr, int wc, int fr_, int fq_, LAS unsigned char*, int) const {
;     ...
;             for (int m = 0; m < 4; ++m) {
;                 const int row = row0 + ai * HALF + m * 16; const size_t off = (size_t)row * DM + col0;
;                 float sq = 0.f;
; #pragma unroll
;                 for (int bj = 0; bj < 2; ++bj) {
;                     const h16x8 bs = *(const h16x8*)(h16 + off + bj * HALF);
;                     f32x4 o0 = acc[ai][bj][m][0] * pre, o1 = acc[ai][bj][m][1] * pre;
; #pragma unroll
;                     for (int e = 0; e < 4; ++e) { o0[e] += (float)bs[e]; o1[e] += (float)bs[4 + e]; }
;                     if (out32) { if (!dry) { __builtin_nontemporal_store(o0, (f32x4*)(out32 + off + bj * HALF)); __builtin_nontemporal_store(o1, (f32x4*)(out32 + off + bj * HALF + 4)); } }
;                     else if (!dry) {
;                         sq += (o0[0] * o0[0] + o0[1] * o0[1]) + (o0[2] * o0[2] + o0[3] * o0[3]) + (o1[0] * o1[0] + o1[1] * o1[1]) + (o1[2] * o1[2] + o1[3] * o1[3]);
;                         u32x4 w; w.x = pkh(o0[0], o0[1]); w.y = pkh(o0[2], o0[3]); w.z = pkh(o1[0], o1[1]); w.w = pkh(o1[2], o1[3]);
;                         *(u32x4*)(h16 + off + bj * HALF) = w;
;                         if (h8) { u32x2 q; q.x = pk8(o0[0] * F8_SA, o0[1] * F8_SA, o0[2] * F8_SA, o0[3] * F8_SA); q.y = pk8(o1[0] * F8_SA, o1[1] * F8_SA, o1[2] * F8_SA, o1[3] * F8_SA); *(u32x2*)(h8 + off + bj * HALF) = q; } }
;                 }
;                 if (!out32 && !dry) { sq += __shfl_xor(sq, 16); sq += __shfl_xor(sq, 32); if (fq == 0) atomicAdd(ss_out + row, sq); }
.LBB0_674:
	s_or_b64 exec, exec, s[2:3]
	v_add_u32_e32 v98, 32, v148
	s_waitcnt lgkmcnt(0)
	v_ashrrev_i32_e32 v99, 31, v98
	v_lshlrev_b64 v[100:101], 10, v[98:99]
	v_lshl_add_u64 v[104:105], v[100:101], 0, v[146:147]
	v_lshl_add_u64 v[106:107], v[104:105], 1, s[90:91]
	v_mov_b32_e32 v108, 0
	v_mov_b32_e32 v109, 0
	v_lshl_add_u64 v[104:105], s[10:11], 0, v[104:105]
	s_waitcnt vmcnt(19)
	v_cvt_f32_f16_e32 v110, v184
	v_cvt_f32_f16_sdwa v111, v184 dst_sel:DWORD dst_unused:UNUSED_PAD src0_sel:WORD_1
	v_cvt_f32_f16_e32 v112, v186
	v_cvt_f32_f16_sdwa v113, v186 dst_sel:DWORD dst_unused:UNUSED_PAD src0_sel:WORD_1
	v_cvt_f32_f16_e32 v100, v185
	v_cvt_f32_f16_sdwa v101, v185 dst_sel:DWORD dst_unused:UNUSED_PAD src0_sel:WORD_1
	v_cvt_f32_f16_e32 v102, v187
	v_cvt_f32_f16_sdwa v103, v187 dst_sel:DWORD dst_unused:UNUSED_PAD src0_sel:WORD_1
	v_pk_add_f32 v[94:95], v[94:95], v[110:111]
	v_pk_add_f32 v[110:111], v[90:91], v[112:113]
	v_pk_add_f32 v[96:97], v[96:97], v[100:101]
	v_pk_add_f32 v[100:101], v[92:93], v[102:103]
	v_mul_f32_e32 v92, 0x41000000, v94
	v_mul_f32_e32 v93, 0x41000000, v95
	v_mul_f32_e32 v112, 0x41000000, v110
	v_mul_f32_e32 v113, 0x41000000, v111
	v_cvt_pk_fp8_f32 v108, v92, v93
	v_cvt_pk_fp8_f32 v109, v112, v113
	v_mul_f32_e32 v102, 0x41000000, v96
	v_mul_f32_e32 v103, 0x41000000, v97
	v_mul_f32_e32 v92, 0x41000000, v100
	v_mul_f32_e32 v93, 0x41000000, v101
	v_cvt_pk_fp8_f32 v108, v102, v103 op_sel:[0,0,1]
	v_cvt_pk_fp8_f32 v109, v92, v93 op_sel:[0,0,1]
	v_cvt_pk_f16_f32 v90, v94, v95
	v_cvt_pk_f16_f32 v91, v96, v97
	v_cvt_pk_f16_f32 v92, v110, v111
	v_cvt_pk_f16_f32 v93, v100, v101
	global_store_dwordx4 v[106:107], v[90:93], off sc1
	global_store_dwordx2 v[104:105], v[108:109], off
	v_pk_mul_f32 v[94:95], v[94:95], v[94:95]
	v_pk_mul_f32 v[96:97], v[96:97], v[96:97]
	v_pk_mul_f32 v[108:109], v[110:111], v[110:111]
	v_add_f32_e32 v96, v96, v97
	v_add_f32_e32 v94, v94, v95
	v_pk_mul_f32 v[100:101], v[100:101], v[100:101]
	v_add_f32_e32 v95, v108, v109
	v_add_f32_e32 v94, v94, v96
	v_add_f32_e32 v97, v100, v101
	v_add_f32_e32 v94, v95, v94
	v_add_f32_e32 v108, v97, v94
	v_mov_b32_e32 v102, 0
	v_mov_b32_e32 v103, 0
	s_waitcnt vmcnt(20)
	v_cvt_f32_f16_e32 v94, v188
	v_cvt_f32_f16_sdwa v95, v188 dst_sel:DWORD dst_unused:UNUSED_PAD src0_sel:WORD_1
	v_cvt_f32_f16_e32 v96, v190
	v_cvt_f32_f16_sdwa v97, v190 dst_sel:DWORD dst_unused:UNUSED_PAD src0_sel:WORD_1
	v_cvt_f32_f16_e32 v90, v189
	v_cvt_f32_f16_sdwa v91, v189 dst_sel:DWORD dst_unused:UNUSED_PAD src0_sel:WORD_1
	v_cvt_f32_f16_e32 v92, v191
	v_cvt_f32_f16_sdwa v93, v191 dst_sel:DWORD dst_unused:UNUSED_PAD src0_sel:WORD_1
	v_pk_add_f32 v[86:87], v[86:87], v[94:95]
	v_pk_add_f32 v[94:95], v[82:83], v[96:97]
	v_pk_add_f32 v[82:83], v[88:89], v[90:91]
	v_pk_add_f32 v[88:89], v[84:85], v[92:93]
	v_pk_mul_f32 v[90:91], v[86:87], v[86:87]
	v_pk_mul_f32 v[92:93], v[82:83], v[82:83]
	v_pk_mul_f32 v[96:97], v[94:95], v[94:95]
	v_cvt_pk_f16_f32 v84, v86, v87
	v_mul_f32_e32 v86, 0x41000000, v86
	v_mul_f32_e32 v87, 0x41000000, v87
	v_add_f32_e32 v92, v92, v93
	v_add_f32_e32 v90, v90, v91
	v_pk_mul_f32 v[100:101], v[88:89], v[88:89]
	v_add_f32_e32 v91, v96, v97
	v_cvt_pk_fp8_f32 v102, v86, v87
	v_add_f32_e32 v86, v90, v92
	v_add_f32_e32 v93, v100, v101
	v_add_f32_e32 v86, v91, v86
	v_add_f32_e32 v86, v93, v86
	v_add_f32_e32 v86, v108, v86
	v_mul_f32_e32 v109, 0x41000000, v94
	v_mul_f32_e32 v110, 0x41000000, v95
	ds_bpermute_b32 v87, v122, v86
	v_cvt_pk_fp8_f32 v103, v109, v110
	v_cvt_pk_f16_f32 v85, v82, v83
	v_mul_f32_e32 v82, 0x41000000, v82
	v_mul_f32_e32 v83, 0x41000000, v83
	v_cvt_pk_fp8_f32 v102, v82, v83 op_sel:[0,0,1]
	v_mul_f32_e32 v82, 0x41000000, v88
	v_mul_f32_e32 v83, 0x41000000, v89
	v_cvt_pk_fp8_f32 v103, v82, v83 op_sel:[0,0,1]
	s_waitcnt lgkmcnt(0)
	v_add_f32_e32 v82, v86, v87
	ds_bpermute_b32 v83, v116, v82
	v_cvt_pk_f16_f32 v86, v94, v95
	v_cvt_pk_f16_f32 v87, v88, v89
	global_store_dwordx4 v[106:107], v[84:87], off offset:256 sc1
	global_store_dwordx2 v[104:105], v[102:103], off offset:128
	s_and_saveexec_b64 s[2:3], vcc
	s_cbranch_execz .LBB0_676
	v_lshl_add_u64 v[84:85], v[98:99], 2, s[4:5]
	s_waitcnt lgkmcnt(0)
	v_add_f32_e32 v82, v82, v83
	global_atomic_add_f32 v[84:85], v82, off
.LBB0_676:
	s_or_b64 exec, exec, s[2:3]
	v_add_u32_e32 v82, 48, v148
	s_waitcnt lgkmcnt(0)
	v_ashrrev_i32_e32 v83, 31, v82
	v_lshlrev_b64 v[84:85], 10, v[82:83]
	v_lshl_add_u64 v[88:89], v[84:85], 0, v[146:147]
	v_lshl_add_u64 v[90:91], v[88:89], 1, s[90:91]
	v_mov_b32_e32 v92, 0
	v_mov_b32_e32 v93, 0
	v_lshl_add_u64 v[88:89], s[10:11], 0, v[88:89]
	s_waitcnt vmcnt(21)
	v_cvt_f32_f16_e32 v94, v192
	v_cvt_f32_f16_sdwa v95, v192 dst_sel:DWORD dst_unused:UNUSED_PAD src0_sel:WORD_1
	v_cvt_f32_f16_e32 v96, v194
	v_cvt_f32_f16_sdwa v97, v194 dst_sel:DWORD dst_unused:UNUSED_PAD src0_sel:WORD_1
	v_cvt_f32_f16_e32 v84, v193
	v_cvt_f32_f16_sdwa v85, v193 dst_sel:DWORD dst_unused:UNUSED_PAD src0_sel:WORD_1
	v_cvt_f32_f16_e32 v86, v195
	v_cvt_f32_f16_sdwa v87, v195 dst_sel:DWORD dst_unused:UNUSED_PAD src0_sel:WORD_1
	v_pk_add_f32 v[78:79], v[78:79], v[94:95]
	v_pk_add_f32 v[94:95], v[74:75], v[96:97]
	v_pk_add_f32 v[80:81], v[80:81], v[84:85]
	v_pk_add_f32 v[84:85], v[76:77], v[86:87]
	v_mul_f32_e32 v76, 0x41000000, v78
	v_mul_f32_e32 v77, 0x41000000, v79
	v_mul_f32_e32 v96, 0x41000000, v94
	v_mul_f32_e32 v97, 0x41000000, v95
	v_cvt_pk_fp8_f32 v92, v76, v77
	v_cvt_pk_fp8_f32 v93, v96, v97
	v_mul_f32_e32 v86, 0x41000000, v80
	v_mul_f32_e32 v87, 0x41000000, v81
	v_mul_f32_e32 v76, 0x41000000, v84
	v_mul_f32_e32 v77, 0x41000000, v85
	v_cvt_pk_fp8_f32 v92, v86, v87 op_sel:[0,0,1]
	v_cvt_pk_fp8_f32 v93, v76, v77 op_sel:[0,0,1]
	v_cvt_pk_f16_f32 v74, v78, v79
	v_cvt_pk_f16_f32 v75, v80, v81
	v_cvt_pk_f16_f32 v76, v94, v95
	v_cvt_pk_f16_f32 v77, v84, v85
	global_store_dwordx4 v[90:91], v[74:77], off sc1
	global_store_dwordx2 v[88:89], v[92:93], off
	v_pk_mul_f32 v[78:79], v[78:79], v[78:79]
	v_pk_mul_f32 v[80:81], v[80:81], v[80:81]
	v_pk_mul_f32 v[92:93], v[94:95], v[94:95]
	v_add_f32_e32 v80, v80, v81
	v_add_f32_e32 v78, v78, v79
	v_pk_mul_f32 v[84:85], v[84:85], v[84:85]
	v_add_f32_e32 v79, v92, v93
	v_add_f32_e32 v78, v78, v80
	v_add_f32_e32 v81, v84, v85
	v_add_f32_e32 v78, v79, v78
	v_add_f32_e32 v92, v81, v78
	v_mov_b32_e32 v86, 0
	v_mov_b32_e32 v87, 0
	s_waitcnt vmcnt(22)
; __device__ __forceinline__ unsigned pkh(float lo, float hi) { f32x2 v = {lo, hi}; h16x2 h = __builtin_convertvector(v, h16x2); return __builtin_bit_cast(unsigned, h); }
; __device__ __forceinline__ unsigned pk8(float a, float b, float c, float d) { int w = __builtin_amdgcn_cvt_pk_fp8_f32(a, b, 0, false); w = __builtin_amdgcn_cvt_pk_fp8_f32(c, d, w, true); return (unsigned)w; }
;     __device__ __forceinline__ void operator()(f32x4 (&acc)[2][2][4][2], const Unit& u, const Order& S, int wr, int wc, int fr_, int fq_, LAS unsigned char*, int) const {
;     ...
;             for (int m = 0; m < 4; ++m) {
;                 const int row = row0 + ai * HALF + m * 16; const size_t off = (size_t)row * DM + col0;
;                 float sq = 0.f;
; #pragma unroll
;                 for (int bj = 0; bj < 2; ++bj) {
;                     const h16x8 bs = *(const h16x8*)(h16 + off + bj * HALF);
;                     f32x4 o0 = acc[ai][bj][m][0] * pre, o1 = acc[ai][bj][m][1] * pre;
; #pragma unroll
;                     for (int e = 0; e < 4; ++e) { o0[e] += (float)bs[e]; o1[e] += (float)bs[4 + e]; }
;                     if (out32) { if (!dry) { __builtin_nontemporal_store(o0, (f32x4*)(out32 + off + bj * HALF)); __builtin_nontemporal_store(o1, (f32x4*)(out32 + off + bj * HALF + 4)); } }
;                     else if (!dry) {
;                         sq += (o0[0] * o0[0] + o0[1] * o0[1]) + (o0[2] * o0[2] + o0[3] * o0[3]) + (o1[0] * o1[0] + o1[1] * o1[1]) + (o1[2] * o1[2] + o1[3] * o1[3]);
;                         u32x4 w; w.x = pkh(o0[0], o0[1]); w.y = pkh(o0[2], o0[3]); w.z = pkh(o1[0], o1[1]); w.w = pkh(o1[2], o1[3]);
;                         *(u32x4*)(h16 + off + bj * HALF) = w;
;                         if (h8) { u32x2 q; q.x = pk8(o0[0] * F8_SA, o0[1] * F8_SA, o0[2] * F8_SA, o0[3] * F8_SA); q.y = pk8(o1[0] * F8_SA, o1[1] * F8_SA, o1[2] * F8_SA, o1[3] * F8_SA); *(u32x2*)(h8 + off + bj * HALF) = q; } }
;                 }
;                 if (!out32 && !dry) { sq += __shfl_xor(sq, 16); sq += __shfl_xor(sq, 32); if (fq == 0) atomicAdd(ss_out + row, sq); }
	v_cvt_f32_f16_e32 v78, v196
	v_cvt_f32_f16_sdwa v79, v196 dst_sel:DWORD dst_unused:UNUSED_PAD src0_sel:WORD_1
	v_cvt_f32_f16_e32 v80, v198
	v_cvt_f32_f16_sdwa v81, v198 dst_sel:DWORD dst_unused:UNUSED_PAD src0_sel:WORD_1
	v_cvt_f32_f16_e32 v74, v197
	v_cvt_f32_f16_sdwa v75, v197 dst_sel:DWORD dst_unused:UNUSED_PAD src0_sel:WORD_1
	v_cvt_f32_f16_e32 v76, v199
	v_cvt_f32_f16_sdwa v77, v199 dst_sel:DWORD dst_unused:UNUSED_PAD src0_sel:WORD_1
	v_pk_add_f32 v[70:71], v[70:71], v[78:79]
	v_pk_add_f32 v[78:79], v[66:67], v[80:81]
	v_pk_add_f32 v[66:67], v[72:73], v[74:75]
	v_pk_add_f32 v[72:73], v[68:69], v[76:77]
	v_pk_mul_f32 v[74:75], v[70:71], v[70:71]
	v_pk_mul_f32 v[76:77], v[66:67], v[66:67]
	v_pk_mul_f32 v[80:81], v[78:79], v[78:79]
	v_cvt_pk_f16_f32 v68, v70, v71
	v_mul_f32_e32 v70, 0x41000000, v70
	v_mul_f32_e32 v71, 0x41000000, v71
	v_add_f32_e32 v76, v76, v77
	v_add_f32_e32 v74, v74, v75
	v_pk_mul_f32 v[84:85], v[72:73], v[72:73]
	v_add_f32_e32 v75, v80, v81
	v_cvt_pk_fp8_f32 v86, v70, v71
	v_add_f32_e32 v70, v74, v76
	v_add_f32_e32 v77, v84, v85
	v_add_f32_e32 v70, v75, v70
	v_add_f32_e32 v70, v77, v70
	v_add_f32_e32 v70, v92, v70
	v_mul_f32_e32 v93, 0x41000000, v78
	v_mul_f32_e32 v94, 0x41000000, v79
	ds_bpermute_b32 v71, v122, v70
	v_cvt_pk_fp8_f32 v87, v93, v94
	v_cvt_pk_f16_f32 v69, v66, v67
	v_mul_f32_e32 v66, 0x41000000, v66
	v_mul_f32_e32 v67, 0x41000000, v67
	v_cvt_pk_fp8_f32 v86, v66, v67 op_sel:[0,0,1]
	v_mul_f32_e32 v66, 0x41000000, v72
	v_mul_f32_e32 v67, 0x41000000, v73
	v_cvt_pk_fp8_f32 v87, v66, v67 op_sel:[0,0,1]
	s_waitcnt lgkmcnt(0)
	v_add_f32_e32 v66, v70, v71
	ds_bpermute_b32 v67, v116, v66
	v_cvt_pk_f16_f32 v70, v78, v79
	v_cvt_pk_f16_f32 v71, v72, v73
	global_store_dwordx4 v[90:91], v[68:71], off offset:256 sc1
	global_store_dwordx2 v[88:89], v[86:87], off offset:128
	s_and_saveexec_b64 s[2:3], vcc
	s_cbranch_execz .LBB0_678
	v_lshl_add_u64 v[68:69], v[82:83], 2, s[4:5]
	s_waitcnt lgkmcnt(0)
	v_add_f32_e32 v66, v66, v67
	global_atomic_add_f32 v[68:69], v66, off
.LBB0_678:
	s_or_b64 exec, exec, s[2:3]
	v_add_u32_e32 v66, 0x80, v148
	s_waitcnt lgkmcnt(0)
	v_ashrrev_i32_e32 v67, 31, v66
	v_lshlrev_b64 v[68:69], 10, v[66:67]
	v_lshl_add_u64 v[72:73], v[68:69], 0, v[146:147]
	v_lshl_add_u64 v[74:75], v[72:73], 1, s[90:91]
	v_mov_b32_e32 v76, 0
	v_mov_b32_e32 v77, 0
	v_lshl_add_u64 v[72:73], s[10:11], 0, v[72:73]
	s_waitcnt vmcnt(23)
	v_cvt_f32_f16_e32 v78, v200
	v_cvt_f32_f16_sdwa v79, v200 dst_sel:DWORD dst_unused:UNUSED_PAD src0_sel:WORD_1
	v_cvt_f32_f16_e32 v80, v202
	v_cvt_f32_f16_sdwa v81, v202 dst_sel:DWORD dst_unused:UNUSED_PAD src0_sel:WORD_1
	v_cvt_f32_f16_e32 v68, v201
	v_cvt_f32_f16_sdwa v69, v201 dst_sel:DWORD dst_unused:UNUSED_PAD src0_sel:WORD_1
	v_cvt_f32_f16_e32 v70, v203
	v_cvt_f32_f16_sdwa v71, v203 dst_sel:DWORD dst_unused:UNUSED_PAD src0_sel:WORD_1
	v_pk_add_f32 v[62:63], v[62:63], v[78:79]
	v_pk_add_f32 v[78:79], v[58:59], v[80:81]
	v_pk_add_f32 v[64:65], v[64:65], v[68:69]
	v_pk_add_f32 v[68:69], v[60:61], v[70:71]
	v_mul_f32_e32 v60, 0x41000000, v62
	v_mul_f32_e32 v61, 0x41000000, v63
	v_mul_f32_e32 v80, 0x41000000, v78
	v_mul_f32_e32 v81, 0x41000000, v79
	v_cvt_pk_fp8_f32 v76, v60, v61
	v_cvt_pk_fp8_f32 v77, v80, v81
	v_mul_f32_e32 v70, 0x41000000, v64
	v_mul_f32_e32 v71, 0x41000000, v65
	v_mul_f32_e32 v60, 0x41000000, v68
	v_mul_f32_e32 v61, 0x41000000, v69
	v_cvt_pk_fp8_f32 v76, v70, v71 op_sel:[0,0,1]
	v_cvt_pk_fp8_f32 v77, v60, v61 op_sel:[0,0,1]
	v_cvt_pk_f16_f32 v58, v62, v63
	v_cvt_pk_f16_f32 v59, v64, v65
	v_cvt_pk_f16_f32 v60, v78, v79
	v_cvt_pk_f16_f32 v61, v68, v69
	global_store_dwordx4 v[74:75], v[58:61], off sc1
	global_store_dwordx2 v[72:73], v[76:77], off
	v_pk_mul_f32 v[62:63], v[62:63], v[62:63]
	v_pk_mul_f32 v[64:65], v[64:65], v[64:65]
	v_pk_mul_f32 v[76:77], v[78:79], v[78:79]
	v_add_f32_e32 v64, v64, v65
	v_add_f32_e32 v62, v62, v63
	v_pk_mul_f32 v[68:69], v[68:69], v[68:69]
	v_add_f32_e32 v63, v76, v77
	v_add_f32_e32 v62, v62, v64
	v_add_f32_e32 v65, v68, v69
	v_add_f32_e32 v62, v63, v62
	v_add_f32_e32 v76, v65, v62
	v_mov_b32_e32 v70, 0
	v_mov_b32_e32 v71, 0
	s_waitcnt vmcnt(24)
	v_cvt_f32_f16_e32 v62, v208
	v_cvt_f32_f16_sdwa v63, v208 dst_sel:DWORD dst_unused:UNUSED_PAD src0_sel:WORD_1
	v_cvt_f32_f16_e32 v64, v210
	v_cvt_f32_f16_sdwa v65, v210 dst_sel:DWORD dst_unused:UNUSED_PAD src0_sel:WORD_1
	v_cvt_f32_f16_e32 v58, v209
	v_cvt_f32_f16_sdwa v59, v209 dst_sel:DWORD dst_unused:UNUSED_PAD src0_sel:WORD_1
	v_cvt_f32_f16_e32 v60, v211
	v_cvt_f32_f16_sdwa v61, v211 dst_sel:DWORD dst_unused:UNUSED_PAD src0_sel:WORD_1
	v_pk_add_f32 v[54:55], v[54:55], v[62:63]
	v_pk_add_f32 v[62:63], v[50:51], v[64:65]
	v_pk_add_f32 v[50:51], v[56:57], v[58:59]
	v_pk_add_f32 v[56:57], v[52:53], v[60:61]
	v_pk_mul_f32 v[58:59], v[54:55], v[54:55]
	v_pk_mul_f32 v[60:61], v[50:51], v[50:51]
	v_pk_mul_f32 v[64:65], v[62:63], v[62:63]
	v_cvt_pk_f16_f32 v52, v54, v55
	v_mul_f32_e32 v54, 0x41000000, v54
	v_mul_f32_e32 v55, 0x41000000, v55
	v_add_f32_e32 v60, v60, v61
	v_add_f32_e32 v58, v58, v59
	v_pk_mul_f32 v[68:69], v[56:57], v[56:57]
	v_add_f32_e32 v59, v64, v65
	v_cvt_pk_fp8_f32 v70, v54, v55
	v_add_f32_e32 v54, v58, v60
	v_add_f32_e32 v61, v68, v69
	v_add_f32_e32 v54, v59, v54
	v_add_f32_e32 v54, v61, v54
	v_add_f32_e32 v54, v76, v54
	v_mul_f32_e32 v77, 0x41000000, v62
	v_mul_f32_e32 v78, 0x41000000, v63
	ds_bpermute_b32 v55, v122, v54
	v_cvt_pk_fp8_f32 v71, v77, v78
	v_cvt_pk_f16_f32 v53, v50, v51
	v_mul_f32_e32 v50, 0x41000000, v50
	v_mul_f32_e32 v51, 0x41000000, v51
	v_cvt_pk_fp8_f32 v70, v50, v51 op_sel:[0,0,1]
	v_mul_f32_e32 v50, 0x41000000, v56
	v_mul_f32_e32 v51, 0x41000000, v57
	v_cvt_pk_fp8_f32 v71, v50, v51 op_sel:[0,0,1]
	s_waitcnt lgkmcnt(0)
	v_add_f32_e32 v50, v54, v55
	ds_bpermute_b32 v51, v116, v50
	v_cvt_pk_f16_f32 v54, v62, v63
	v_cvt_pk_f16_f32 v55, v56, v57
	global_store_dwordx4 v[74:75], v[52:55], off offset:256 sc1
	global_store_dwordx2 v[72:73], v[70:71], off offset:128
	s_and_saveexec_b64 s[2:3], vcc
	s_cbranch_execz .LBB0_680
	v_lshl_add_u64 v[52:53], v[66:67], 2, s[4:5]
	s_waitcnt lgkmcnt(0)
	v_add_f32_e32 v50, v50, v51
	global_atomic_add_f32 v[52:53], v50, off
; __device__ __forceinline__ unsigned pkh(float lo, float hi) { f32x2 v = {lo, hi}; h16x2 h = __builtin_convertvector(v, h16x2); return __builtin_bit_cast(unsigned, h); }
; __device__ __forceinline__ unsigned pk8(float a, float b, float c, float d) { int w = __builtin_amdgcn_cvt_pk_fp8_f32(a, b, 0, false); w = __builtin_amdgcn_cvt_pk_fp8_f32(c, d, w, true); return (unsigned)w; }
;     __device__ __forceinline__ void operator()(f32x4 (&acc)[2][2][4][2], const Unit& u, const Order& S, int wr, int wc, int fr_, int fq_, LAS unsigned char*, int) const {
;     ...
;             for (int m = 0; m < 4; ++m) {
;                 const int row = row0 + ai * HALF + m * 16; const size_t off = (size_t)row * DM + col0;
;                 float sq = 0.f;
; #pragma unroll
;                 for (int bj = 0; bj < 2; ++bj) {
;                     const h16x8 bs = *(const h16x8*)(h16 + off + bj * HALF);
;                     f32x4 o0 = acc[ai][bj][m][0] * pre, o1 = acc[ai][bj][m][1] * pre;
; #pragma unroll
;                     for (int e = 0; e < 4; ++e) { o0[e] += (float)bs[e]; o1[e] += (float)bs[4 + e]; }
;                     if (out32) { if (!dry) { __builtin_nontemporal_store(o0, (f32x4*)(out32 + off + bj * HALF)); __builtin_nontemporal_store(o1, (f32x4*)(out32 + off + bj * HALF + 4)); } }
;                     else if (!dry) {
;                         sq += (o0[0] * o0[0] + o0[1] * o0[1]) + (o0[2] * o0[2] + o0[3] * o0[3]) + (o1[0] * o1[0] + o1[1] * o1[1]) + (o1[2] * o1[2] + o1[3] * o1[3]);
;                         u32x4 w; w.x = pkh(o0[0], o0[1]); w.y = pkh(o0[2], o0[3]); w.z = pkh(o1[0], o1[1]); w.w = pkh(o1[2], o1[3]);
;                         *(u32x4*)(h16 + off + bj * HALF) = w;
;                         if (h8) { u32x2 q; q.x = pk8(o0[0] * F8_SA, o0[1] * F8_SA, o0[2] * F8_SA, o0[3] * F8_SA); q.y = pk8(o1[0] * F8_SA, o1[1] * F8_SA, o1[2] * F8_SA, o1[3] * F8_SA); *(u32x2*)(h8 + off + bj * HALF) = q; } }
;                 }
;                 if (!out32 && !dry) { sq += __shfl_xor(sq, 16); sq += __shfl_xor(sq, 32); if (fq == 0) atomicAdd(ss_out + row, sq); }
.LBB0_680:
	s_or_b64 exec, exec, s[2:3]
	v_add_u32_e32 v50, 0x90, v148
	s_waitcnt lgkmcnt(0)
	v_ashrrev_i32_e32 v51, 31, v50
	v_lshlrev_b64 v[52:53], 10, v[50:51]
	v_lshl_add_u64 v[56:57], v[52:53], 0, v[146:147]
	v_lshl_add_u64 v[58:59], v[56:57], 1, s[90:91]
	v_mov_b32_e32 v60, 0
	v_mov_b32_e32 v61, 0
	v_lshl_add_u64 v[56:57], s[10:11], 0, v[56:57]
	s_waitcnt vmcnt(25)
	v_cvt_f32_f16_e32 v62, v212
	v_cvt_f32_f16_sdwa v63, v212 dst_sel:DWORD dst_unused:UNUSED_PAD src0_sel:WORD_1
	v_cvt_f32_f16_e32 v64, v214
	v_cvt_f32_f16_sdwa v65, v214 dst_sel:DWORD dst_unused:UNUSED_PAD src0_sel:WORD_1
	v_cvt_f32_f16_e32 v52, v213
	v_cvt_f32_f16_sdwa v53, v213 dst_sel:DWORD dst_unused:UNUSED_PAD src0_sel:WORD_1
	v_cvt_f32_f16_e32 v54, v215
	v_cvt_f32_f16_sdwa v55, v215 dst_sel:DWORD dst_unused:UNUSED_PAD src0_sel:WORD_1
	v_pk_add_f32 v[46:47], v[46:47], v[62:63]
	v_pk_add_f32 v[62:63], v[42:43], v[64:65]
	v_pk_add_f32 v[48:49], v[48:49], v[52:53]
	v_pk_add_f32 v[52:53], v[44:45], v[54:55]
	v_mul_f32_e32 v44, 0x41000000, v46
	v_mul_f32_e32 v45, 0x41000000, v47
	v_mul_f32_e32 v64, 0x41000000, v62
	v_mul_f32_e32 v65, 0x41000000, v63
	v_cvt_pk_fp8_f32 v60, v44, v45
	v_cvt_pk_fp8_f32 v61, v64, v65
	v_mul_f32_e32 v54, 0x41000000, v48
	v_mul_f32_e32 v55, 0x41000000, v49
	v_mul_f32_e32 v44, 0x41000000, v52
	v_mul_f32_e32 v45, 0x41000000, v53
	v_cvt_pk_fp8_f32 v60, v54, v55 op_sel:[0,0,1]
	v_cvt_pk_fp8_f32 v61, v44, v45 op_sel:[0,0,1]
	v_cvt_pk_f16_f32 v42, v46, v47
	v_cvt_pk_f16_f32 v43, v48, v49
	v_cvt_pk_f16_f32 v44, v62, v63
	v_cvt_pk_f16_f32 v45, v52, v53
	global_store_dwordx4 v[58:59], v[42:45], off sc1
	global_store_dwordx2 v[56:57], v[60:61], off
	v_pk_mul_f32 v[46:47], v[46:47], v[46:47]
	v_pk_mul_f32 v[48:49], v[48:49], v[48:49]
	v_pk_mul_f32 v[60:61], v[62:63], v[62:63]
	v_add_f32_e32 v48, v48, v49
	v_add_f32_e32 v46, v46, v47
	v_pk_mul_f32 v[52:53], v[52:53], v[52:53]
	v_add_f32_e32 v47, v60, v61
	v_add_f32_e32 v46, v46, v48
	v_add_f32_e32 v49, v52, v53
	v_add_f32_e32 v46, v47, v46
	v_add_f32_e32 v60, v49, v46
	v_mov_b32_e32 v54, 0
	v_mov_b32_e32 v55, 0
	s_waitcnt vmcnt(26)
	v_cvt_f32_f16_e32 v46, v216
	v_cvt_f32_f16_sdwa v47, v216 dst_sel:DWORD dst_unused:UNUSED_PAD src0_sel:WORD_1
	v_cvt_f32_f16_e32 v48, v218
	v_cvt_f32_f16_sdwa v49, v218 dst_sel:DWORD dst_unused:UNUSED_PAD src0_sel:WORD_1
	v_cvt_f32_f16_e32 v42, v217
	v_cvt_f32_f16_sdwa v43, v217 dst_sel:DWORD dst_unused:UNUSED_PAD src0_sel:WORD_1
	v_cvt_f32_f16_e32 v44, v219
	v_cvt_f32_f16_sdwa v45, v219 dst_sel:DWORD dst_unused:UNUSED_PAD src0_sel:WORD_1
	v_pk_add_f32 v[38:39], v[38:39], v[46:47]
	v_pk_add_f32 v[46:47], v[34:35], v[48:49]
	v_pk_add_f32 v[34:35], v[40:41], v[42:43]
	v_pk_add_f32 v[40:41], v[36:37], v[44:45]
	v_pk_mul_f32 v[42:43], v[38:39], v[38:39]
	v_pk_mul_f32 v[44:45], v[34:35], v[34:35]
	v_pk_mul_f32 v[48:49], v[46:47], v[46:47]
	v_cvt_pk_f16_f32 v36, v38, v39
	v_mul_f32_e32 v38, 0x41000000, v38
	v_mul_f32_e32 v39, 0x41000000, v39
	v_add_f32_e32 v44, v44, v45
	v_add_f32_e32 v42, v42, v43
	v_pk_mul_f32 v[52:53], v[40:41], v[40:41]
	v_add_f32_e32 v43, v48, v49
	v_cvt_pk_fp8_f32 v54, v38, v39
	v_add_f32_e32 v38, v42, v44
	v_add_f32_e32 v45, v52, v53
	v_add_f32_e32 v38, v43, v38
	v_add_f32_e32 v38, v45, v38
	v_add_f32_e32 v38, v60, v38
	v_mul_f32_e32 v61, 0x41000000, v46
	v_mul_f32_e32 v62, 0x41000000, v47
	ds_bpermute_b32 v39, v122, v38
	v_cvt_pk_fp8_f32 v55, v61, v62
	v_cvt_pk_f16_f32 v37, v34, v35
	v_mul_f32_e32 v34, 0x41000000, v34
	v_mul_f32_e32 v35, 0x41000000, v35
	v_cvt_pk_fp8_f32 v54, v34, v35 op_sel:[0,0,1]
	v_mul_f32_e32 v34, 0x41000000, v40
	v_mul_f32_e32 v35, 0x41000000, v41
	v_cvt_pk_fp8_f32 v55, v34, v35 op_sel:[0,0,1]
	s_waitcnt lgkmcnt(0)
	v_add_f32_e32 v34, v38, v39
	ds_bpermute_b32 v35, v116, v34
	v_cvt_pk_f16_f32 v38, v46, v47
	v_cvt_pk_f16_f32 v39, v40, v41
	global_store_dwordx4 v[58:59], v[36:39], off offset:256 sc1
	global_store_dwordx2 v[56:57], v[54:55], off offset:128
	s_and_saveexec_b64 s[2:3], vcc
	s_cbranch_execz .LBB0_682
	v_lshl_add_u64 v[36:37], v[50:51], 2, s[4:5]
	s_waitcnt lgkmcnt(0)
	v_add_f32_e32 v34, v34, v35
	global_atomic_add_f32 v[36:37], v34, off
.LBB0_682:
	s_or_b64 exec, exec, s[2:3]
	v_add_u32_e32 v34, 0xa0, v148
	s_waitcnt lgkmcnt(0)
	v_ashrrev_i32_e32 v35, 31, v34
	v_lshlrev_b64 v[36:37], 10, v[34:35]
	v_lshl_add_u64 v[40:41], v[36:37], 0, v[146:147]
	v_lshl_add_u64 v[42:43], v[40:41], 1, s[90:91]
	v_mov_b32_e32 v44, 0
	v_mov_b32_e32 v45, 0
	v_lshl_add_u64 v[40:41], s[10:11], 0, v[40:41]
	s_waitcnt vmcnt(27)
	v_cvt_f32_f16_e32 v46, v240
	v_cvt_f32_f16_sdwa v47, v240 dst_sel:DWORD dst_unused:UNUSED_PAD src0_sel:WORD_1
	v_cvt_f32_f16_e32 v48, v242
	v_cvt_f32_f16_sdwa v49, v242 dst_sel:DWORD dst_unused:UNUSED_PAD src0_sel:WORD_1
	v_cvt_f32_f16_e32 v36, v241
	v_cvt_f32_f16_sdwa v37, v241 dst_sel:DWORD dst_unused:UNUSED_PAD src0_sel:WORD_1
	v_cvt_f32_f16_e32 v38, v243
	v_cvt_f32_f16_sdwa v39, v243 dst_sel:DWORD dst_unused:UNUSED_PAD src0_sel:WORD_1
	v_pk_add_f32 v[30:31], v[30:31], v[46:47]
	v_pk_add_f32 v[46:47], v[26:27], v[48:49]
	v_pk_add_f32 v[32:33], v[32:33], v[36:37]
	v_pk_add_f32 v[36:37], v[28:29], v[38:39]
	v_mul_f32_e32 v28, 0x41000000, v30
	v_mul_f32_e32 v29, 0x41000000, v31
	v_mul_f32_e32 v48, 0x41000000, v46
	v_mul_f32_e32 v49, 0x41000000, v47
	v_cvt_pk_fp8_f32 v44, v28, v29
	v_cvt_pk_fp8_f32 v45, v48, v49
	v_mul_f32_e32 v38, 0x41000000, v32
	v_mul_f32_e32 v39, 0x41000000, v33
	v_mul_f32_e32 v28, 0x41000000, v36
	v_mul_f32_e32 v29, 0x41000000, v37
	v_cvt_pk_fp8_f32 v44, v38, v39 op_sel:[0,0,1]
	v_cvt_pk_fp8_f32 v45, v28, v29 op_sel:[0,0,1]
	v_cvt_pk_f16_f32 v26, v30, v31
	v_cvt_pk_f16_f32 v27, v32, v33
	v_cvt_pk_f16_f32 v28, v46, v47
	v_cvt_pk_f16_f32 v29, v36, v37
	global_store_dwordx4 v[42:43], v[26:29], off sc1
	global_store_dwordx2 v[40:41], v[44:45], off
	v_pk_mul_f32 v[30:31], v[30:31], v[30:31]
	v_pk_mul_f32 v[32:33], v[32:33], v[32:33]
	v_pk_mul_f32 v[44:45], v[46:47], v[46:47]
	v_add_f32_e32 v32, v32, v33
	v_add_f32_e32 v30, v30, v31
	v_pk_mul_f32 v[36:37], v[36:37], v[36:37]
	v_add_f32_e32 v31, v44, v45
	v_add_f32_e32 v30, v30, v32
	v_add_f32_e32 v33, v36, v37
	v_add_f32_e32 v30, v31, v30
	v_add_f32_e32 v44, v33, v30
	v_mov_b32_e32 v38, 0
	v_mov_b32_e32 v39, 0
	s_waitcnt vmcnt(28)
; __device__ __forceinline__ unsigned pkh(float lo, float hi) { f32x2 v = {lo, hi}; h16x2 h = __builtin_convertvector(v, h16x2); return __builtin_bit_cast(unsigned, h); }
; __device__ __forceinline__ unsigned pk8(float a, float b, float c, float d) { int w = __builtin_amdgcn_cvt_pk_fp8_f32(a, b, 0, false); w = __builtin_amdgcn_cvt_pk_fp8_f32(c, d, w, true); return (unsigned)w; }
;     __device__ __forceinline__ void operator()(f32x4 (&acc)[2][2][4][2], const Unit& u, const Order& S, int wr, int wc, int fr_, int fq_, LAS unsigned char*, int) const {
;     ...
;             for (int m = 0; m < 4; ++m) {
;                 const int row = row0 + ai * HALF + m * 16; const size_t off = (size_t)row * DM + col0;
;                 float sq = 0.f;
; #pragma unroll
;                 for (int bj = 0; bj < 2; ++bj) {
;                     const h16x8 bs = *(const h16x8*)(h16 + off + bj * HALF);
;                     f32x4 o0 = acc[ai][bj][m][0] * pre, o1 = acc[ai][bj][m][1] * pre;
; #pragma unroll
;                     for (int e = 0; e < 4; ++e) { o0[e] += (float)bs[e]; o1[e] += (float)bs[4 + e]; }
;                     if (out32) { if (!dry) { __builtin_nontemporal_store(o0, (f32x4*)(out32 + off + bj * HALF)); __builtin_nontemporal_store(o1, (f32x4*)(out32 + off + bj * HALF + 4)); } }
;                     else if (!dry) {
;                         sq += (o0[0] * o0[0] + o0[1] * o0[1]) + (o0[2] * o0[2] + o0[3] * o0[3]) + (o1[0] * o1[0] + o1[1] * o1[1]) + (o1[2] * o1[2] + o1[3] * o1[3]);
;                         u32x4 w; w.x = pkh(o0[0], o0[1]); w.y = pkh(o0[2], o0[3]); w.z = pkh(o1[0], o1[1]); w.w = pkh(o1[2], o1[3]);
;                         *(u32x4*)(h16 + off + bj * HALF) = w;
;                         if (h8) { u32x2 q; q.x = pk8(o0[0] * F8_SA, o0[1] * F8_SA, o0[2] * F8_SA, o0[3] * F8_SA); q.y = pk8(o1[0] * F8_SA, o1[1] * F8_SA, o1[2] * F8_SA, o1[3] * F8_SA); *(u32x2*)(h8 + off + bj * HALF) = q; } }
;                 }
;                 if (!out32 && !dry) { sq += __shfl_xor(sq, 16); sq += __shfl_xor(sq, 32); if (fq == 0) atomicAdd(ss_out + row, sq); }
	v_cvt_f32_f16_e32 v30, v244
	v_cvt_f32_f16_sdwa v31, v244 dst_sel:DWORD dst_unused:UNUSED_PAD src0_sel:WORD_1
	v_cvt_f32_f16_e32 v32, v246
	v_cvt_f32_f16_sdwa v33, v246 dst_sel:DWORD dst_unused:UNUSED_PAD src0_sel:WORD_1
	v_cvt_f32_f16_e32 v26, v245
	v_cvt_f32_f16_sdwa v27, v245 dst_sel:DWORD dst_unused:UNUSED_PAD src0_sel:WORD_1
	v_cvt_f32_f16_e32 v28, v247
	v_cvt_f32_f16_sdwa v29, v247 dst_sel:DWORD dst_unused:UNUSED_PAD src0_sel:WORD_1
	v_pk_add_f32 v[22:23], v[22:23], v[30:31]
	v_pk_add_f32 v[30:31], v[18:19], v[32:33]
	v_pk_add_f32 v[18:19], v[24:25], v[26:27]
	v_pk_add_f32 v[24:25], v[20:21], v[28:29]
	v_pk_mul_f32 v[26:27], v[22:23], v[22:23]
	v_pk_mul_f32 v[28:29], v[18:19], v[18:19]
	v_pk_mul_f32 v[32:33], v[30:31], v[30:31]
	v_cvt_pk_f16_f32 v20, v22, v23
	v_mul_f32_e32 v22, 0x41000000, v22
	v_mul_f32_e32 v23, 0x41000000, v23
	v_add_f32_e32 v28, v28, v29
	v_add_f32_e32 v26, v26, v27
	v_pk_mul_f32 v[36:37], v[24:25], v[24:25]
	v_add_f32_e32 v27, v32, v33
	v_cvt_pk_fp8_f32 v38, v22, v23
	v_add_f32_e32 v22, v26, v28
	v_add_f32_e32 v29, v36, v37
	v_add_f32_e32 v22, v27, v22
	v_add_f32_e32 v22, v29, v22
	v_add_f32_e32 v22, v44, v22
	v_mul_f32_e32 v45, 0x41000000, v30
	v_mul_f32_e32 v46, 0x41000000, v31
	ds_bpermute_b32 v23, v122, v22
	v_cvt_pk_fp8_f32 v39, v45, v46
	v_cvt_pk_f16_f32 v21, v18, v19
	v_mul_f32_e32 v18, 0x41000000, v18
	v_mul_f32_e32 v19, 0x41000000, v19
	v_cvt_pk_fp8_f32 v38, v18, v19 op_sel:[0,0,1]
	v_mul_f32_e32 v18, 0x41000000, v24
	v_mul_f32_e32 v19, 0x41000000, v25
	v_cvt_pk_fp8_f32 v39, v18, v19 op_sel:[0,0,1]
	s_waitcnt lgkmcnt(0)
	v_add_f32_e32 v18, v22, v23
	ds_bpermute_b32 v19, v116, v18
	v_cvt_pk_f16_f32 v22, v30, v31
	v_cvt_pk_f16_f32 v23, v24, v25
	global_store_dwordx4 v[42:43], v[20:23], off offset:256 sc1
	global_store_dwordx2 v[40:41], v[38:39], off offset:128
	s_and_saveexec_b64 s[2:3], vcc
	s_cbranch_execz .LBB0_684
	v_lshl_add_u64 v[20:21], v[34:35], 2, s[4:5]
	s_waitcnt lgkmcnt(0)
	v_add_f32_e32 v18, v18, v19
	global_atomic_add_f32 v[20:21], v18, off
.LBB0_684:
	s_or_b64 exec, exec, s[2:3]
	v_add_u32_e32 v18, 0xb0, v148
	s_waitcnt lgkmcnt(0)
	v_ashrrev_i32_e32 v19, 31, v18
	v_lshlrev_b64 v[20:21], 10, v[18:19]
	v_lshl_add_u64 v[24:25], v[20:21], 0, v[146:147]
	v_lshl_add_u64 v[26:27], v[24:25], 1, s[90:91]
	v_mov_b32_e32 v28, 0
	v_mov_b32_e32 v29, 0
	v_lshl_add_u64 v[24:25], s[10:11], 0, v[24:25]
	s_waitcnt vmcnt(29)
	v_cvt_f32_f16_e32 v30, v248
	v_cvt_f32_f16_sdwa v31, v248 dst_sel:DWORD dst_unused:UNUSED_PAD src0_sel:WORD_1
	v_cvt_f32_f16_e32 v32, v250
	v_cvt_f32_f16_sdwa v33, v250 dst_sel:DWORD dst_unused:UNUSED_PAD src0_sel:WORD_1
	v_cvt_f32_f16_e32 v20, v249
	v_cvt_f32_f16_sdwa v21, v249 dst_sel:DWORD dst_unused:UNUSED_PAD src0_sel:WORD_1
	v_cvt_f32_f16_e32 v22, v251
	v_cvt_f32_f16_sdwa v23, v251 dst_sel:DWORD dst_unused:UNUSED_PAD src0_sel:WORD_1
	v_pk_add_f32 v[14:15], v[14:15], v[30:31]
	v_pk_add_f32 v[30:31], v[10:11], v[32:33]
	v_pk_add_f32 v[16:17], v[16:17], v[20:21]
	v_pk_add_f32 v[20:21], v[12:13], v[22:23]
	v_mul_f32_e32 v12, 0x41000000, v14
	v_mul_f32_e32 v13, 0x41000000, v15
	v_mul_f32_e32 v32, 0x41000000, v30
	v_mul_f32_e32 v33, 0x41000000, v31
	v_cvt_pk_fp8_f32 v28, v12, v13
	v_cvt_pk_fp8_f32 v29, v32, v33
	v_mul_f32_e32 v22, 0x41000000, v16
	v_mul_f32_e32 v23, 0x41000000, v17
	v_mul_f32_e32 v12, 0x41000000, v20
	v_mul_f32_e32 v13, 0x41000000, v21
	v_cvt_pk_fp8_f32 v28, v22, v23 op_sel:[0,0,1]
	v_cvt_pk_fp8_f32 v29, v12, v13 op_sel:[0,0,1]
	v_cvt_pk_f16_f32 v10, v14, v15
	v_cvt_pk_f16_f32 v11, v16, v17
	v_cvt_pk_f16_f32 v12, v30, v31
	v_cvt_pk_f16_f32 v13, v20, v21
	global_store_dwordx4 v[26:27], v[10:13], off sc1
	global_store_dwordx2 v[24:25], v[28:29], off
	v_pk_mul_f32 v[14:15], v[14:15], v[14:15]
	v_pk_mul_f32 v[16:17], v[16:17], v[16:17]
	v_pk_mul_f32 v[28:29], v[30:31], v[30:31]
	v_add_f32_e32 v16, v16, v17
	v_add_f32_e32 v14, v14, v15
	v_pk_mul_f32 v[20:21], v[20:21], v[20:21]
	v_add_f32_e32 v15, v28, v29
	v_add_f32_e32 v14, v14, v16
	v_add_f32_e32 v17, v20, v21
	v_add_f32_e32 v14, v15, v14
	v_add_f32_e32 v28, v17, v14
	v_mov_b32_e32 v22, 0
	v_mov_b32_e32 v23, 0
	s_waitcnt vmcnt(30)
	v_cvt_f32_f16_e32 v14, v252
	v_cvt_f32_f16_sdwa v15, v252 dst_sel:DWORD dst_unused:UNUSED_PAD src0_sel:WORD_1
	v_cvt_f32_f16_e32 v16, v254
	v_cvt_f32_f16_sdwa v17, v254 dst_sel:DWORD dst_unused:UNUSED_PAD src0_sel:WORD_1
	v_cvt_f32_f16_e32 v10, v253
	v_cvt_f32_f16_sdwa v11, v253 dst_sel:DWORD dst_unused:UNUSED_PAD src0_sel:WORD_1
	v_cvt_f32_f16_e32 v12, v255
	v_cvt_f32_f16_sdwa v13, v255 dst_sel:DWORD dst_unused:UNUSED_PAD src0_sel:WORD_1
	v_pk_add_f32 v[6:7], v[6:7], v[14:15]
	v_pk_add_f32 v[14:15], v[2:3], v[16:17]
	v_pk_add_f32 v[2:3], v[8:9], v[10:11]
	v_pk_add_f32 v[8:9], v[4:5], v[12:13]
	v_pk_mul_f32 v[10:11], v[6:7], v[6:7]
	v_pk_mul_f32 v[12:13], v[2:3], v[2:3]
	v_pk_mul_f32 v[16:17], v[14:15], v[14:15]
	v_cvt_pk_f16_f32 v4, v6, v7
	v_mul_f32_e32 v6, 0x41000000, v6
	v_mul_f32_e32 v7, 0x41000000, v7
	v_add_f32_e32 v12, v12, v13
	v_add_f32_e32 v10, v10, v11
	v_pk_mul_f32 v[20:21], v[8:9], v[8:9]
	v_add_f32_e32 v11, v16, v17
	v_cvt_pk_fp8_f32 v22, v6, v7
	v_add_f32_e32 v6, v10, v12
	v_add_f32_e32 v13, v20, v21
	v_add_f32_e32 v6, v11, v6
	v_add_f32_e32 v6, v13, v6
	v_add_f32_e32 v6, v28, v6
	v_mul_f32_e32 v29, 0x41000000, v14
	v_mul_f32_e32 v30, 0x41000000, v15
	ds_bpermute_b32 v7, v122, v6
	v_cvt_pk_fp8_f32 v23, v29, v30
	v_cvt_pk_f16_f32 v5, v2, v3
	v_mul_f32_e32 v2, 0x41000000, v2
	v_mul_f32_e32 v3, 0x41000000, v3
	v_cvt_pk_fp8_f32 v22, v2, v3 op_sel:[0,0,1]
	v_mul_f32_e32 v2, 0x41000000, v8
	v_mul_f32_e32 v3, 0x41000000, v9
	v_cvt_pk_fp8_f32 v23, v2, v3 op_sel:[0,0,1]
	s_waitcnt lgkmcnt(0)
	v_add_f32_e32 v2, v6, v7
	ds_bpermute_b32 v3, v116, v2
	v_cvt_pk_f16_f32 v6, v14, v15
	v_cvt_pk_f16_f32 v7, v8, v9
	global_store_dwordx4 v[26:27], v[4:7], off offset:256 sc1
	global_store_dwordx2 v[24:25], v[22:23], off offset:128
	s_and_saveexec_b64 s[2:3], vcc
	s_cbranch_execz .LBB0_686
	v_lshl_add_u64 v[4:5], v[18:19], 2, s[4:5]
	s_waitcnt lgkmcnt(0)
	v_add_f32_e32 v2, v2, v3
	global_atomic_add_f32 v[4:5], v2, off

; __device__ __forceinline__ unsigned pkh(float lo, float hi) { f32x2 v = {lo, hi}; h16x2 h = __builtin_convertvector(v, h16x2); return __builtin_bit_cast(unsigned, h); }
; __device__ __forceinline__ unsigned pk8(float a, float b, float c, float d) { int w = __builtin_amdgcn_cvt_pk_fp8_f32(a, b, 0, false); w = __builtin_amdgcn_cvt_pk_fp8_f32(c, d, w, true); return (unsigned)w; }
;     __device__ __forceinline__ void operator()(f32x4 (&acc)[2][2][4][2], const Unit& u, const Order& S, int wr, int wc, int fr_, int fq_, LAS unsigned char*, int) const {
;     ...
;             for (int m = 0; m < 4; ++m) {
;                 const int row = row0 + ai * HALF + m * 16; const size_t off = (size_t)row * DM + col0;
;                 float sq = 0.f;
; #pragma unroll
;                 for (int bj = 0; bj < 2; ++bj) {
;                     const h16x8 bs = *(const h16x8*)(h16 + off + bj * HALF);
;                     f32x4 o0 = acc[ai][bj][m][0] * pre, o1 = acc[ai][bj][m][1] * pre;
; #pragma unroll
;                     for (int e = 0; e < 4; ++e) { o0[e] += (float)bs[e]; o1[e] += (float)bs[4 + e]; }
;                     if (out32) { if (!dry) { __builtin_nontemporal_store(o0, (f32x4*)(out32 + off + bj * HALF)); __builtin_nontemporal_store(o1, (f32x4*)(out32 + off + bj * HALF + 4)); } }
;                     else if (!dry) {
;                         sq += (o0[0] * o0[0] + o0[1] * o0[1]) + (o0[2] * o0[2] + o0[3] * o0[3]) + (o1[0] * o1[0] + o1[1] * o1[1]) + (o1[2] * o1[2] + o1[3] * o1[3]);
;                         u32x4 w; w.x = pkh(o0[0], o0[1]); w.y = pkh(o0[2], o0[3]); w.z = pkh(o1[0], o1[1]); w.w = pkh(o1[2], o1[3]);
;                         *(u32x4*)(h16 + off + bj * HALF) = w;
;                         if (h8) { u32x2 q; q.x = pk8(o0[0] * F8_SA, o0[1] * F8_SA, o0[2] * F8_SA, o0[3] * F8_SA); q.y = pk8(o1[0] * F8_SA, o1[1] * F8_SA, o1[2] * F8_SA, o1[3] * F8_SA); *(u32x2*)(h8 + off + bj * HALF) = q; } }
;                 }
;                 if (!out32 && !dry) { sq += __shfl_xor(sq, 16); sq += __shfl_xor(sq, 32); if (fq == 0) atomicAdd(ss_out + row, sq); }
.LBB0_1326:
	s_lshl_b32 s3, s46, 8
	v_mov_b32_e32 v8, v187
	v_mov_b32_e32 v2, v186
	s_add_i32 s3, s3, s39
	s_nop 15
	s_nop 15
	s_lshl_b32 s2, s2, 8
	v_add_u32_e32 v4, s3, v2
	s_or_b32 s2, s2, s40
	v_ashrrev_i32_e32 v5, 31, v4
	v_lshl_add_u32 v2, v8, 3, s2
	v_lshlrev_b64 v[6:7], 11, v[4:5]
	v_ashrrev_i32_e32 v3, 31, v2
	v_lshl_add_u64 v[6:7], s[90:91], 0, v[6:7]
	v_lshl_add_u64 v[18:19], v[2:3], 1, v[6:7]
	global_load_dwordx4 v[10:13], v[18:19], off
	global_load_dwordx4 v[14:17], v[18:19], off offset:256
	s_mov_b32 s99, 0
	s_mov_b32 s98, 0x8000
	v_lshl_add_u64 v[252:253], s[98:99], 0, v[18:19]
	global_load_dwordx4 v[178:181], v[252:253], off
	global_load_dwordx4 v[182:185], v[252:253], off offset:256
	s_mov_b32 s98, 0x10000
	v_lshl_add_u64 v[252:253], s[98:99], 0, v[18:19]
	global_load_dwordx4 v[194:197], v[252:253], off
	global_load_dwordx4 v[198:201], v[252:253], off offset:256
	s_mov_b32 s98, 0x18000
	v_lshl_add_u64 v[252:253], s[98:99], 0, v[18:19]
	global_load_dwordx4 v[208:211], v[252:253], off
	global_load_dwordx4 v[212:215], v[252:253], off offset:256
	s_mov_b32 s98, 0x40000
	v_lshl_add_u64 v[252:253], s[98:99], 0, v[18:19]
	global_load_dwordx4 v[216:219], v[252:253], off
	global_load_dwordx4 v[220:223], v[252:253], off offset:256
	s_mov_b32 s98, 0x48000
	v_lshl_add_u64 v[252:253], s[98:99], 0, v[18:19]
	global_load_dwordx4 v[224:227], v[252:253], off
	global_load_dwordx4 v[228:231], v[252:253], off offset:256
	s_mov_b32 s98, 0x50000
	v_lshl_add_u64 v[252:253], s[98:99], 0, v[18:19]
	global_load_dwordx4 v[240:243], v[252:253], off
	global_load_dwordx4 v[244:247], v[252:253], off offset:256
	s_mov_b32 s98, 0x58000
	v_lshl_add_u64 v[252:253], s[98:99], 0, v[18:19]
	global_load_dwordx4 v[248:251], v[252:253], off
	global_load_dwordx4 v[252:255], v[252:253], off offset:256
	v_and_b32_e32 v7, 64, v192
	v_xor_b32_e32 v6, 16, v192
	v_add_u32_e32 v7, 64, v7
	v_cmp_lt_i32_e64 s[2:3], v6, v7
	v_xor_b32_e32 v9, 32, v192
	v_cmp_eq_u32_e32 vcc, 0, v8
	v_cndmask_b32_e64 v6, v192, v6, s[2:3]
	v_cmp_lt_i32_e64 s[2:3], v9, v7
	v_lshlrev_b32_e32 v8, 2, v6
	s_waitcnt vmcnt(14)
	v_cvt_f32_f16_e32 v6, v10
	v_cvt_f32_f16_sdwa v7, v10 dst_sel:DWORD dst_unused:UNUSED_PAD src0_sel:WORD_1
	v_cvt_f32_f16_e32 v10, v11
	v_cvt_f32_f16_sdwa v11, v11 dst_sel:DWORD dst_unused:UNUSED_PAD src0_sel:WORD_1
	v_cvt_f32_f16_e32 v22, v14
	v_cvt_f32_f16_sdwa v23, v14 dst_sel:DWORD dst_unused:UNUSED_PAD src0_sel:WORD_1
	v_cvt_f32_f16_e32 v14, v15
	v_cvt_f32_f16_sdwa v15, v15 dst_sel:DWORD dst_unused:UNUSED_PAD src0_sel:WORD_1
	v_cvt_f32_f16_e32 v20, v12
	v_cvt_f32_f16_sdwa v21, v12 dst_sel:DWORD dst_unused:UNUSED_PAD src0_sel:WORD_1
	v_cvt_f32_f16_e32 v12, v13
	v_cvt_f32_f16_sdwa v13, v13 dst_sel:DWORD dst_unused:UNUSED_PAD src0_sel:WORD_1
	v_cvt_f32_f16_e32 v24, v16
	v_cvt_f32_f16_sdwa v25, v16 dst_sel:DWORD dst_unused:UNUSED_PAD src0_sel:WORD_1
	v_cvt_f32_f16_e32 v16, v17
	v_cvt_f32_f16_sdwa v17, v17 dst_sel:DWORD dst_unused:UNUSED_PAD src0_sel:WORD_1
	v_pk_fma_f32 v[6:7], v[158:159], s[12:13], v[6:7] op_sel_hi:[1,0,1]
	v_pk_fma_f32 v[26:27], v[160:161], s[12:13], v[10:11] op_sel_hi:[1,0,1]
	v_pk_fma_f32 v[22:23], v[150:151], s[12:13], v[22:23] op_sel_hi:[1,0,1]
	v_pk_fma_f32 v[30:31], v[152:153], s[12:13], v[14:15] op_sel_hi:[1,0,1]
	v_pk_fma_f32 v[20:21], v[154:155], s[12:13], v[20:21] op_sel_hi:[1,0,1]
	v_pk_fma_f32 v[28:29], v[156:157], s[12:13], v[12:13] op_sel_hi:[1,0,1]
	v_pk_fma_f32 v[24:25], v[146:147], s[12:13], v[24:25] op_sel_hi:[1,0,1]
	v_pk_mul_f32 v[12:13], v[6:7], v[6:7]
	v_pk_mul_f32 v[14:15], v[26:27], v[26:27]
	v_cvt_pk_f16_f32 v10, v6, v7
	v_cvt_pk_f16_f32 v11, v26, v27
	v_pk_mul_f32 v[6:7], v[22:23], v[22:23]
	v_pk_mul_f32 v[26:27], v[30:31], v[30:31]
	v_pk_fma_f32 v[32:33], v[148:149], s[12:13], v[16:17] op_sel_hi:[1,0,1]
	v_pk_mul_f32 v[16:17], v[20:21], v[20:21]
	v_pk_mul_f32 v[148:149], v[24:25], v[24:25]
	v_add_f32_e32 v26, v26, v27
	v_add_f32_e32 v6, v6, v7
	v_add_f32_e32 v14, v14, v15
	v_add_f32_e32 v12, v12, v13
	v_pk_mul_f32 v[146:147], v[28:29], v[28:29]
	v_pk_mul_f32 v[150:151], v[32:33], v[32:33]
	v_add_f32_e32 v7, v148, v149
	v_add_f32_e32 v13, v16, v17
	v_add_f32_e32 v6, v6, v26
	v_add_f32_e32 v12, v12, v14
	v_add_f32_e32 v27, v150, v151
	v_add_f32_e32 v15, v146, v147
	v_add_f32_e32 v6, v7, v6
	v_add_f32_e32 v7, v13, v12
	v_add_f32_e32 v6, v27, v6
	v_add_f32_e32 v7, v15, v7
	v_add_f32_e32 v6, v7, v6
	ds_bpermute_b32 v7, v8, v6
	v_cndmask_b32_e64 v9, v192, v9, s[2:3]
	v_lshlrev_b32_e32 v9, 2, v9
	v_cvt_pk_f16_f32 v12, v20, v21
	v_cvt_pk_f16_f32 v13, v28, v29
	s_waitcnt lgkmcnt(0)
	v_add_f32_e32 v6, v6, v7
	ds_bpermute_b32 v7, v9, v6
	v_cvt_pk_f16_f32 v14, v22, v23
	v_cvt_pk_f16_f32 v15, v30, v31
	v_cvt_pk_f16_f32 v16, v24, v25
	v_cvt_pk_f16_f32 v17, v32, v33
	global_store_dwordx4 v[18:19], v[10:13], off sc1
	global_store_dwordx4 v[18:19], v[14:17], off offset:256 sc1
	s_and_saveexec_b64 s[2:3], vcc
	s_cbranch_execz .LBB0_1328
	v_lshl_add_u64 v[10:11], v[4:5], 2, s[18:19]
	s_waitcnt lgkmcnt(0)
	v_add_f32_e32 v5, v6, v7
	global_atomic_add_f32 v[10:11], v5, off
; __device__ __forceinline__ unsigned pkh(float lo, float hi) { f32x2 v = {lo, hi}; h16x2 h = __builtin_convertvector(v, h16x2); return __builtin_bit_cast(unsigned, h); }
; __device__ __forceinline__ unsigned pk8(float a, float b, float c, float d) { int w = __builtin_amdgcn_cvt_pk_fp8_f32(a, b, 0, false); w = __builtin_amdgcn_cvt_pk_fp8_f32(c, d, w, true); return (unsigned)w; }
;     __device__ __forceinline__ void operator()(f32x4 (&acc)[2][2][4][2], const Unit& u, const Order& S, int wr, int wc, int fr_, int fq_, LAS unsigned char*, int) const {
;     ...
;             for (int m = 0; m < 4; ++m) {
;                 const int row = row0 + ai * HALF + m * 16; const size_t off = (size_t)row * DM + col0;
;                 float sq = 0.f;
; #pragma unroll
;                 for (int bj = 0; bj < 2; ++bj) {
;                     const h16x8 bs = *(const h16x8*)(h16 + off + bj * HALF);
;                     f32x4 o0 = acc[ai][bj][m][0] * pre, o1 = acc[ai][bj][m][1] * pre;
; #pragma unroll
;                     for (int e = 0; e < 4; ++e) { o0[e] += (float)bs[e]; o1[e] += (float)bs[4 + e]; }
;                     if (out32) { if (!dry) { __builtin_nontemporal_store(o0, (f32x4*)(out32 + off + bj * HALF)); __builtin_nontemporal_store(o1, (f32x4*)(out32 + off + bj * HALF + 4)); } }
;                     else if (!dry) {
;                         sq += (o0[0] * o0[0] + o0[1] * o0[1]) + (o0[2] * o0[2] + o0[3] * o0[3]) + (o1[0] * o1[0] + o1[1] * o1[1]) + (o1[2] * o1[2] + o1[3] * o1[3]);
;                         u32x4 w; w.x = pkh(o0[0], o0[1]); w.y = pkh(o0[2], o0[3]); w.z = pkh(o1[0], o1[1]); w.w = pkh(o1[2], o1[3]);
;                         *(u32x4*)(h16 + off + bj * HALF) = w;
;                         if (h8) { u32x2 q; q.x = pk8(o0[0] * F8_SA, o0[1] * F8_SA, o0[2] * F8_SA, o0[3] * F8_SA); q.y = pk8(o1[0] * F8_SA, o1[1] * F8_SA, o1[2] * F8_SA, o1[3] * F8_SA); *(u32x2*)(h8 + off + bj * HALF) = q; } }
;                 }
;                 if (!out32 && !dry) { sq += __shfl_xor(sq, 16); sq += __shfl_xor(sq, 32); if (fq == 0) atomicAdd(ss_out + row, sq); }
.LBB0_1328:
	s_or_b64 exec, exec, s[2:3]
	v_add_u32_e32 v6, 16, v4
	s_waitcnt lgkmcnt(0)
	v_ashrrev_i32_e32 v7, 31, v6
	v_lshlrev_b64 v[10:11], 11, v[6:7]
	v_lshl_add_u64 v[10:11], s[90:91], 0, v[10:11]
	v_lshl_add_u64 v[18:19], v[2:3], 1, v[10:11]
	s_waitcnt vmcnt(15)
	v_cvt_f32_f16_e32 v20, v178
	v_cvt_f32_f16_sdwa v21, v178 dst_sel:DWORD dst_unused:UNUSED_PAD src0_sel:WORD_1
	v_cvt_f32_f16_e32 v10, v179
	v_cvt_f32_f16_sdwa v11, v179 dst_sel:DWORD dst_unused:UNUSED_PAD src0_sel:WORD_1
	s_waitcnt vmcnt(14)
	v_cvt_f32_f16_e32 v24, v182
	v_cvt_f32_f16_sdwa v25, v182 dst_sel:DWORD dst_unused:UNUSED_PAD src0_sel:WORD_1
	v_cvt_f32_f16_e32 v14, v183
	v_cvt_f32_f16_sdwa v15, v183 dst_sel:DWORD dst_unused:UNUSED_PAD src0_sel:WORD_1
	v_cvt_f32_f16_e32 v22, v180
	v_cvt_f32_f16_sdwa v23, v180 dst_sel:DWORD dst_unused:UNUSED_PAD src0_sel:WORD_1
	v_cvt_f32_f16_e32 v12, v181
	v_cvt_f32_f16_sdwa v13, v181 dst_sel:DWORD dst_unused:UNUSED_PAD src0_sel:WORD_1
	v_cvt_f32_f16_e32 v26, v184
	v_cvt_f32_f16_sdwa v27, v184 dst_sel:DWORD dst_unused:UNUSED_PAD src0_sel:WORD_1
	v_cvt_f32_f16_e32 v16, v185
	v_cvt_f32_f16_sdwa v17, v185 dst_sel:DWORD dst_unused:UNUSED_PAD src0_sel:WORD_1
	v_pk_fma_f32 v[20:21], v[142:143], s[12:13], v[20:21] op_sel_hi:[1,0,1]
	v_pk_fma_f32 v[28:29], v[144:145], s[12:13], v[10:11] op_sel_hi:[1,0,1]
	v_pk_fma_f32 v[24:25], v[134:135], s[12:13], v[24:25] op_sel_hi:[1,0,1]
	v_pk_fma_f32 v[14:15], v[136:137], s[12:13], v[14:15] op_sel_hi:[1,0,1]
	v_pk_fma_f32 v[22:23], v[138:139], s[12:13], v[22:23] op_sel_hi:[1,0,1]
	v_pk_fma_f32 v[30:31], v[140:141], s[12:13], v[12:13] op_sel_hi:[1,0,1]
	v_pk_fma_f32 v[26:27], v[130:131], s[12:13], v[26:27] op_sel_hi:[1,0,1]
	v_pk_mul_f32 v[12:13], v[20:21], v[20:21]
	v_pk_mul_f32 v[32:33], v[28:29], v[28:29]
	v_cvt_pk_f16_f32 v10, v20, v21
	v_cvt_pk_f16_f32 v11, v28, v29
	v_pk_mul_f32 v[20:21], v[24:25], v[24:25]
	v_pk_mul_f32 v[28:29], v[14:15], v[14:15]
	v_pk_fma_f32 v[16:17], v[132:133], s[12:13], v[16:17] op_sel_hi:[1,0,1]
	v_pk_mul_f32 v[130:131], v[22:23], v[22:23]
	v_pk_mul_f32 v[134:135], v[26:27], v[26:27]
	v_add_f32_e32 v5, v28, v29
	v_add_f32_e32 v20, v20, v21
	v_add_f32_e32 v29, v32, v33
	v_add_f32_e32 v12, v12, v13
	v_pk_mul_f32 v[132:133], v[30:31], v[30:31]
	v_pk_mul_f32 v[136:137], v[16:17], v[16:17]
	v_add_f32_e32 v21, v134, v135
	v_add_f32_e32 v13, v130, v131
	v_add_f32_e32 v5, v20, v5
	v_add_f32_e32 v12, v12, v29
	v_add_f32_e32 v28, v136, v137
	v_add_f32_e32 v32, v132, v133
	v_add_f32_e32 v5, v21, v5
	v_add_f32_e32 v12, v13, v12
	v_add_f32_e32 v5, v28, v5
	v_add_f32_e32 v12, v32, v12
	v_add_f32_e32 v5, v12, v5
	ds_bpermute_b32 v20, v8, v5
	v_cvt_pk_f16_f32 v12, v22, v23
	v_cvt_pk_f16_f32 v13, v30, v31
	global_store_dwordx4 v[18:19], v[10:13], off sc1
	s_waitcnt lgkmcnt(0)
	v_add_f32_e32 v5, v5, v20
	ds_bpermute_b32 v10, v9, v5
	v_cvt_pk_f16_f32 v12, v24, v25
	v_cvt_pk_f16_f32 v13, v14, v15
	v_cvt_pk_f16_f32 v14, v26, v27
	v_cvt_pk_f16_f32 v15, v16, v17
	global_store_dwordx4 v[18:19], v[12:15], off offset:256 sc1
	s_and_saveexec_b64 s[2:3], vcc
	s_cbranch_execz .LBB0_1330
	v_lshl_add_u64 v[6:7], v[6:7], 2, s[18:19]
	s_waitcnt lgkmcnt(0)
	v_add_f32_e32 v5, v5, v10
	global_atomic_add_f32 v[6:7], v5, off
.LBB0_1330:
	s_or_b64 exec, exec, s[2:3]
	v_add_u32_e32 v6, 32, v4
	v_ashrrev_i32_e32 v7, 31, v6
	s_waitcnt lgkmcnt(0)
	v_lshlrev_b64 v[10:11], 11, v[6:7]
	v_lshl_add_u64 v[10:11], s[90:91], 0, v[10:11]
	v_lshl_add_u64 v[18:19], v[2:3], 1, v[10:11]
	s_waitcnt vmcnt(15)
	v_cvt_f32_f16_e32 v20, v194
	v_cvt_f32_f16_sdwa v21, v194 dst_sel:DWORD dst_unused:UNUSED_PAD src0_sel:WORD_1
	v_cvt_f32_f16_e32 v10, v195
	v_cvt_f32_f16_sdwa v11, v195 dst_sel:DWORD dst_unused:UNUSED_PAD src0_sel:WORD_1
	s_waitcnt vmcnt(14)
	v_cvt_f32_f16_e32 v24, v198
	v_cvt_f32_f16_sdwa v25, v198 dst_sel:DWORD dst_unused:UNUSED_PAD src0_sel:WORD_1
	v_cvt_f32_f16_e32 v14, v199
	v_cvt_f32_f16_sdwa v15, v199 dst_sel:DWORD dst_unused:UNUSED_PAD src0_sel:WORD_1
	v_cvt_f32_f16_e32 v22, v196
	v_cvt_f32_f16_sdwa v23, v196 dst_sel:DWORD dst_unused:UNUSED_PAD src0_sel:WORD_1
	v_cvt_f32_f16_e32 v12, v197
	v_cvt_f32_f16_sdwa v13, v197 dst_sel:DWORD dst_unused:UNUSED_PAD src0_sel:WORD_1
	v_cvt_f32_f16_e32 v26, v200
	v_cvt_f32_f16_sdwa v27, v200 dst_sel:DWORD dst_unused:UNUSED_PAD src0_sel:WORD_1
	v_cvt_f32_f16_e32 v16, v201
	v_cvt_f32_f16_sdwa v17, v201 dst_sel:DWORD dst_unused:UNUSED_PAD src0_sel:WORD_1
	v_pk_fma_f32 v[20:21], v[126:127], s[12:13], v[20:21] op_sel_hi:[1,0,1]
	v_pk_fma_f32 v[28:29], v[128:129], s[12:13], v[10:11] op_sel_hi:[1,0,1]
	v_pk_fma_f32 v[24:25], v[118:119], s[12:13], v[24:25] op_sel_hi:[1,0,1]
	v_pk_fma_f32 v[14:15], v[120:121], s[12:13], v[14:15] op_sel_hi:[1,0,1]
	v_pk_fma_f32 v[22:23], v[122:123], s[12:13], v[22:23] op_sel_hi:[1,0,1]
	v_pk_fma_f32 v[30:31], v[124:125], s[12:13], v[12:13] op_sel_hi:[1,0,1]
	v_pk_fma_f32 v[26:27], v[114:115], s[12:13], v[26:27] op_sel_hi:[1,0,1]
	v_pk_mul_f32 v[12:13], v[20:21], v[20:21]
	v_pk_mul_f32 v[32:33], v[28:29], v[28:29]
	v_cvt_pk_f16_f32 v10, v20, v21
	v_cvt_pk_f16_f32 v11, v28, v29
	v_pk_mul_f32 v[20:21], v[24:25], v[24:25]
	v_pk_mul_f32 v[28:29], v[14:15], v[14:15]
	v_pk_fma_f32 v[16:17], v[116:117], s[12:13], v[16:17] op_sel_hi:[1,0,1]
	v_pk_mul_f32 v[114:115], v[22:23], v[22:23]
	v_pk_mul_f32 v[118:119], v[26:27], v[26:27]
	v_add_f32_e32 v5, v28, v29
	v_add_f32_e32 v20, v20, v21
	v_add_f32_e32 v29, v32, v33
	v_add_f32_e32 v12, v12, v13
	v_pk_mul_f32 v[116:117], v[30:31], v[30:31]
	v_pk_mul_f32 v[120:121], v[16:17], v[16:17]
	v_add_f32_e32 v21, v118, v119
	v_add_f32_e32 v13, v114, v115
	v_add_f32_e32 v5, v20, v5
	v_add_f32_e32 v12, v12, v29
	v_add_f32_e32 v28, v120, v121
	v_add_f32_e32 v32, v116, v117
	v_add_f32_e32 v5, v21, v5
	v_add_f32_e32 v12, v13, v12
	v_add_f32_e32 v5, v28, v5
	v_add_f32_e32 v12, v32, v12
	v_add_f32_e32 v5, v12, v5
	ds_bpermute_b32 v20, v8, v5
	v_cvt_pk_f16_f32 v12, v22, v23
	v_cvt_pk_f16_f32 v13, v30, v31
	global_store_dwordx4 v[18:19], v[10:13], off sc1
	s_waitcnt lgkmcnt(0)
	v_add_f32_e32 v5, v5, v20
	ds_bpermute_b32 v10, v9, v5
	v_cvt_pk_f16_f32 v12, v24, v25
	v_cvt_pk_f16_f32 v13, v14, v15
	v_cvt_pk_f16_f32 v14, v26, v27
	v_cvt_pk_f16_f32 v15, v16, v17
	global_store_dwordx4 v[18:19], v[12:15], off offset:256 sc1
	s_and_saveexec_b64 s[2:3], vcc
	s_cbranch_execz .LBB0_1332
	v_lshl_add_u64 v[6:7], v[6:7], 2, s[18:19]
	s_waitcnt lgkmcnt(0)
	v_add_f32_e32 v5, v5, v10
	global_atomic_add_f32 v[6:7], v5, off
; __device__ __forceinline__ unsigned pkh(float lo, float hi) { f32x2 v = {lo, hi}; h16x2 h = __builtin_convertvector(v, h16x2); return __builtin_bit_cast(unsigned, h); }
; __device__ __forceinline__ unsigned pk8(float a, float b, float c, float d) { int w = __builtin_amdgcn_cvt_pk_fp8_f32(a, b, 0, false); w = __builtin_amdgcn_cvt_pk_fp8_f32(c, d, w, true); return (unsigned)w; }
;     __device__ __forceinline__ void operator()(f32x4 (&acc)[2][2][4][2], const Unit& u, const Order& S, int wr, int wc, int fr_, int fq_, LAS unsigned char*, int) const {
;     ...
;             for (int m = 0; m < 4; ++m) {
;                 const int row = row0 + ai * HALF + m * 16; const size_t off = (size_t)row * DM + col0;
;                 float sq = 0.f;
; #pragma unroll
;                 for (int bj = 0; bj < 2; ++bj) {
;                     const h16x8 bs = *(const h16x8*)(h16 + off + bj * HALF);
;                     f32x4 o0 = acc[ai][bj][m][0] * pre, o1 = acc[ai][bj][m][1] * pre;
; #pragma unroll
;                     for (int e = 0; e < 4; ++e) { o0[e] += (float)bs[e]; o1[e] += (float)bs[4 + e]; }
;                     if (out32) { if (!dry) { __builtin_nontemporal_store(o0, (f32x4*)(out32 + off + bj * HALF)); __builtin_nontemporal_store(o1, (f32x4*)(out32 + off + bj * HALF + 4)); } }
;                     else if (!dry) {
;                         sq += (o0[0] * o0[0] + o0[1] * o0[1]) + (o0[2] * o0[2] + o0[3] * o0[3]) + (o1[0] * o1[0] + o1[1] * o1[1]) + (o1[2] * o1[2] + o1[3] * o1[3]);
;                         u32x4 w; w.x = pkh(o0[0], o0[1]); w.y = pkh(o0[2], o0[3]); w.z = pkh(o1[0], o1[1]); w.w = pkh(o1[2], o1[3]);
;                         *(u32x4*)(h16 + off + bj * HALF) = w;
;                         if (h8) { u32x2 q; q.x = pk8(o0[0] * F8_SA, o0[1] * F8_SA, o0[2] * F8_SA, o0[3] * F8_SA); q.y = pk8(o1[0] * F8_SA, o1[1] * F8_SA, o1[2] * F8_SA, o1[3] * F8_SA); *(u32x2*)(h8 + off + bj * HALF) = q; } }
;                 }
;                 if (!out32 && !dry) { sq += __shfl_xor(sq, 16); sq += __shfl_xor(sq, 32); if (fq == 0) atomicAdd(ss_out + row, sq); }
.LBB0_1332:
	s_or_b64 exec, exec, s[2:3]
	v_add_u32_e32 v6, 48, v4
	v_ashrrev_i32_e32 v7, 31, v6
	s_waitcnt lgkmcnt(0)
	v_lshlrev_b64 v[10:11], 11, v[6:7]
	v_lshl_add_u64 v[10:11], s[90:91], 0, v[10:11]
	v_lshl_add_u64 v[18:19], v[2:3], 1, v[10:11]
	s_waitcnt vmcnt(15)
	v_cvt_f32_f16_e32 v20, v208
	v_cvt_f32_f16_sdwa v21, v208 dst_sel:DWORD dst_unused:UNUSED_PAD src0_sel:WORD_1
	v_cvt_f32_f16_e32 v10, v209
	v_cvt_f32_f16_sdwa v11, v209 dst_sel:DWORD dst_unused:UNUSED_PAD src0_sel:WORD_1
	s_waitcnt vmcnt(14)
	v_cvt_f32_f16_e32 v24, v212
	v_cvt_f32_f16_sdwa v25, v212 dst_sel:DWORD dst_unused:UNUSED_PAD src0_sel:WORD_1
	v_cvt_f32_f16_e32 v14, v213
	v_cvt_f32_f16_sdwa v15, v213 dst_sel:DWORD dst_unused:UNUSED_PAD src0_sel:WORD_1
	v_cvt_f32_f16_e32 v22, v210
	v_cvt_f32_f16_sdwa v23, v210 dst_sel:DWORD dst_unused:UNUSED_PAD src0_sel:WORD_1
	v_cvt_f32_f16_e32 v12, v211
	v_cvt_f32_f16_sdwa v13, v211 dst_sel:DWORD dst_unused:UNUSED_PAD src0_sel:WORD_1
	v_cvt_f32_f16_e32 v26, v214
	v_cvt_f32_f16_sdwa v27, v214 dst_sel:DWORD dst_unused:UNUSED_PAD src0_sel:WORD_1
	v_cvt_f32_f16_e32 v16, v215
	v_cvt_f32_f16_sdwa v17, v215 dst_sel:DWORD dst_unused:UNUSED_PAD src0_sel:WORD_1
	v_pk_fma_f32 v[20:21], v[110:111], s[12:13], v[20:21] op_sel_hi:[1,0,1]
	v_pk_fma_f32 v[28:29], v[112:113], s[12:13], v[10:11] op_sel_hi:[1,0,1]
	v_pk_fma_f32 v[24:25], v[102:103], s[12:13], v[24:25] op_sel_hi:[1,0,1]
	v_pk_fma_f32 v[14:15], v[104:105], s[12:13], v[14:15] op_sel_hi:[1,0,1]
	v_pk_fma_f32 v[22:23], v[106:107], s[12:13], v[22:23] op_sel_hi:[1,0,1]
	v_pk_fma_f32 v[30:31], v[108:109], s[12:13], v[12:13] op_sel_hi:[1,0,1]
	v_pk_fma_f32 v[26:27], v[98:99], s[12:13], v[26:27] op_sel_hi:[1,0,1]
	v_pk_mul_f32 v[12:13], v[20:21], v[20:21]
	v_pk_mul_f32 v[32:33], v[28:29], v[28:29]
	v_cvt_pk_f16_f32 v10, v20, v21
	v_cvt_pk_f16_f32 v11, v28, v29
	v_pk_mul_f32 v[20:21], v[24:25], v[24:25]
	v_pk_mul_f32 v[28:29], v[14:15], v[14:15]
	v_pk_fma_f32 v[16:17], v[100:101], s[12:13], v[16:17] op_sel_hi:[1,0,1]
	v_pk_mul_f32 v[98:99], v[22:23], v[22:23]
	v_pk_mul_f32 v[102:103], v[26:27], v[26:27]
	v_add_f32_e32 v5, v28, v29
	v_add_f32_e32 v20, v20, v21
	v_add_f32_e32 v29, v32, v33
	v_add_f32_e32 v12, v12, v13
	v_pk_mul_f32 v[100:101], v[30:31], v[30:31]
	v_pk_mul_f32 v[104:105], v[16:17], v[16:17]
	v_add_f32_e32 v21, v102, v103
	v_add_f32_e32 v13, v98, v99
	v_add_f32_e32 v5, v20, v5
	v_add_f32_e32 v12, v12, v29
	v_add_f32_e32 v28, v104, v105
	v_add_f32_e32 v32, v100, v101
	v_add_f32_e32 v5, v21, v5
	v_add_f32_e32 v12, v13, v12
	v_add_f32_e32 v5, v28, v5
	v_add_f32_e32 v12, v32, v12
	v_add_f32_e32 v5, v12, v5
	ds_bpermute_b32 v20, v8, v5
	v_cvt_pk_f16_f32 v12, v22, v23
	v_cvt_pk_f16_f32 v13, v30, v31
	global_store_dwordx4 v[18:19], v[10:13], off sc1
	s_waitcnt lgkmcnt(0)
	v_add_f32_e32 v5, v5, v20
	ds_bpermute_b32 v10, v9, v5
	v_cvt_pk_f16_f32 v12, v24, v25
	v_cvt_pk_f16_f32 v13, v14, v15
	v_cvt_pk_f16_f32 v14, v26, v27
	v_cvt_pk_f16_f32 v15, v16, v17
	global_store_dwordx4 v[18:19], v[12:15], off offset:256 sc1
	s_and_saveexec_b64 s[2:3], vcc
	s_cbranch_execz .LBB0_1334
	v_lshl_add_u64 v[6:7], v[6:7], 2, s[18:19]
	s_waitcnt lgkmcnt(0)
	v_add_f32_e32 v5, v5, v10
	global_atomic_add_f32 v[6:7], v5, off
.LBB0_1334:
	s_or_b64 exec, exec, s[2:3]
	v_add_u32_e32 v6, 0x80, v4
	v_ashrrev_i32_e32 v7, 31, v6
	s_waitcnt lgkmcnt(0)
	v_lshlrev_b64 v[10:11], 11, v[6:7]
	v_lshl_add_u64 v[10:11], s[90:91], 0, v[10:11]
	v_lshl_add_u64 v[18:19], v[2:3], 1, v[10:11]
	s_waitcnt vmcnt(15)
	v_cvt_f32_f16_e32 v20, v216
	v_cvt_f32_f16_sdwa v21, v216 dst_sel:DWORD dst_unused:UNUSED_PAD src0_sel:WORD_1
	v_cvt_f32_f16_e32 v10, v217
	v_cvt_f32_f16_sdwa v11, v217 dst_sel:DWORD dst_unused:UNUSED_PAD src0_sel:WORD_1
	s_waitcnt vmcnt(14)
	v_cvt_f32_f16_e32 v24, v220
	v_cvt_f32_f16_sdwa v25, v220 dst_sel:DWORD dst_unused:UNUSED_PAD src0_sel:WORD_1
	v_cvt_f32_f16_e32 v14, v221
	v_cvt_f32_f16_sdwa v15, v221 dst_sel:DWORD dst_unused:UNUSED_PAD src0_sel:WORD_1
	v_cvt_f32_f16_e32 v22, v218
	v_cvt_f32_f16_sdwa v23, v218 dst_sel:DWORD dst_unused:UNUSED_PAD src0_sel:WORD_1
	v_cvt_f32_f16_e32 v12, v219
	v_cvt_f32_f16_sdwa v13, v219 dst_sel:DWORD dst_unused:UNUSED_PAD src0_sel:WORD_1
	v_cvt_f32_f16_e32 v26, v222
	v_cvt_f32_f16_sdwa v27, v222 dst_sel:DWORD dst_unused:UNUSED_PAD src0_sel:WORD_1
	v_cvt_f32_f16_e32 v16, v223
	v_cvt_f32_f16_sdwa v17, v223 dst_sel:DWORD dst_unused:UNUSED_PAD src0_sel:WORD_1
	v_pk_fma_f32 v[20:21], v[94:95], s[12:13], v[20:21] op_sel_hi:[1,0,1]
	v_pk_fma_f32 v[28:29], v[96:97], s[12:13], v[10:11] op_sel_hi:[1,0,1]
	v_pk_fma_f32 v[24:25], v[86:87], s[12:13], v[24:25] op_sel_hi:[1,0,1]
	v_pk_fma_f32 v[14:15], v[88:89], s[12:13], v[14:15] op_sel_hi:[1,0,1]
	v_pk_fma_f32 v[22:23], v[90:91], s[12:13], v[22:23] op_sel_hi:[1,0,1]
	v_pk_fma_f32 v[30:31], v[92:93], s[12:13], v[12:13] op_sel_hi:[1,0,1]
	v_pk_fma_f32 v[26:27], v[82:83], s[12:13], v[26:27] op_sel_hi:[1,0,1]
	v_pk_mul_f32 v[12:13], v[20:21], v[20:21]
	v_pk_mul_f32 v[32:33], v[28:29], v[28:29]
	v_cvt_pk_f16_f32 v10, v20, v21
	v_cvt_pk_f16_f32 v11, v28, v29
	v_pk_mul_f32 v[20:21], v[24:25], v[24:25]
	v_pk_mul_f32 v[28:29], v[14:15], v[14:15]
	v_pk_fma_f32 v[16:17], v[84:85], s[12:13], v[16:17] op_sel_hi:[1,0,1]
	v_pk_mul_f32 v[82:83], v[22:23], v[22:23]
	v_pk_mul_f32 v[86:87], v[26:27], v[26:27]
	v_add_f32_e32 v5, v28, v29
	v_add_f32_e32 v20, v20, v21
	v_add_f32_e32 v29, v32, v33
	v_add_f32_e32 v12, v12, v13
	v_pk_mul_f32 v[84:85], v[30:31], v[30:31]
	v_pk_mul_f32 v[88:89], v[16:17], v[16:17]
	v_add_f32_e32 v21, v86, v87
	v_add_f32_e32 v13, v82, v83
	v_add_f32_e32 v5, v20, v5
	v_add_f32_e32 v12, v12, v29
	v_add_f32_e32 v28, v88, v89
	v_add_f32_e32 v32, v84, v85
	v_add_f32_e32 v5, v21, v5
	v_add_f32_e32 v12, v13, v12
	v_add_f32_e32 v5, v28, v5
	v_add_f32_e32 v12, v32, v12
	v_add_f32_e32 v5, v12, v5
	ds_bpermute_b32 v20, v8, v5
	v_cvt_pk_f16_f32 v12, v22, v23
	v_cvt_pk_f16_f32 v13, v30, v31
	global_store_dwordx4 v[18:19], v[10:13], off sc1
	s_waitcnt lgkmcnt(0)
	v_add_f32_e32 v5, v5, v20
	ds_bpermute_b32 v10, v9, v5
	v_cvt_pk_f16_f32 v12, v24, v25
	v_cvt_pk_f16_f32 v13, v14, v15
	v_cvt_pk_f16_f32 v14, v26, v27
	v_cvt_pk_f16_f32 v15, v16, v17
	global_store_dwordx4 v[18:19], v[12:15], off offset:256 sc1
	s_and_saveexec_b64 s[2:3], vcc
	s_cbranch_execz .LBB0_1336
	v_lshl_add_u64 v[6:7], v[6:7], 2, s[18:19]
	s_waitcnt lgkmcnt(0)
	v_add_f32_e32 v5, v5, v10
	global_atomic_add_f32 v[6:7], v5, off
; __device__ __forceinline__ unsigned pkh(float lo, float hi) { f32x2 v = {lo, hi}; h16x2 h = __builtin_convertvector(v, h16x2); return __builtin_bit_cast(unsigned, h); }
; __device__ __forceinline__ unsigned pk8(float a, float b, float c, float d) { int w = __builtin_amdgcn_cvt_pk_fp8_f32(a, b, 0, false); w = __builtin_amdgcn_cvt_pk_fp8_f32(c, d, w, true); return (unsigned)w; }
;     __device__ __forceinline__ void operator()(f32x4 (&acc)[2][2][4][2], const Unit& u, const Order& S, int wr, int wc, int fr_, int fq_, LAS unsigned char*, int) const {
;     ...
;             for (int m = 0; m < 4; ++m) {
;                 const int row = row0 + ai * HALF + m * 16; const size_t off = (size_t)row * DM + col0;
;                 float sq = 0.f;
; #pragma unroll
;                 for (int bj = 0; bj < 2; ++bj) {
;                     const h16x8 bs = *(const h16x8*)(h16 + off + bj * HALF);
;                     f32x4 o0 = acc[ai][bj][m][0] * pre, o1 = acc[ai][bj][m][1] * pre;
; #pragma unroll
;                     for (int e = 0; e < 4; ++e) { o0[e] += (float)bs[e]; o1[e] += (float)bs[4 + e]; }
;                     if (out32) { if (!dry) { __builtin_nontemporal_store(o0, (f32x4*)(out32 + off + bj * HALF)); __builtin_nontemporal_store(o1, (f32x4*)(out32 + off + bj * HALF + 4)); } }
;                     else if (!dry) {
;                         sq += (o0[0] * o0[0] + o0[1] * o0[1]) + (o0[2] * o0[2] + o0[3] * o0[3]) + (o1[0] * o1[0] + o1[1] * o1[1]) + (o1[2] * o1[2] + o1[3] * o1[3]);
;                         u32x4 w; w.x = pkh(o0[0], o0[1]); w.y = pkh(o0[2], o0[3]); w.z = pkh(o1[0], o1[1]); w.w = pkh(o1[2], o1[3]);
;                         *(u32x4*)(h16 + off + bj * HALF) = w;
;                         if (h8) { u32x2 q; q.x = pk8(o0[0] * F8_SA, o0[1] * F8_SA, o0[2] * F8_SA, o0[3] * F8_SA); q.y = pk8(o1[0] * F8_SA, o1[1] * F8_SA, o1[2] * F8_SA, o1[3] * F8_SA); *(u32x2*)(h8 + off + bj * HALF) = q; } }
;                 }
;                 if (!out32 && !dry) { sq += __shfl_xor(sq, 16); sq += __shfl_xor(sq, 32); if (fq == 0) atomicAdd(ss_out + row, sq); }
.LBB0_1336:
	s_or_b64 exec, exec, s[2:3]
	v_add_u32_e32 v6, 0x90, v4
	v_ashrrev_i32_e32 v7, 31, v6
	s_waitcnt lgkmcnt(0)
	v_lshlrev_b64 v[10:11], 11, v[6:7]
	v_lshl_add_u64 v[10:11], s[90:91], 0, v[10:11]
	v_lshl_add_u64 v[18:19], v[2:3], 1, v[10:11]
	s_waitcnt vmcnt(15)
	v_cvt_f32_f16_e32 v20, v224
	v_cvt_f32_f16_sdwa v21, v224 dst_sel:DWORD dst_unused:UNUSED_PAD src0_sel:WORD_1
	v_cvt_f32_f16_e32 v10, v225
	v_cvt_f32_f16_sdwa v11, v225 dst_sel:DWORD dst_unused:UNUSED_PAD src0_sel:WORD_1
	s_waitcnt vmcnt(14)
	v_cvt_f32_f16_e32 v24, v228
	v_cvt_f32_f16_sdwa v25, v228 dst_sel:DWORD dst_unused:UNUSED_PAD src0_sel:WORD_1
	v_cvt_f32_f16_e32 v14, v229
	v_cvt_f32_f16_sdwa v15, v229 dst_sel:DWORD dst_unused:UNUSED_PAD src0_sel:WORD_1
	v_cvt_f32_f16_e32 v22, v226
	v_cvt_f32_f16_sdwa v23, v226 dst_sel:DWORD dst_unused:UNUSED_PAD src0_sel:WORD_1
	v_cvt_f32_f16_e32 v12, v227
	v_cvt_f32_f16_sdwa v13, v227 dst_sel:DWORD dst_unused:UNUSED_PAD src0_sel:WORD_1
	v_cvt_f32_f16_e32 v26, v230
	v_cvt_f32_f16_sdwa v27, v230 dst_sel:DWORD dst_unused:UNUSED_PAD src0_sel:WORD_1
	v_cvt_f32_f16_e32 v16, v231
	v_cvt_f32_f16_sdwa v17, v231 dst_sel:DWORD dst_unused:UNUSED_PAD src0_sel:WORD_1
	v_pk_fma_f32 v[20:21], v[78:79], s[12:13], v[20:21] op_sel_hi:[1,0,1]
	v_pk_fma_f32 v[28:29], v[80:81], s[12:13], v[10:11] op_sel_hi:[1,0,1]
	v_pk_fma_f32 v[24:25], v[70:71], s[12:13], v[24:25] op_sel_hi:[1,0,1]
	v_pk_fma_f32 v[14:15], v[72:73], s[12:13], v[14:15] op_sel_hi:[1,0,1]
	v_pk_fma_f32 v[22:23], v[74:75], s[12:13], v[22:23] op_sel_hi:[1,0,1]
	v_pk_fma_f32 v[30:31], v[76:77], s[12:13], v[12:13] op_sel_hi:[1,0,1]
	v_pk_fma_f32 v[26:27], v[66:67], s[12:13], v[26:27] op_sel_hi:[1,0,1]
	v_pk_mul_f32 v[12:13], v[20:21], v[20:21]
	v_pk_mul_f32 v[32:33], v[28:29], v[28:29]
	v_cvt_pk_f16_f32 v10, v20, v21
	v_cvt_pk_f16_f32 v11, v28, v29
	v_pk_mul_f32 v[20:21], v[24:25], v[24:25]
	v_pk_mul_f32 v[28:29], v[14:15], v[14:15]
	v_pk_fma_f32 v[16:17], v[68:69], s[12:13], v[16:17] op_sel_hi:[1,0,1]
	v_pk_mul_f32 v[66:67], v[22:23], v[22:23]
	v_pk_mul_f32 v[70:71], v[26:27], v[26:27]
	v_add_f32_e32 v5, v28, v29
	v_add_f32_e32 v20, v20, v21
	v_add_f32_e32 v29, v32, v33
	v_add_f32_e32 v12, v12, v13
	v_pk_mul_f32 v[68:69], v[30:31], v[30:31]
	v_pk_mul_f32 v[72:73], v[16:17], v[16:17]
	v_add_f32_e32 v21, v70, v71
	v_add_f32_e32 v13, v66, v67
	v_add_f32_e32 v5, v20, v5
	v_add_f32_e32 v12, v12, v29
	v_add_f32_e32 v28, v72, v73
	v_add_f32_e32 v32, v68, v69
	v_add_f32_e32 v5, v21, v5
	v_add_f32_e32 v12, v13, v12
	v_add_f32_e32 v5, v28, v5
	v_add_f32_e32 v12, v32, v12
	v_add_f32_e32 v5, v12, v5
	ds_bpermute_b32 v20, v8, v5
	v_cvt_pk_f16_f32 v12, v22, v23
	v_cvt_pk_f16_f32 v13, v30, v31
	global_store_dwordx4 v[18:19], v[10:13], off sc1
	s_waitcnt lgkmcnt(0)
	v_add_f32_e32 v5, v5, v20
	ds_bpermute_b32 v10, v9, v5
	v_cvt_pk_f16_f32 v12, v24, v25
	v_cvt_pk_f16_f32 v13, v14, v15
	v_cvt_pk_f16_f32 v14, v26, v27
	v_cvt_pk_f16_f32 v15, v16, v17
	global_store_dwordx4 v[18:19], v[12:15], off offset:256 sc1
	s_and_saveexec_b64 s[2:3], vcc
	s_cbranch_execz .LBB0_1338
	v_lshl_add_u64 v[6:7], v[6:7], 2, s[18:19]
	s_waitcnt lgkmcnt(0)
	v_add_f32_e32 v5, v5, v10
	global_atomic_add_f32 v[6:7], v5, off
; __device__ __forceinline__ unsigned pkh(float lo, float hi) { f32x2 v = {lo, hi}; h16x2 h = __builtin_convertvector(v, h16x2); return __builtin_bit_cast(unsigned, h); }
; __device__ __forceinline__ unsigned pk8(float a, float b, float c, float d) { int w = __builtin_amdgcn_cvt_pk_fp8_f32(a, b, 0, false); w = __builtin_amdgcn_cvt_pk_fp8_f32(c, d, w, true); return (unsigned)w; }
;     __device__ __forceinline__ void operator()(f32x4 (&acc)[2][2][4][2], const Unit& u, const Order& S, int wr, int wc, int fr_, int fq_, LAS unsigned char*, int) const {
;     ...
;             for (int m = 0; m < 4; ++m) {
;                 const int row = row0 + ai * HALF + m * 16; const size_t off = (size_t)row * DM + col0;
;                 float sq = 0.f;
; #pragma unroll
;                 for (int bj = 0; bj < 2; ++bj) {
;                     const h16x8 bs = *(const h16x8*)(h16 + off + bj * HALF);
;                     f32x4 o0 = acc[ai][bj][m][0] * pre, o1 = acc[ai][bj][m][1] * pre;
; #pragma unroll
;                     for (int e = 0; e < 4; ++e) { o0[e] += (float)bs[e]; o1[e] += (float)bs[4 + e]; }
;                     if (out32) { if (!dry) { __builtin_nontemporal_store(o0, (f32x4*)(out32 + off + bj * HALF)); __builtin_nontemporal_store(o1, (f32x4*)(out32 + off + bj * HALF + 4)); } }
;                     else if (!dry) {
;                         sq += (o0[0] * o0[0] + o0[1] * o0[1]) + (o0[2] * o0[2] + o0[3] * o0[3]) + (o1[0] * o1[0] + o1[1] * o1[1]) + (o1[2] * o1[2] + o1[3] * o1[3]);
;                         u32x4 w; w.x = pkh(o0[0], o0[1]); w.y = pkh(o0[2], o0[3]); w.z = pkh(o1[0], o1[1]); w.w = pkh(o1[2], o1[3]);
;                         *(u32x4*)(h16 + off + bj * HALF) = w;
;                         if (h8) { u32x2 q; q.x = pk8(o0[0] * F8_SA, o0[1] * F8_SA, o0[2] * F8_SA, o0[3] * F8_SA); q.y = pk8(o1[0] * F8_SA, o1[1] * F8_SA, o1[2] * F8_SA, o1[3] * F8_SA); *(u32x2*)(h8 + off + bj * HALF) = q; } }
;                 }
;                 if (!out32 && !dry) { sq += __shfl_xor(sq, 16); sq += __shfl_xor(sq, 32); if (fq == 0) atomicAdd(ss_out + row, sq); }
.LBB0_1338:
	s_or_b64 exec, exec, s[2:3]
	v_add_u32_e32 v6, 0xa0, v4
	v_ashrrev_i32_e32 v7, 31, v6
	s_waitcnt lgkmcnt(0)
	v_lshlrev_b64 v[10:11], 11, v[6:7]
	v_lshl_add_u64 v[10:11], s[90:91], 0, v[10:11]
	v_lshl_add_u64 v[18:19], v[2:3], 1, v[10:11]
	s_waitcnt vmcnt(15)
	v_cvt_f32_f16_e32 v20, v240
	v_cvt_f32_f16_sdwa v21, v240 dst_sel:DWORD dst_unused:UNUSED_PAD src0_sel:WORD_1
	v_cvt_f32_f16_e32 v10, v241
	v_cvt_f32_f16_sdwa v11, v241 dst_sel:DWORD dst_unused:UNUSED_PAD src0_sel:WORD_1
	s_waitcnt vmcnt(14)
	v_cvt_f32_f16_e32 v24, v244
	v_cvt_f32_f16_sdwa v25, v244 dst_sel:DWORD dst_unused:UNUSED_PAD src0_sel:WORD_1
	v_cvt_f32_f16_e32 v14, v245
	v_cvt_f32_f16_sdwa v15, v245 dst_sel:DWORD dst_unused:UNUSED_PAD src0_sel:WORD_1
	v_cvt_f32_f16_e32 v22, v242
	v_cvt_f32_f16_sdwa v23, v242 dst_sel:DWORD dst_unused:UNUSED_PAD src0_sel:WORD_1
	v_cvt_f32_f16_e32 v12, v243
	v_cvt_f32_f16_sdwa v13, v243 dst_sel:DWORD dst_unused:UNUSED_PAD src0_sel:WORD_1
	v_cvt_f32_f16_e32 v26, v246
	v_cvt_f32_f16_sdwa v27, v246 dst_sel:DWORD dst_unused:UNUSED_PAD src0_sel:WORD_1
	v_cvt_f32_f16_e32 v16, v247
	v_cvt_f32_f16_sdwa v17, v247 dst_sel:DWORD dst_unused:UNUSED_PAD src0_sel:WORD_1
	v_pk_fma_f32 v[20:21], v[62:63], s[12:13], v[20:21] op_sel_hi:[1,0,1]
	v_pk_fma_f32 v[28:29], v[64:65], s[12:13], v[10:11] op_sel_hi:[1,0,1]
	v_pk_fma_f32 v[24:25], v[54:55], s[12:13], v[24:25] op_sel_hi:[1,0,1]
	v_pk_fma_f32 v[14:15], v[56:57], s[12:13], v[14:15] op_sel_hi:[1,0,1]
	v_pk_fma_f32 v[22:23], v[58:59], s[12:13], v[22:23] op_sel_hi:[1,0,1]
	v_pk_fma_f32 v[30:31], v[60:61], s[12:13], v[12:13] op_sel_hi:[1,0,1]
	v_pk_fma_f32 v[26:27], v[50:51], s[12:13], v[26:27] op_sel_hi:[1,0,1]
	v_pk_mul_f32 v[12:13], v[20:21], v[20:21]
	v_pk_mul_f32 v[32:33], v[28:29], v[28:29]
	v_cvt_pk_f16_f32 v10, v20, v21
	v_cvt_pk_f16_f32 v11, v28, v29
	v_pk_mul_f32 v[20:21], v[24:25], v[24:25]
	v_pk_mul_f32 v[28:29], v[14:15], v[14:15]
	v_pk_fma_f32 v[16:17], v[52:53], s[12:13], v[16:17] op_sel_hi:[1,0,1]
	v_pk_mul_f32 v[50:51], v[22:23], v[22:23]
	v_pk_mul_f32 v[54:55], v[26:27], v[26:27]
	v_add_f32_e32 v5, v28, v29
	v_add_f32_e32 v20, v20, v21
	v_add_f32_e32 v29, v32, v33
	v_add_f32_e32 v12, v12, v13
	v_pk_mul_f32 v[52:53], v[30:31], v[30:31]
	v_pk_mul_f32 v[56:57], v[16:17], v[16:17]
	v_add_f32_e32 v21, v54, v55
	v_add_f32_e32 v13, v50, v51
	v_add_f32_e32 v5, v20, v5
	v_add_f32_e32 v12, v12, v29
	v_add_f32_e32 v28, v56, v57
	v_add_f32_e32 v32, v52, v53
	v_add_f32_e32 v5, v21, v5
	v_add_f32_e32 v12, v13, v12
	v_add_f32_e32 v5, v28, v5
	v_add_f32_e32 v12, v32, v12
	v_add_f32_e32 v5, v12, v5
	ds_bpermute_b32 v20, v8, v5
	v_cvt_pk_f16_f32 v12, v22, v23
	v_cvt_pk_f16_f32 v13, v30, v31
	global_store_dwordx4 v[18:19], v[10:13], off sc1
	s_waitcnt lgkmcnt(0)
	v_add_f32_e32 v5, v5, v20
	ds_bpermute_b32 v10, v9, v5
	v_cvt_pk_f16_f32 v12, v24, v25
	v_cvt_pk_f16_f32 v13, v14, v15
	v_cvt_pk_f16_f32 v14, v26, v27
	v_cvt_pk_f16_f32 v15, v16, v17
	global_store_dwordx4 v[18:19], v[12:15], off offset:256 sc1
	s_and_saveexec_b64 s[2:3], vcc
	s_cbranch_execz .LBB0_1340
	v_lshl_add_u64 v[6:7], v[6:7], 2, s[18:19]
	s_waitcnt lgkmcnt(0)
	v_add_f32_e32 v5, v5, v10
	global_atomic_add_f32 v[6:7], v5, off
.LBB0_1340:
	s_or_b64 exec, exec, s[2:3]
	v_add_u32_e32 v4, 0xb0, v4
	v_ashrrev_i32_e32 v5, 31, v4
	v_lshlrev_b64 v[6:7], 11, v[4:5]
	v_lshl_add_u64 v[6:7], s[90:91], 0, v[6:7]
	v_lshl_add_u64 v[18:19], v[2:3], 1, v[6:7]
	s_waitcnt lgkmcnt(0)
	s_waitcnt vmcnt(15)
	v_cvt_f32_f16_e32 v2, v248
	v_cvt_f32_f16_sdwa v3, v248 dst_sel:DWORD dst_unused:UNUSED_PAD src0_sel:WORD_1
	v_cvt_f32_f16_e32 v10, v249
	v_cvt_f32_f16_sdwa v11, v249 dst_sel:DWORD dst_unused:UNUSED_PAD src0_sel:WORD_1
	s_waitcnt vmcnt(14)
	v_cvt_f32_f16_e32 v20, v252
	v_cvt_f32_f16_sdwa v21, v252 dst_sel:DWORD dst_unused:UNUSED_PAD src0_sel:WORD_1
	v_cvt_f32_f16_e32 v14, v253
	v_cvt_f32_f16_sdwa v15, v253 dst_sel:DWORD dst_unused:UNUSED_PAD src0_sel:WORD_1
	v_cvt_f32_f16_e32 v6, v250
	v_cvt_f32_f16_sdwa v7, v250 dst_sel:DWORD dst_unused:UNUSED_PAD src0_sel:WORD_1
	v_cvt_f32_f16_e32 v12, v251
	v_cvt_f32_f16_sdwa v13, v251 dst_sel:DWORD dst_unused:UNUSED_PAD src0_sel:WORD_1
	v_cvt_f32_f16_e32 v22, v254
	v_cvt_f32_f16_sdwa v23, v254 dst_sel:DWORD dst_unused:UNUSED_PAD src0_sel:WORD_1
	v_cvt_f32_f16_e32 v16, v255
	v_cvt_f32_f16_sdwa v17, v255 dst_sel:DWORD dst_unused:UNUSED_PAD src0_sel:WORD_1
	v_pk_fma_f32 v[2:3], v[46:47], s[12:13], v[2:3] op_sel_hi:[1,0,1]
	v_pk_fma_f32 v[24:25], v[48:49], s[12:13], v[10:11] op_sel_hi:[1,0,1]
	v_pk_fma_f32 v[20:21], v[38:39], s[12:13], v[20:21] op_sel_hi:[1,0,1]
	v_pk_fma_f32 v[14:15], v[40:41], s[12:13], v[14:15] op_sel_hi:[1,0,1]
	v_pk_fma_f32 v[6:7], v[42:43], s[12:13], v[6:7] op_sel_hi:[1,0,1]
	v_pk_fma_f32 v[26:27], v[44:45], s[12:13], v[12:13] op_sel_hi:[1,0,1]
	v_pk_fma_f32 v[22:23], v[34:35], s[12:13], v[22:23] op_sel_hi:[1,0,1]
	v_pk_mul_f32 v[12:13], v[2:3], v[2:3]
	v_pk_mul_f32 v[28:29], v[24:25], v[24:25]
	v_cvt_pk_f16_f32 v10, v2, v3
	v_cvt_pk_f16_f32 v11, v24, v25
	v_pk_mul_f32 v[2:3], v[20:21], v[20:21]
	v_pk_mul_f32 v[24:25], v[14:15], v[14:15]
	v_pk_fma_f32 v[16:17], v[36:37], s[12:13], v[16:17] op_sel_hi:[1,0,1]
	v_pk_mul_f32 v[30:31], v[6:7], v[6:7]
	v_pk_mul_f32 v[34:35], v[22:23], v[22:23]
	v_add_f32_e32 v24, v24, v25
	v_add_f32_e32 v2, v2, v3
	v_add_f32_e32 v28, v28, v29
	v_add_f32_e32 v12, v12, v13
	v_pk_mul_f32 v[32:33], v[26:27], v[26:27]
	v_pk_mul_f32 v[36:37], v[16:17], v[16:17]
	v_add_f32_e32 v3, v34, v35
	v_add_f32_e32 v13, v30, v31
	v_add_f32_e32 v2, v2, v24
	v_add_f32_e32 v12, v12, v28
	v_add_f32_e32 v25, v36, v37
	v_add_f32_e32 v29, v32, v33
	v_add_f32_e32 v2, v3, v2
	v_add_f32_e32 v3, v13, v12
	v_add_f32_e32 v2, v25, v2
	v_add_f32_e32 v3, v29, v3
	v_add_f32_e32 v2, v3, v2
	ds_bpermute_b32 v3, v8, v2
	v_cvt_pk_f16_f32 v12, v6, v7
	v_cvt_pk_f16_f32 v13, v26, v27
	v_cvt_pk_f16_f32 v6, v20, v21
	v_cvt_pk_f16_f32 v7, v14, v15
	s_waitcnt lgkmcnt(0)
	v_add_f32_e32 v2, v2, v3
	ds_bpermute_b32 v3, v9, v2
	v_cvt_pk_f16_f32 v8, v22, v23
	v_cvt_pk_f16_f32 v9, v16, v17
	global_store_dwordx4 v[18:19], v[10:13], off sc1
	global_store_dwordx4 v[18:19], v[6:9], off offset:256 sc1
	s_and_saveexec_b64 s[2:3], vcc
	s_cbranch_execz .LBB0_1342
	v_lshl_add_u64 v[4:5], v[4:5], 2, s[18:19]
	s_waitcnt lgkmcnt(0)
	v_add_f32_e32 v2, v2, v3
	global_atomic_add_f32 v[4:5], v2, off

; #define PG8_WAIT_V(n) asm volatile("s_waitcnt vmcnt(" #n ")" ::: "memory")
; #define PG8_BAR __builtin_amdgcn_s_barrier()
; template <class Epi, bool ALIGN_EPI, bool FP8 = false>
; __device__ __forceinline__ void gemm_phase(LAS unsigned char* lds, LAS unsigned char* xl, const Gemm g, const Order& S, const Epi& E) {
;     ...
;     PG8_WAIT_V(0);
;     if constexpr (!ALIGN_EPI) { if (wr == 0) PG8_BAR; }
;     PG8_BAR;
.LBB0_1345:
	s_waitcnt vmcnt(16)
	s_barrier

;     __device__ __forceinline__ void operator()(f32x4 (&acc)[2][2][4][2], const Unit& u, const Order& S, int wr, int wc, int fr_, int fq_, LAS unsigned char*, int) const {
;     ...
;                 const int row = row0 + ai * HALF + m * 16; const size_t off = (size_t)row * DM + col0;
;                 float sq = 0.f;
; #pragma unroll
;                 for (int bj = 0; bj < 2; ++bj) {
;                     const h16x8 bs = *(const h16x8*)(h16 + off + bj * HALF);
;                     f32x4 o0 = acc[ai][bj][m][0] * pre, o1 = acc[ai][bj][m][1] * pre;
; #pragma unroll
;                     for (int e = 0; e < 4; ++e) { o0[e] += (float)bs[e]; o1[e] += (float)bs[4 + e]; }
;                     if (out32) { if (!dry) { __builtin_nontemporal_store(o0, (f32x4*)(out32 + off + bj * HALF)); __builtin_nontemporal_store(o1, (f32x4*)(out32 + off + bj * HALF + 4)); } }
.LBB0_1593:
	v_mov_b32_e32 v144, v153
	v_mov_b32_e32 v159, v152
	s_lshl_b32 s2, s39, 8
	s_add_i32 s2, s2, s50
	v_add_u32_e32 v144, s2, v144
	s_lshl_b32 s2, s38, 8
	s_or_b32 s2, s2, s51
	v_lshl_add_u32 v146, v159, 3, s2
	v_ashrrev_i32_e32 v145, 31, v144
	v_ashrrev_i32_e32 v147, 31, v146
	v_lshlrev_b64 v[148:149], 10, v[144:145]
	v_lshl_add_u64 v[146:147], v[148:149], 0, v[146:147]
	v_lshl_add_u64 v[148:149], v[146:147], 1, s[90:91]
	global_load_dwordx4 v[160:163], v[148:149], off
	s_mov_b32 s99, 0
	global_load_dwordx4 v[168:171], v[148:149], off offset:256
	s_mov_b32 s98, 0x8000
	v_lshl_add_u64 v[248:249], s[98:99], 0, v[148:149]
	global_load_dwordx4 v[172:175], v[248:249], off
	global_load_dwordx4 v[176:179], v[248:249], off offset:256
	s_mov_b32 s98, 0x10000
	v_lshl_add_u64 v[248:249], s[98:99], 0, v[148:149]
	global_load_dwordx4 v[180:183], v[248:249], off
	global_load_dwordx4 v[184:187], v[248:249], off offset:256
	s_mov_b32 s98, 0x18000
	v_lshl_add_u64 v[248:249], s[98:99], 0, v[148:149]
	global_load_dwordx4 v[188:191], v[248:249], off
	global_load_dwordx4 v[192:195], v[248:249], off offset:256
	s_mov_b32 s98, 0x40000
	v_lshl_add_u64 v[248:249], s[98:99], 0, v[148:149]
	global_load_dwordx4 v[196:199], v[248:249], off
	global_load_dwordx4 v[200:203], v[248:249], off offset:256
	s_mov_b32 s98, 0x48000
	v_lshl_add_u64 v[248:249], s[98:99], 0, v[148:149]
	global_load_dwordx4 v[204:207], v[248:249], off
	global_load_dwordx4 v[208:211], v[248:249], off offset:256
	s_mov_b32 s98, 0x50000
	v_lshl_add_u64 v[248:249], s[98:99], 0, v[148:149]
	global_load_dwordx4 v[212:215], v[248:249], off
	global_load_dwordx4 v[240:243], v[248:249], off offset:256
	s_mov_b32 s98, 0x58000
	v_lshl_add_u64 v[248:249], s[98:99], 0, v[148:149]
	global_load_dwordx4 v[244:247], v[248:249], off
	global_load_dwordx4 v[248:251], v[248:249], off offset:256
	v_mov_b32_e32 v150, v124
	v_mov_b32_e32 v124, v122
	v_cndmask_b32_e64 v122, 0, 1, s[12:13]
	v_mov_b32_e32 v151, v126
	v_mov_b32_e32 v126, v125
	v_mov_b32_e32 v125, v120
	v_mov_b32_e32 v120, v123
	v_cmp_ne_u32_e64 s[2:3], 1, v122
	s_mov_b64 s[4:5], -1
	s_andn2_b64 vcc, exec, s[12:13]
	s_waitcnt vmcnt(15)
	v_cvt_f32_f16_e32 v123, v161
	v_cvt_f32_f16_e32 v122, v160
	v_cvt_f32_f16_sdwa v161, v161 dst_sel:DWORD dst_unused:UNUSED_PAD src0_sel:WORD_1
	v_cvt_f32_f16_sdwa v160, v160 dst_sel:DWORD dst_unused:UNUSED_PAD src0_sel:WORD_1
	v_cvt_f32_f16_e32 v165, v162
	v_cvt_f32_f16_e32 v164, v163
	v_cvt_f32_f16_sdwa v167, v162 dst_sel:DWORD dst_unused:UNUSED_PAD src0_sel:WORD_1
	v_cvt_f32_f16_sdwa v166, v163 dst_sel:DWORD dst_unused:UNUSED_PAD src0_sel:WORD_1
	v_pk_add_f32 v[122:123], v[150:151], v[122:123]
	v_pk_add_f32 v[126:127], v[126:127], v[160:161]
	v_pk_add_f32 v[124:125], v[124:125], v[164:165]
	v_pk_add_f32 v[150:151], v[120:121], v[166:167]
	v_lshl_add_u64 v[120:121], v[146:147], 2, s[74:75]
	s_cbranch_vccnz .LBB0_1595
	v_mov_b32_e32 v160, v122
	v_mov_b32_e32 v161, v126
	v_mov_b32_e32 v162, v123
	v_mov_b32_e32 v163, v127
	global_store_dwordx4 v[120:121], v[160:163], off nt
	s_mov_b64 s[4:5], 0
	s_nop 0
	v_mov_b32_e32 v160, v125
	v_mov_b32_e32 v161, v151
	v_mov_b32_e32 v162, v124
	v_mov_b32_e32 v163, v150
	global_store_dwordx4 v[120:121], v[160:163], off offset:16 nt

;     __device__ __forceinline__ void operator()(f32x4 (&acc)[2][2][4][2], const Unit& u, const Order& S, int wr, int wc, int fr_, int fq_, LAS unsigned char*, int) const {
;     ...
;                 const int row = row0 + ai * HALF + m * 16; const size_t off = (size_t)row * DM + col0;
;                 float sq = 0.f;
; #pragma unroll
;                 for (int bj = 0; bj < 2; ++bj) {
;                     const h16x8 bs = *(const h16x8*)(h16 + off + bj * HALF);
;                     f32x4 o0 = acc[ai][bj][m][0] * pre, o1 = acc[ai][bj][m][1] * pre;
; #pragma unroll
;                     for (int e = 0; e < 4; ++e) { o0[e] += (float)bs[e]; o1[e] += (float)bs[4 + e]; }
;                     if (out32) { if (!dry) { __builtin_nontemporal_store(o0, (f32x4*)(out32 + off + bj * HALF)); __builtin_nontemporal_store(o1, (f32x4*)(out32 + off + bj * HALF + 4)); } }
.LBB0_1597:
	v_mov_b32_e32 v126, v116
	v_mov_b32_e32 v127, v118
	v_mov_b32_e32 v118, v117
	v_mov_b32_e32 v116, v114
	v_mov_b32_e32 v117, v112
	v_mov_b32_e32 v112, v115
	s_and_b64 vcc, exec, s[2:3]
	s_mov_b64 s[4:5], -1
	s_waitcnt vmcnt(15)
	v_cvt_f32_f16_e32 v115, v169
	v_cvt_f32_f16_e32 v114, v168
	v_cvt_f32_f16_sdwa v123, v169 dst_sel:DWORD dst_unused:UNUSED_PAD src0_sel:WORD_1
	v_cvt_f32_f16_sdwa v122, v168 dst_sel:DWORD dst_unused:UNUSED_PAD src0_sel:WORD_1
	v_cvt_f32_f16_e32 v151, v170
	v_cvt_f32_f16_e32 v150, v171
	v_cvt_f32_f16_sdwa v163, v170 dst_sel:DWORD dst_unused:UNUSED_PAD src0_sel:WORD_1
	v_cvt_f32_f16_sdwa v162, v171 dst_sel:DWORD dst_unused:UNUSED_PAD src0_sel:WORD_1
	v_pk_add_f32 v[114:115], v[126:127], v[114:115]
	v_pk_add_f32 v[118:119], v[118:119], v[122:123]
	v_pk_add_f32 v[116:117], v[116:117], v[150:151]
	v_pk_add_f32 v[112:113], v[112:113], v[162:163]
	s_cbranch_vccnz .LBB0_1599
	v_mov_b32_e32 v122, v114
	v_mov_b32_e32 v123, v118
	v_mov_b32_e32 v124, v115
	v_mov_b32_e32 v125, v119
	global_store_dwordx4 v[120:121], v[122:125], off offset:512 nt
	s_mov_b64 s[4:5], 0
	s_nop 0
	v_mov_b32_e32 v122, v117
	v_mov_b32_e32 v123, v113
	v_mov_b32_e32 v124, v116
	v_mov_b32_e32 v125, v112
	global_store_dwordx4 v[120:121], v[122:125], off offset:528 nt

;     __device__ __forceinline__ void operator()(f32x4 (&acc)[2][2][4][2], const Unit& u, const Order& S, int wr, int wc, int fr_, int fq_, LAS unsigned char*, int) const {
;     ...
;                 const int row = row0 + ai * HALF + m * 16; const size_t off = (size_t)row * DM + col0;
;                 float sq = 0.f;
; #pragma unroll
;                 for (int bj = 0; bj < 2; ++bj) {
;                     const h16x8 bs = *(const h16x8*)(h16 + off + bj * HALF);
;                     f32x4 o0 = acc[ai][bj][m][0] * pre, o1 = acc[ai][bj][m][1] * pre;
; #pragma unroll
;                     for (int e = 0; e < 4; ++e) { o0[e] += (float)bs[e]; o1[e] += (float)bs[4 + e]; }
;                     if (out32) { if (!dry) { __builtin_nontemporal_store(o0, (f32x4*)(out32 + off + bj * HALF)); __builtin_nontemporal_store(o1, (f32x4*)(out32 + off + bj * HALF + 4)); } }
.LBB0_1605:
	v_lshl_add_u64 v[118:119], v[146:147], 0, s[18:19]
	s_waitcnt lgkmcnt(0)
	v_lshl_add_u64 v[112:113], v[118:119], 1, s[90:91]
	v_mov_b32_e32 v120, v108
	v_mov_b32_e32 v121, v110
	v_mov_b32_e32 v110, v109
	v_mov_b32_e32 v108, v106
	v_mov_b32_e32 v109, v104
	v_mov_b32_e32 v104, v107
	s_mov_b64 s[38:39], -1
	s_and_b64 vcc, exec, s[2:3]
	s_waitcnt vmcnt(15)
	v_cvt_f32_f16_e32 v107, v173
	v_cvt_f32_f16_e32 v106, v172
	v_cvt_f32_f16_sdwa v115, v173 dst_sel:DWORD dst_unused:UNUSED_PAD src0_sel:WORD_1
	v_cvt_f32_f16_sdwa v114, v172 dst_sel:DWORD dst_unused:UNUSED_PAD src0_sel:WORD_1
	v_cvt_f32_f16_e32 v123, v174
	v_cvt_f32_f16_e32 v122, v175
	v_cvt_f32_f16_sdwa v125, v174 dst_sel:DWORD dst_unused:UNUSED_PAD src0_sel:WORD_1
	v_cvt_f32_f16_sdwa v124, v175 dst_sel:DWORD dst_unused:UNUSED_PAD src0_sel:WORD_1
	v_pk_add_f32 v[106:107], v[120:121], v[106:107]
	v_pk_add_f32 v[110:111], v[110:111], v[114:115]
	v_pk_add_f32 v[108:109], v[108:109], v[122:123]
	v_pk_add_f32 v[114:115], v[104:105], v[124:125]
	v_lshl_add_u64 v[104:105], v[118:119], 2, s[74:75]
	s_cbranch_vccnz .LBB0_1607
	v_mov_b32_e32 v116, v106
	v_mov_b32_e32 v117, v110
	v_mov_b32_e32 v118, v107
	v_mov_b32_e32 v119, v111
	global_store_dwordx4 v[104:105], v[116:119], off nt
	s_mov_b64 s[38:39], 0
	s_nop 0
	v_mov_b32_e32 v116, v109
	v_mov_b32_e32 v117, v115
	v_mov_b32_e32 v118, v108
	v_mov_b32_e32 v119, v114
	global_store_dwordx4 v[104:105], v[116:119], off offset:16 nt

;     __device__ __forceinline__ void operator()(f32x4 (&acc)[2][2][4][2], const Unit& u, const Order& S, int wr, int wc, int fr_, int fq_, LAS unsigned char*, int) const {
;     ...
;                 const int row = row0 + ai * HALF + m * 16; const size_t off = (size_t)row * DM + col0;
;                 float sq = 0.f;
; #pragma unroll
;                 for (int bj = 0; bj < 2; ++bj) {
;                     const h16x8 bs = *(const h16x8*)(h16 + off + bj * HALF);
;                     f32x4 o0 = acc[ai][bj][m][0] * pre, o1 = acc[ai][bj][m][1] * pre;
; #pragma unroll
;                     for (int e = 0; e < 4; ++e) { o0[e] += (float)bs[e]; o1[e] += (float)bs[4 + e]; }
;                     if (out32) { if (!dry) { __builtin_nontemporal_store(o0, (f32x4*)(out32 + off + bj * HALF)); __builtin_nontemporal_store(o1, (f32x4*)(out32 + off + bj * HALF + 4)); } }
.LBB0_1609:
	v_mov_b32_e32 v110, v100
	v_mov_b32_e32 v111, v102
	v_mov_b32_e32 v102, v101
	v_mov_b32_e32 v100, v98
	v_mov_b32_e32 v101, v96
	v_mov_b32_e32 v96, v99
	s_and_b64 vcc, exec, s[2:3]
	s_mov_b64 s[38:39], -1
	s_waitcnt vmcnt(15)
	v_cvt_f32_f16_e32 v99, v177
	v_cvt_f32_f16_e32 v98, v176
	v_cvt_f32_f16_sdwa v107, v177 dst_sel:DWORD dst_unused:UNUSED_PAD src0_sel:WORD_1
	v_cvt_f32_f16_sdwa v106, v176 dst_sel:DWORD dst_unused:UNUSED_PAD src0_sel:WORD_1
	v_cvt_f32_f16_e32 v115, v178
	v_cvt_f32_f16_e32 v114, v179
	v_cvt_f32_f16_sdwa v119, v178 dst_sel:DWORD dst_unused:UNUSED_PAD src0_sel:WORD_1
	v_cvt_f32_f16_sdwa v118, v179 dst_sel:DWORD dst_unused:UNUSED_PAD src0_sel:WORD_1
	v_pk_add_f32 v[98:99], v[110:111], v[98:99]
	v_pk_add_f32 v[102:103], v[102:103], v[106:107]
	v_pk_add_f32 v[100:101], v[100:101], v[114:115]
	v_pk_add_f32 v[96:97], v[96:97], v[118:119]
	s_cbranch_vccz .LBB0_1612
	s_andn2_b64 vcc, exec, s[38:39]
	s_cbranch_vccz .LBB0_1613

;     __device__ __forceinline__ void operator()(f32x4 (&acc)[2][2][4][2], const Unit& u, const Order& S, int wr, int wc, int fr_, int fq_, LAS unsigned char*, int) const {
;     ...
;                 const int row = row0 + ai * HALF + m * 16; const size_t off = (size_t)row * DM + col0;
;                 float sq = 0.f;
; #pragma unroll
;                 for (int bj = 0; bj < 2; ++bj) {
;                     const h16x8 bs = *(const h16x8*)(h16 + off + bj * HALF);
;                     f32x4 o0 = acc[ai][bj][m][0] * pre, o1 = acc[ai][bj][m][1] * pre;
; #pragma unroll
;                     for (int e = 0; e < 4; ++e) { o0[e] += (float)bs[e]; o1[e] += (float)bs[4 + e]; }
;                     if (out32) { if (!dry) { __builtin_nontemporal_store(o0, (f32x4*)(out32 + off + bj * HALF)); __builtin_nontemporal_store(o1, (f32x4*)(out32 + off + bj * HALF + 4)); } }
.LBB0_1617:
	v_lshl_add_u64 v[102:103], v[146:147], 0, s[20:21]
	s_waitcnt lgkmcnt(0)
	v_lshl_add_u64 v[96:97], v[102:103], 1, s[90:91]
	v_mov_b32_e32 v104, v92
	v_mov_b32_e32 v105, v94
	v_mov_b32_e32 v94, v93
	v_mov_b32_e32 v92, v90
	v_mov_b32_e32 v93, v88
	v_mov_b32_e32 v88, v91
	s_mov_b64 s[38:39], -1
	s_and_b64 vcc, exec, s[2:3]
	s_waitcnt vmcnt(15)
	v_cvt_f32_f16_e32 v91, v181
	v_cvt_f32_f16_e32 v90, v180
	v_cvt_f32_f16_sdwa v99, v181 dst_sel:DWORD dst_unused:UNUSED_PAD src0_sel:WORD_1
	v_cvt_f32_f16_sdwa v98, v180 dst_sel:DWORD dst_unused:UNUSED_PAD src0_sel:WORD_1
	v_cvt_f32_f16_e32 v107, v182
	v_cvt_f32_f16_e32 v106, v183
	v_cvt_f32_f16_sdwa v109, v182 dst_sel:DWORD dst_unused:UNUSED_PAD src0_sel:WORD_1
	v_cvt_f32_f16_sdwa v108, v183 dst_sel:DWORD dst_unused:UNUSED_PAD src0_sel:WORD_1
	v_pk_add_f32 v[90:91], v[104:105], v[90:91]
	v_pk_add_f32 v[94:95], v[94:95], v[98:99]
	v_pk_add_f32 v[92:93], v[92:93], v[106:107]
	v_pk_add_f32 v[98:99], v[88:89], v[108:109]
	v_lshl_add_u64 v[88:89], v[102:103], 2, s[74:75]
	s_cbranch_vccnz .LBB0_1619
	v_mov_b32_e32 v100, v90
	v_mov_b32_e32 v101, v94
	v_mov_b32_e32 v102, v91
	v_mov_b32_e32 v103, v95
	global_store_dwordx4 v[88:89], v[100:103], off nt
	s_mov_b64 s[38:39], 0
	s_nop 0
	v_mov_b32_e32 v100, v93
	v_mov_b32_e32 v101, v99
	v_mov_b32_e32 v102, v92
	v_mov_b32_e32 v103, v98
	global_store_dwordx4 v[88:89], v[100:103], off offset:16 nt

;     __device__ __forceinline__ void operator()(f32x4 (&acc)[2][2][4][2], const Unit& u, const Order& S, int wr, int wc, int fr_, int fq_, LAS unsigned char*, int) const {
;     ...
;                 const int row = row0 + ai * HALF + m * 16; const size_t off = (size_t)row * DM + col0;
;                 float sq = 0.f;
; #pragma unroll
;                 for (int bj = 0; bj < 2; ++bj) {
;                     const h16x8 bs = *(const h16x8*)(h16 + off + bj * HALF);
;                     f32x4 o0 = acc[ai][bj][m][0] * pre, o1 = acc[ai][bj][m][1] * pre;
; #pragma unroll
;                     for (int e = 0; e < 4; ++e) { o0[e] += (float)bs[e]; o1[e] += (float)bs[4 + e]; }
;                     if (out32) { if (!dry) { __builtin_nontemporal_store(o0, (f32x4*)(out32 + off + bj * HALF)); __builtin_nontemporal_store(o1, (f32x4*)(out32 + off + bj * HALF + 4)); } }
.LBB0_1621:
	v_mov_b32_e32 v94, v84
	v_mov_b32_e32 v95, v86
	v_mov_b32_e32 v86, v85
	v_mov_b32_e32 v84, v82
	v_mov_b32_e32 v85, v80
	v_mov_b32_e32 v80, v83
	s_and_b64 vcc, exec, s[2:3]
	s_mov_b64 s[38:39], -1
	s_waitcnt vmcnt(15)
	v_cvt_f32_f16_e32 v83, v185
	v_cvt_f32_f16_e32 v82, v184
	v_cvt_f32_f16_sdwa v91, v185 dst_sel:DWORD dst_unused:UNUSED_PAD src0_sel:WORD_1
	v_cvt_f32_f16_sdwa v90, v184 dst_sel:DWORD dst_unused:UNUSED_PAD src0_sel:WORD_1
	v_cvt_f32_f16_e32 v99, v186
	v_cvt_f32_f16_e32 v98, v187
	v_cvt_f32_f16_sdwa v103, v186 dst_sel:DWORD dst_unused:UNUSED_PAD src0_sel:WORD_1
	v_cvt_f32_f16_sdwa v102, v187 dst_sel:DWORD dst_unused:UNUSED_PAD src0_sel:WORD_1
	v_pk_add_f32 v[82:83], v[94:95], v[82:83]
	v_pk_add_f32 v[86:87], v[86:87], v[90:91]
	v_pk_add_f32 v[84:85], v[84:85], v[98:99]
	v_pk_add_f32 v[80:81], v[80:81], v[102:103]
	s_cbranch_vccz .LBB0_1624
	s_andn2_b64 vcc, exec, s[38:39]
	s_cbranch_vccz .LBB0_1625

;     __device__ __forceinline__ void operator()(f32x4 (&acc)[2][2][4][2], const Unit& u, const Order& S, int wr, int wc, int fr_, int fq_, LAS unsigned char*, int) const {
;     ...
;                 const int row = row0 + ai * HALF + m * 16; const size_t off = (size_t)row * DM + col0;
;                 float sq = 0.f;
; #pragma unroll
;                 for (int bj = 0; bj < 2; ++bj) {
;                     const h16x8 bs = *(const h16x8*)(h16 + off + bj * HALF);
;                     f32x4 o0 = acc[ai][bj][m][0] * pre, o1 = acc[ai][bj][m][1] * pre;
; #pragma unroll
;                     for (int e = 0; e < 4; ++e) { o0[e] += (float)bs[e]; o1[e] += (float)bs[4 + e]; }
;                     if (out32) { if (!dry) { __builtin_nontemporal_store(o0, (f32x4*)(out32 + off + bj * HALF)); __builtin_nontemporal_store(o1, (f32x4*)(out32 + off + bj * HALF + 4)); } }
.LBB0_1629:
	v_lshl_add_u64 v[86:87], v[146:147], 0, s[22:23]
	s_waitcnt lgkmcnt(0)
	v_lshl_add_u64 v[80:81], v[86:87], 1, s[90:91]
	v_mov_b32_e32 v88, v76
	v_mov_b32_e32 v89, v78
	v_mov_b32_e32 v78, v77
	v_mov_b32_e32 v76, v74
	v_mov_b32_e32 v77, v72
	v_mov_b32_e32 v72, v75
	s_mov_b64 s[38:39], -1
	s_and_b64 vcc, exec, s[2:3]
	s_waitcnt vmcnt(15)
	v_cvt_f32_f16_e32 v75, v189
	v_cvt_f32_f16_e32 v74, v188
	v_cvt_f32_f16_sdwa v83, v189 dst_sel:DWORD dst_unused:UNUSED_PAD src0_sel:WORD_1
	v_cvt_f32_f16_sdwa v82, v188 dst_sel:DWORD dst_unused:UNUSED_PAD src0_sel:WORD_1
	v_cvt_f32_f16_e32 v91, v190
	v_cvt_f32_f16_e32 v90, v191
	v_cvt_f32_f16_sdwa v93, v190 dst_sel:DWORD dst_unused:UNUSED_PAD src0_sel:WORD_1
	v_cvt_f32_f16_sdwa v92, v191 dst_sel:DWORD dst_unused:UNUSED_PAD src0_sel:WORD_1
	v_pk_add_f32 v[74:75], v[88:89], v[74:75]
	v_pk_add_f32 v[78:79], v[78:79], v[82:83]
	v_pk_add_f32 v[76:77], v[76:77], v[90:91]
	v_pk_add_f32 v[82:83], v[72:73], v[92:93]
	v_lshl_add_u64 v[72:73], v[86:87], 2, s[74:75]
	s_cbranch_vccnz .LBB0_1631
	v_mov_b32_e32 v84, v74
	v_mov_b32_e32 v85, v78
	v_mov_b32_e32 v86, v75
	v_mov_b32_e32 v87, v79
	global_store_dwordx4 v[72:73], v[84:87], off nt
	s_mov_b64 s[38:39], 0
	s_nop 0
	v_mov_b32_e32 v84, v77
	v_mov_b32_e32 v85, v83
	v_mov_b32_e32 v86, v76
	v_mov_b32_e32 v87, v82
	global_store_dwordx4 v[72:73], v[84:87], off offset:16 nt

;     __device__ __forceinline__ void operator()(f32x4 (&acc)[2][2][4][2], const Unit& u, const Order& S, int wr, int wc, int fr_, int fq_, LAS unsigned char*, int) const {
;     ...
;                 const int row = row0 + ai * HALF + m * 16; const size_t off = (size_t)row * DM + col0;
;                 float sq = 0.f;
; #pragma unroll
;                 for (int bj = 0; bj < 2; ++bj) {
;                     const h16x8 bs = *(const h16x8*)(h16 + off + bj * HALF);
;                     f32x4 o0 = acc[ai][bj][m][0] * pre, o1 = acc[ai][bj][m][1] * pre;
; #pragma unroll
;                     for (int e = 0; e < 4; ++e) { o0[e] += (float)bs[e]; o1[e] += (float)bs[4 + e]; }
;                     if (out32) { if (!dry) { __builtin_nontemporal_store(o0, (f32x4*)(out32 + off + bj * HALF)); __builtin_nontemporal_store(o1, (f32x4*)(out32 + off + bj * HALF + 4)); } }
.LBB0_1633:
	v_mov_b32_e32 v78, v68
	v_mov_b32_e32 v79, v70
	v_mov_b32_e32 v70, v69
	v_mov_b32_e32 v68, v66
	v_mov_b32_e32 v69, v64
	v_mov_b32_e32 v64, v67
	s_and_b64 vcc, exec, s[2:3]
	s_mov_b64 s[38:39], -1
	s_waitcnt vmcnt(15)
	v_cvt_f32_f16_e32 v67, v193
	v_cvt_f32_f16_e32 v66, v192
	v_cvt_f32_f16_sdwa v75, v193 dst_sel:DWORD dst_unused:UNUSED_PAD src0_sel:WORD_1
	v_cvt_f32_f16_sdwa v74, v192 dst_sel:DWORD dst_unused:UNUSED_PAD src0_sel:WORD_1
	v_cvt_f32_f16_e32 v83, v194
	v_cvt_f32_f16_e32 v82, v195
	v_cvt_f32_f16_sdwa v87, v194 dst_sel:DWORD dst_unused:UNUSED_PAD src0_sel:WORD_1
	v_cvt_f32_f16_sdwa v86, v195 dst_sel:DWORD dst_unused:UNUSED_PAD src0_sel:WORD_1
	v_pk_add_f32 v[66:67], v[78:79], v[66:67]
	v_pk_add_f32 v[70:71], v[70:71], v[74:75]
	v_pk_add_f32 v[68:69], v[68:69], v[82:83]
	v_pk_add_f32 v[64:65], v[64:65], v[86:87]
	s_cbranch_vccz .LBB0_1636
	s_andn2_b64 vcc, exec, s[38:39]
	s_cbranch_vccz .LBB0_1637

;     __device__ __forceinline__ void operator()(f32x4 (&acc)[2][2][4][2], const Unit& u, const Order& S, int wr, int wc, int fr_, int fq_, LAS unsigned char*, int) const {
;     ...
;                 const int row = row0 + ai * HALF + m * 16; const size_t off = (size_t)row * DM + col0;
;                 float sq = 0.f;
; #pragma unroll
;                 for (int bj = 0; bj < 2; ++bj) {
;                     const h16x8 bs = *(const h16x8*)(h16 + off + bj * HALF);
;                     f32x4 o0 = acc[ai][bj][m][0] * pre, o1 = acc[ai][bj][m][1] * pre;
; #pragma unroll
;                     for (int e = 0; e < 4; ++e) { o0[e] += (float)bs[e]; o1[e] += (float)bs[4 + e]; }
;                     if (out32) { if (!dry) { __builtin_nontemporal_store(o0, (f32x4*)(out32 + off + bj * HALF)); __builtin_nontemporal_store(o1, (f32x4*)(out32 + off + bj * HALF + 4)); } }
.LBB0_1641:
	v_lshl_add_u64 v[70:71], v[146:147], 0, s[24:25]
	s_waitcnt lgkmcnt(0)
	v_lshl_add_u64 v[64:65], v[70:71], 1, s[90:91]
	v_mov_b32_e32 v72, v60
	v_mov_b32_e32 v73, v62
	v_mov_b32_e32 v62, v61
	v_mov_b32_e32 v60, v58
	v_mov_b32_e32 v61, v56
	v_mov_b32_e32 v56, v59
	s_mov_b64 s[38:39], -1
	s_and_b64 vcc, exec, s[2:3]
	s_waitcnt vmcnt(15)
	v_cvt_f32_f16_e32 v59, v197
	v_cvt_f32_f16_e32 v58, v196
	v_cvt_f32_f16_sdwa v67, v197 dst_sel:DWORD dst_unused:UNUSED_PAD src0_sel:WORD_1
	v_cvt_f32_f16_sdwa v66, v196 dst_sel:DWORD dst_unused:UNUSED_PAD src0_sel:WORD_1
	v_cvt_f32_f16_e32 v75, v198
	v_cvt_f32_f16_e32 v74, v199
	v_cvt_f32_f16_sdwa v77, v198 dst_sel:DWORD dst_unused:UNUSED_PAD src0_sel:WORD_1
	v_cvt_f32_f16_sdwa v76, v199 dst_sel:DWORD dst_unused:UNUSED_PAD src0_sel:WORD_1
	v_pk_add_f32 v[58:59], v[72:73], v[58:59]
	v_pk_add_f32 v[62:63], v[62:63], v[66:67]
	v_pk_add_f32 v[60:61], v[60:61], v[74:75]
	v_pk_add_f32 v[66:67], v[56:57], v[76:77]
	v_lshl_add_u64 v[56:57], v[70:71], 2, s[74:75]
	s_cbranch_vccnz .LBB0_1643
	v_mov_b32_e32 v68, v58
	v_mov_b32_e32 v69, v62
	v_mov_b32_e32 v70, v59
	v_mov_b32_e32 v71, v63
	global_store_dwordx4 v[56:57], v[68:71], off nt
	s_mov_b64 s[38:39], 0
	s_nop 0
	v_mov_b32_e32 v68, v61
	v_mov_b32_e32 v69, v67
	v_mov_b32_e32 v70, v60
	v_mov_b32_e32 v71, v66
	global_store_dwordx4 v[56:57], v[68:71], off offset:16 nt

;     __device__ __forceinline__ void operator()(f32x4 (&acc)[2][2][4][2], const Unit& u, const Order& S, int wr, int wc, int fr_, int fq_, LAS unsigned char*, int) const {
;     ...
;                 const int row = row0 + ai * HALF + m * 16; const size_t off = (size_t)row * DM + col0;
;                 float sq = 0.f;
; #pragma unroll
;                 for (int bj = 0; bj < 2; ++bj) {
;                     const h16x8 bs = *(const h16x8*)(h16 + off + bj * HALF);
;                     f32x4 o0 = acc[ai][bj][m][0] * pre, o1 = acc[ai][bj][m][1] * pre;
; #pragma unroll
;                     for (int e = 0; e < 4; ++e) { o0[e] += (float)bs[e]; o1[e] += (float)bs[4 + e]; }
;                     if (out32) { if (!dry) { __builtin_nontemporal_store(o0, (f32x4*)(out32 + off + bj * HALF)); __builtin_nontemporal_store(o1, (f32x4*)(out32 + off + bj * HALF + 4)); } }
.LBB0_1645:
	v_mov_b32_e32 v62, v52
	v_mov_b32_e32 v63, v54
	v_mov_b32_e32 v54, v53
	v_mov_b32_e32 v52, v50
	v_mov_b32_e32 v53, v48
	v_mov_b32_e32 v48, v51
	s_and_b64 vcc, exec, s[2:3]
	s_mov_b64 s[38:39], -1
	s_waitcnt vmcnt(15)
	v_cvt_f32_f16_e32 v51, v201
	v_cvt_f32_f16_e32 v50, v200
	v_cvt_f32_f16_sdwa v59, v201 dst_sel:DWORD dst_unused:UNUSED_PAD src0_sel:WORD_1
	v_cvt_f32_f16_sdwa v58, v200 dst_sel:DWORD dst_unused:UNUSED_PAD src0_sel:WORD_1
	v_cvt_f32_f16_e32 v67, v202
	v_cvt_f32_f16_e32 v66, v203
	v_cvt_f32_f16_sdwa v71, v202 dst_sel:DWORD dst_unused:UNUSED_PAD src0_sel:WORD_1
	v_cvt_f32_f16_sdwa v70, v203 dst_sel:DWORD dst_unused:UNUSED_PAD src0_sel:WORD_1
	v_pk_add_f32 v[50:51], v[62:63], v[50:51]
	v_pk_add_f32 v[54:55], v[54:55], v[58:59]
	v_pk_add_f32 v[52:53], v[52:53], v[66:67]
	v_pk_add_f32 v[48:49], v[48:49], v[70:71]
	s_cbranch_vccz .LBB0_1648
	s_andn2_b64 vcc, exec, s[38:39]
	s_cbranch_vccz .LBB0_1649

;     __device__ __forceinline__ void operator()(f32x4 (&acc)[2][2][4][2], const Unit& u, const Order& S, int wr, int wc, int fr_, int fq_, LAS unsigned char*, int) const {
;     ...
;                 const int row = row0 + ai * HALF + m * 16; const size_t off = (size_t)row * DM + col0;
;                 float sq = 0.f;
; #pragma unroll
;                 for (int bj = 0; bj < 2; ++bj) {
;                     const h16x8 bs = *(const h16x8*)(h16 + off + bj * HALF);
;                     f32x4 o0 = acc[ai][bj][m][0] * pre, o1 = acc[ai][bj][m][1] * pre;
; #pragma unroll
;                     for (int e = 0; e < 4; ++e) { o0[e] += (float)bs[e]; o1[e] += (float)bs[4 + e]; }
;                     if (out32) { if (!dry) { __builtin_nontemporal_store(o0, (f32x4*)(out32 + off + bj * HALF)); __builtin_nontemporal_store(o1, (f32x4*)(out32 + off + bj * HALF + 4)); } }
.LBB0_1653:
	v_lshl_add_u64 v[54:55], v[146:147], 0, s[26:27]
	s_waitcnt lgkmcnt(0)
	v_lshl_add_u64 v[48:49], v[54:55], 1, s[90:91]
	v_mov_b32_e32 v56, v44
	v_mov_b32_e32 v57, v46
	v_mov_b32_e32 v46, v45
	v_mov_b32_e32 v44, v42
	v_mov_b32_e32 v45, v40
	v_mov_b32_e32 v40, v43
	s_mov_b64 s[38:39], -1
	s_and_b64 vcc, exec, s[2:3]
	s_waitcnt vmcnt(15)
	v_cvt_f32_f16_e32 v43, v205
	v_cvt_f32_f16_e32 v42, v204
	v_cvt_f32_f16_sdwa v51, v205 dst_sel:DWORD dst_unused:UNUSED_PAD src0_sel:WORD_1
	v_cvt_f32_f16_sdwa v50, v204 dst_sel:DWORD dst_unused:UNUSED_PAD src0_sel:WORD_1
	v_cvt_f32_f16_e32 v59, v206
	v_cvt_f32_f16_e32 v58, v207
	v_cvt_f32_f16_sdwa v61, v206 dst_sel:DWORD dst_unused:UNUSED_PAD src0_sel:WORD_1
	v_cvt_f32_f16_sdwa v60, v207 dst_sel:DWORD dst_unused:UNUSED_PAD src0_sel:WORD_1
	v_pk_add_f32 v[42:43], v[56:57], v[42:43]
	v_pk_add_f32 v[46:47], v[46:47], v[50:51]
	v_pk_add_f32 v[44:45], v[44:45], v[58:59]
	v_pk_add_f32 v[50:51], v[40:41], v[60:61]
	v_lshl_add_u64 v[40:41], v[54:55], 2, s[74:75]
	s_cbranch_vccnz .LBB0_1655
	v_mov_b32_e32 v52, v42
	v_mov_b32_e32 v53, v46
	v_mov_b32_e32 v54, v43
	v_mov_b32_e32 v55, v47
	global_store_dwordx4 v[40:41], v[52:55], off nt
	s_mov_b64 s[38:39], 0
	s_nop 0
	v_mov_b32_e32 v52, v45
	v_mov_b32_e32 v53, v51
	v_mov_b32_e32 v54, v44
	v_mov_b32_e32 v55, v50
	global_store_dwordx4 v[40:41], v[52:55], off offset:16 nt

;     __device__ __forceinline__ void operator()(f32x4 (&acc)[2][2][4][2], const Unit& u, const Order& S, int wr, int wc, int fr_, int fq_, LAS unsigned char*, int) const {
;     ...
;                 const int row = row0 + ai * HALF + m * 16; const size_t off = (size_t)row * DM + col0;
;                 float sq = 0.f;
; #pragma unroll
;                 for (int bj = 0; bj < 2; ++bj) {
;                     const h16x8 bs = *(const h16x8*)(h16 + off + bj * HALF);
;                     f32x4 o0 = acc[ai][bj][m][0] * pre, o1 = acc[ai][bj][m][1] * pre;
; #pragma unroll
;                     for (int e = 0; e < 4; ++e) { o0[e] += (float)bs[e]; o1[e] += (float)bs[4 + e]; }
;                     if (out32) { if (!dry) { __builtin_nontemporal_store(o0, (f32x4*)(out32 + off + bj * HALF)); __builtin_nontemporal_store(o1, (f32x4*)(out32 + off + bj * HALF + 4)); } }
.LBB0_1657:
	v_mov_b32_e32 v46, v36
	v_mov_b32_e32 v47, v38
	v_mov_b32_e32 v38, v37
	v_mov_b32_e32 v36, v34
	v_mov_b32_e32 v37, v32
	v_mov_b32_e32 v32, v35
	s_and_b64 vcc, exec, s[2:3]
	s_mov_b64 s[38:39], -1
	s_waitcnt vmcnt(15)
	v_cvt_f32_f16_e32 v35, v209
	v_cvt_f32_f16_e32 v34, v208
	v_cvt_f32_f16_sdwa v43, v209 dst_sel:DWORD dst_unused:UNUSED_PAD src0_sel:WORD_1
	v_cvt_f32_f16_sdwa v42, v208 dst_sel:DWORD dst_unused:UNUSED_PAD src0_sel:WORD_1
	v_cvt_f32_f16_e32 v51, v210
	v_cvt_f32_f16_e32 v50, v211
	v_cvt_f32_f16_sdwa v55, v210 dst_sel:DWORD dst_unused:UNUSED_PAD src0_sel:WORD_1
	v_cvt_f32_f16_sdwa v54, v211 dst_sel:DWORD dst_unused:UNUSED_PAD src0_sel:WORD_1
	v_pk_add_f32 v[34:35], v[46:47], v[34:35]
	v_pk_add_f32 v[38:39], v[38:39], v[42:43]
	v_pk_add_f32 v[36:37], v[36:37], v[50:51]
	v_pk_add_f32 v[32:33], v[32:33], v[54:55]
	s_cbranch_vccz .LBB0_1660
	s_andn2_b64 vcc, exec, s[38:39]
	s_cbranch_vccz .LBB0_1661

;     __device__ __forceinline__ void operator()(f32x4 (&acc)[2][2][4][2], const Unit& u, const Order& S, int wr, int wc, int fr_, int fq_, LAS unsigned char*, int) const {
;     ...
;                 const int row = row0 + ai * HALF + m * 16; const size_t off = (size_t)row * DM + col0;
;                 float sq = 0.f;
; #pragma unroll
;                 for (int bj = 0; bj < 2; ++bj) {
;                     const h16x8 bs = *(const h16x8*)(h16 + off + bj * HALF);
;                     f32x4 o0 = acc[ai][bj][m][0] * pre, o1 = acc[ai][bj][m][1] * pre;
; #pragma unroll
;                     for (int e = 0; e < 4; ++e) { o0[e] += (float)bs[e]; o1[e] += (float)bs[4 + e]; }
;                     if (out32) { if (!dry) { __builtin_nontemporal_store(o0, (f32x4*)(out32 + off + bj * HALF)); __builtin_nontemporal_store(o1, (f32x4*)(out32 + off + bj * HALF + 4)); } }
.LBB0_1665:
	v_lshl_add_u64 v[38:39], v[146:147], 0, s[28:29]
	s_waitcnt lgkmcnt(0)
	v_lshl_add_u64 v[32:33], v[38:39], 1, s[90:91]
	v_mov_b32_e32 v40, v28
	v_mov_b32_e32 v41, v30
	v_mov_b32_e32 v30, v29
	v_mov_b32_e32 v28, v26
	v_mov_b32_e32 v29, v24
	v_mov_b32_e32 v24, v27
	s_mov_b64 s[38:39], -1
	s_and_b64 vcc, exec, s[2:3]
	s_waitcnt vmcnt(15)
	v_cvt_f32_f16_e32 v27, v213
	v_cvt_f32_f16_e32 v26, v212
	v_cvt_f32_f16_sdwa v35, v213 dst_sel:DWORD dst_unused:UNUSED_PAD src0_sel:WORD_1
	v_cvt_f32_f16_sdwa v34, v212 dst_sel:DWORD dst_unused:UNUSED_PAD src0_sel:WORD_1
	v_cvt_f32_f16_e32 v43, v214
	v_cvt_f32_f16_e32 v42, v215
	v_cvt_f32_f16_sdwa v45, v214 dst_sel:DWORD dst_unused:UNUSED_PAD src0_sel:WORD_1
	v_cvt_f32_f16_sdwa v44, v215 dst_sel:DWORD dst_unused:UNUSED_PAD src0_sel:WORD_1
	v_pk_add_f32 v[26:27], v[40:41], v[26:27]
	v_pk_add_f32 v[30:31], v[30:31], v[34:35]
	v_pk_add_f32 v[28:29], v[28:29], v[42:43]
	v_pk_add_f32 v[34:35], v[24:25], v[44:45]
	v_lshl_add_u64 v[24:25], v[38:39], 2, s[74:75]
	s_cbranch_vccnz .LBB0_1667
	v_mov_b32_e32 v36, v26
	v_mov_b32_e32 v37, v30
	v_mov_b32_e32 v38, v27
	v_mov_b32_e32 v39, v31
	global_store_dwordx4 v[24:25], v[36:39], off nt
	s_mov_b64 s[38:39], 0
	s_nop 0
	v_mov_b32_e32 v36, v29
	v_mov_b32_e32 v37, v35
	v_mov_b32_e32 v38, v28
	v_mov_b32_e32 v39, v34
	global_store_dwordx4 v[24:25], v[36:39], off offset:16 nt

;     __device__ __forceinline__ void operator()(f32x4 (&acc)[2][2][4][2], const Unit& u, const Order& S, int wr, int wc, int fr_, int fq_, LAS unsigned char*, int) const {
;     ...
;                 const int row = row0 + ai * HALF + m * 16; const size_t off = (size_t)row * DM + col0;
;                 float sq = 0.f;
; #pragma unroll
;                 for (int bj = 0; bj < 2; ++bj) {
;                     const h16x8 bs = *(const h16x8*)(h16 + off + bj * HALF);
;                     f32x4 o0 = acc[ai][bj][m][0] * pre, o1 = acc[ai][bj][m][1] * pre;
; #pragma unroll
;                     for (int e = 0; e < 4; ++e) { o0[e] += (float)bs[e]; o1[e] += (float)bs[4 + e]; }
;                     if (out32) { if (!dry) { __builtin_nontemporal_store(o0, (f32x4*)(out32 + off + bj * HALF)); __builtin_nontemporal_store(o1, (f32x4*)(out32 + off + bj * HALF + 4)); } }
.LBB0_1669:
	v_mov_b32_e32 v30, v20
	v_mov_b32_e32 v31, v22
	v_mov_b32_e32 v22, v21
	v_mov_b32_e32 v20, v18
	v_mov_b32_e32 v21, v16
	v_mov_b32_e32 v16, v19
	s_and_b64 vcc, exec, s[2:3]
	s_mov_b64 s[38:39], -1
	s_waitcnt vmcnt(15)
	v_cvt_f32_f16_e32 v19, v241
	v_cvt_f32_f16_e32 v18, v240
	v_cvt_f32_f16_sdwa v27, v241 dst_sel:DWORD dst_unused:UNUSED_PAD src0_sel:WORD_1
	v_cvt_f32_f16_sdwa v26, v240 dst_sel:DWORD dst_unused:UNUSED_PAD src0_sel:WORD_1
	v_cvt_f32_f16_e32 v35, v242
	v_cvt_f32_f16_e32 v34, v243
	v_cvt_f32_f16_sdwa v39, v242 dst_sel:DWORD dst_unused:UNUSED_PAD src0_sel:WORD_1
	v_cvt_f32_f16_sdwa v38, v243 dst_sel:DWORD dst_unused:UNUSED_PAD src0_sel:WORD_1
	v_pk_add_f32 v[18:19], v[30:31], v[18:19]
	v_pk_add_f32 v[22:23], v[22:23], v[26:27]
	v_pk_add_f32 v[20:21], v[20:21], v[34:35]
	v_pk_add_f32 v[16:17], v[16:17], v[38:39]
	s_cbranch_vccz .LBB0_1672
	s_andn2_b64 vcc, exec, s[38:39]
	s_cbranch_vccz .LBB0_1673

;     __device__ __forceinline__ void operator()(f32x4 (&acc)[2][2][4][2], const Unit& u, const Order& S, int wr, int wc, int fr_, int fq_, LAS unsigned char*, int) const {
;     ...
;                 const int row = row0 + ai * HALF + m * 16; const size_t off = (size_t)row * DM + col0;
;                 float sq = 0.f;
; #pragma unroll
;                 for (int bj = 0; bj < 2; ++bj) {
;                     const h16x8 bs = *(const h16x8*)(h16 + off + bj * HALF);
;                     f32x4 o0 = acc[ai][bj][m][0] * pre, o1 = acc[ai][bj][m][1] * pre;
; #pragma unroll
;                     for (int e = 0; e < 4; ++e) { o0[e] += (float)bs[e]; o1[e] += (float)bs[4 + e]; }
;                     if (out32) { if (!dry) { __builtin_nontemporal_store(o0, (f32x4*)(out32 + off + bj * HALF)); __builtin_nontemporal_store(o1, (f32x4*)(out32 + off + bj * HALF + 4)); } }
.LBB0_1677:
	v_lshl_add_u64 v[22:23], v[146:147], 0, s[30:31]
	s_waitcnt lgkmcnt(0)
	v_lshl_add_u64 v[16:17], v[22:23], 1, s[90:91]
	v_mov_b32_e32 v24, v12
	v_mov_b32_e32 v25, v14
	v_mov_b32_e32 v14, v13
	v_mov_b32_e32 v12, v10
	v_mov_b32_e32 v13, v8
	v_mov_b32_e32 v8, v11
	s_mov_b64 s[38:39], -1
	s_and_b64 vcc, exec, s[2:3]
	s_waitcnt vmcnt(15)
	v_cvt_f32_f16_e32 v11, v245
	v_cvt_f32_f16_e32 v10, v244
	v_cvt_f32_f16_sdwa v19, v245 dst_sel:DWORD dst_unused:UNUSED_PAD src0_sel:WORD_1
	v_cvt_f32_f16_sdwa v18, v244 dst_sel:DWORD dst_unused:UNUSED_PAD src0_sel:WORD_1
	v_cvt_f32_f16_e32 v27, v246
	v_cvt_f32_f16_e32 v26, v247
	v_cvt_f32_f16_sdwa v29, v246 dst_sel:DWORD dst_unused:UNUSED_PAD src0_sel:WORD_1
	v_cvt_f32_f16_sdwa v28, v247 dst_sel:DWORD dst_unused:UNUSED_PAD src0_sel:WORD_1
	v_pk_add_f32 v[10:11], v[24:25], v[10:11]
	v_pk_add_f32 v[14:15], v[14:15], v[18:19]
	v_pk_add_f32 v[12:13], v[12:13], v[26:27]
	v_pk_add_f32 v[18:19], v[8:9], v[28:29]
	v_lshl_add_u64 v[8:9], v[22:23], 2, s[74:75]
	s_cbranch_vccnz .LBB0_1679
	v_mov_b32_e32 v20, v10
	v_mov_b32_e32 v21, v14
	v_mov_b32_e32 v22, v11
	v_mov_b32_e32 v23, v15
	global_store_dwordx4 v[8:9], v[20:23], off nt
	s_mov_b64 s[38:39], 0
	s_nop 0
	v_mov_b32_e32 v20, v13
	v_mov_b32_e32 v21, v19
	v_mov_b32_e32 v22, v12
	v_mov_b32_e32 v23, v18
	global_store_dwordx4 v[8:9], v[20:23], off offset:16 nt

;     __device__ __forceinline__ void operator()(f32x4 (&acc)[2][2][4][2], const Unit& u, const Order& S, int wr, int wc, int fr_, int fq_, LAS unsigned char*, int) const {
;     ...
;                 const int row = row0 + ai * HALF + m * 16; const size_t off = (size_t)row * DM + col0;
;                 float sq = 0.f;
; #pragma unroll
;                 for (int bj = 0; bj < 2; ++bj) {
;                     const h16x8 bs = *(const h16x8*)(h16 + off + bj * HALF);
;                     f32x4 o0 = acc[ai][bj][m][0] * pre, o1 = acc[ai][bj][m][1] * pre;
; #pragma unroll
;                     for (int e = 0; e < 4; ++e) { o0[e] += (float)bs[e]; o1[e] += (float)bs[4 + e]; }
;                     if (out32) { if (!dry) { __builtin_nontemporal_store(o0, (f32x4*)(out32 + off + bj * HALF)); __builtin_nontemporal_store(o1, (f32x4*)(out32 + off + bj * HALF + 4)); } }
.LBB0_1681:
	v_mov_b32_e32 v14, v4
	v_mov_b32_e32 v15, v6
	v_mov_b32_e32 v6, v5
	v_mov_b32_e32 v4, v2
	v_mov_b32_e32 v5, v0
	v_mov_b32_e32 v0, v3
	s_and_b64 vcc, exec, s[2:3]
	s_mov_b64 s[2:3], -1
	s_waitcnt vmcnt(15)
	v_cvt_f32_f16_e32 v3, v249
	v_cvt_f32_f16_e32 v2, v248
	v_cvt_f32_f16_sdwa v11, v249 dst_sel:DWORD dst_unused:UNUSED_PAD src0_sel:WORD_1
	v_cvt_f32_f16_sdwa v10, v248 dst_sel:DWORD dst_unused:UNUSED_PAD src0_sel:WORD_1
	v_cvt_f32_f16_e32 v19, v250
	v_cvt_f32_f16_e32 v18, v251
	v_cvt_f32_f16_sdwa v23, v250 dst_sel:DWORD dst_unused:UNUSED_PAD src0_sel:WORD_1
	v_cvt_f32_f16_sdwa v22, v251 dst_sel:DWORD dst_unused:UNUSED_PAD src0_sel:WORD_1
	v_pk_add_f32 v[2:3], v[14:15], v[2:3]
	v_pk_add_f32 v[6:7], v[6:7], v[10:11]
	v_pk_add_f32 v[4:5], v[4:5], v[18:19]
	v_pk_add_f32 v[0:1], v[0:1], v[22:23]
	s_cbranch_vccz .LBB0_1685
	s_andn2_b64 vcc, exec, s[2:3]
	s_cbranch_vccz .LBB0_1686
